# speedup vs baseline: 1.0411x; 1.0222x over previous
.Lh2_loop:
	ds_read_b128 v[140:143], v138
	ds_read_b128 v[144:147], v138 offset:1024
	ds_read_b128 v[148:151], v138 offset:2048
	ds_read_b128 v[152:155], v138 offset:3072
	s_add_u32 s8, s6, s65
	s_addc_u32 s9, s7, s66
	ds_read_b128 v[156:159], v134
	ds_read_b128 v[160:163], v134 offset:1024
	ds_read_b128 v[164:167], v133
	ds_read_b128 v[168:171], v133 offset:1024
	ds_read_b128 v[172:175], v132
	ds_read_b128 v[176:179], v132 offset:1024
	ds_read_b128 v[180:183], v131
	ds_read_b128 v[184:187], v131 offset:1024
	s_mov_b32 m0, s76
	s_mov_b32 m0, s75
	s_nop 0
	s_waitcnt lgkmcnt(8)
	s_barrier
	s_waitcnt lgkmcnt(0)
	s_setprio 1
	s_waitcnt lgkmcnt(0)
	v_mfma_f32_16x16x32_bf16 v[124:127], v[140:143], v[156:159], v[124:127]
	v_mfma_f32_16x16x32_bf16 v[120:123], v[148:151], v[156:159], v[120:123]
	v_mfma_f32_16x16x32_bf16 v[116:119], v[140:143], v[164:167], v[116:119]
	v_mfma_f32_16x16x32_bf16 v[112:115], v[148:151], v[164:167], v[112:115]
	v_mfma_f32_16x16x32_bf16 v[108:111], v[140:143], v[172:175], v[108:111]
	v_mfma_f32_16x16x32_bf16 v[104:107], v[148:151], v[172:175], v[104:107]
	v_mfma_f32_16x16x32_bf16 v[100:103], v[140:143], v[180:183], v[100:103]
	v_mfma_f32_16x16x32_bf16 v[96:99], v[148:151], v[180:183], v[96:99]
	v_mfma_f32_16x16x32_bf16 v[124:127], v[144:147], v[160:163], v[124:127]
	v_mfma_f32_16x16x32_bf16 v[120:123], v[152:155], v[160:163], v[120:123]
	v_mfma_f32_16x16x32_bf16 v[116:119], v[144:147], v[168:171], v[116:119]
	v_mfma_f32_16x16x32_bf16 v[112:115], v[152:155], v[168:171], v[112:115]
	v_mfma_f32_16x16x32_bf16 v[108:111], v[144:147], v[176:179], v[108:111]
	v_mfma_f32_16x16x32_bf16 v[104:107], v[152:155], v[176:179], v[104:107]
	v_mfma_f32_16x16x32_bf16 v[100:103], v[144:147], v[184:187], v[100:103]
	v_mfma_f32_16x16x32_bf16 v[96:99], v[152:155], v[184:187], v[96:99]
	s_setprio 0
	s_barrier
	s_add_u32 s10, s6, s36
	s_addc_u32 s11, s7, s37
	ds_read_b128 v[188:191], v137
	ds_read_b128 v[192:195], v137 offset:1024
	ds_read_b128 v[202:205], v137 offset:2048
	ds_read_b128 v[206:209], v137 offset:3072
	s_mov_b32 m0, s63
	s_add_u32 s98, s10, s46
	s_addc_u32 s99, s11, s47
	global_load_lds_dwordx4 v129, s[98:99]
	s_mov_b32 m0, s64
	s_nop 0
	global_load_lds_dwordx4 v130, s[98:99]
	s_barrier
	s_waitcnt lgkmcnt(0)
	s_setprio 1
	s_waitcnt lgkmcnt(0)
	v_mfma_f32_16x16x32_bf16 v[92:95], v[188:191], v[156:159], v[92:95]
	v_mfma_f32_16x16x32_bf16 v[88:91], v[202:205], v[156:159], v[88:91]
	v_mfma_f32_16x16x32_bf16 v[84:87], v[188:191], v[164:167], v[84:87]
	v_mfma_f32_16x16x32_bf16 v[80:83], v[202:205], v[164:167], v[80:83]
	v_mfma_f32_16x16x32_bf16 v[76:79], v[188:191], v[172:175], v[76:79]
	v_mfma_f32_16x16x32_bf16 v[72:75], v[202:205], v[172:175], v[72:75]
	v_mfma_f32_16x16x32_bf16 v[68:71], v[188:191], v[180:183], v[68:71]
	v_mfma_f32_16x16x32_bf16 v[64:67], v[202:205], v[180:183], v[64:67]
	v_mfma_f32_16x16x32_bf16 v[92:95], v[192:195], v[160:163], v[92:95]
	v_mfma_f32_16x16x32_bf16 v[88:91], v[206:209], v[160:163], v[88:91]
	v_mfma_f32_16x16x32_bf16 v[84:87], v[192:195], v[168:171], v[84:87]
	v_mfma_f32_16x16x32_bf16 v[80:83], v[206:209], v[168:171], v[80:83]
	v_mfma_f32_16x16x32_bf16 v[76:79], v[192:195], v[176:179], v[76:79]
	v_mfma_f32_16x16x32_bf16 v[72:75], v[206:209], v[176:179], v[72:75]
	v_mfma_f32_16x16x32_bf16 v[68:71], v[192:195], v[184:187], v[68:71]
	v_mfma_f32_16x16x32_bf16 v[64:67], v[206:209], v[184:187], v[64:67]
	s_setprio 0
	s_barrier
	s_mov_b32 m0, s62
	s_add_u32 s98, s8, s48
	s_addc_u32 s99, s9, s49
	global_load_lds_dwordx4 v129, s[98:99]
	s_mov_b32 m0, s67
	s_nop 0
	global_load_lds_dwordx4 v130, s[98:99]
	s_waitcnt vmcnt(4)
	s_barrier
	s_mov_b32 m0, s68
	s_add_u32 s98, s10, s50
	s_addc_u32 s99, s11, s51
	global_load_lds_dwordx4 v129, s[98:99]
	s_mov_b32 m0, s69
	s_nop 0
	global_load_lds_dwordx4 v130, s[98:99]
	s_barrier
	ds_read_b128 v[140:143], v136
	ds_read_b128 v[144:147], v136 offset:1024
	ds_read_b128 v[148:151], v136 offset:2048
	ds_read_b128 v[152:155], v136 offset:3072
	ds_read_b128 v[156:159], v134 offset:32768
	ds_read_b128 v[160:163], v134 offset:33792
	ds_read_b128 v[164:167], v133 offset:32768
	ds_read_b128 v[168:171], v133 offset:33792
	ds_read_b128 v[172:175], v132 offset:32768
	ds_read_b128 v[176:179], v132 offset:33792
	ds_read_b128 v[180:183], v131 offset:32768
	ds_read_b128 v[184:187], v131 offset:33792
	s_mov_b32 m0, s70
	s_mov_b32 m0, s71
	s_nop 0
	s_waitcnt lgkmcnt(8)
	s_barrier
	s_waitcnt lgkmcnt(0)
	s_setprio 1
	s_waitcnt lgkmcnt(0)
	v_mfma_f32_16x16x32_bf16 v[124:127], v[140:143], v[156:159], v[124:127]
	v_mfma_f32_16x16x32_bf16 v[120:123], v[148:151], v[156:159], v[120:123]
	v_mfma_f32_16x16x32_bf16 v[116:119], v[140:143], v[164:167], v[116:119]
	v_mfma_f32_16x16x32_bf16 v[112:115], v[148:151], v[164:167], v[112:115]
	v_mfma_f32_16x16x32_bf16 v[108:111], v[140:143], v[172:175], v[108:111]
	v_mfma_f32_16x16x32_bf16 v[104:107], v[148:151], v[172:175], v[104:107]
	v_mfma_f32_16x16x32_bf16 v[100:103], v[140:143], v[180:183], v[100:103]
	v_mfma_f32_16x16x32_bf16 v[96:99], v[148:151], v[180:183], v[96:99]
	v_mfma_f32_16x16x32_bf16 v[124:127], v[144:147], v[160:163], v[124:127]
	v_mfma_f32_16x16x32_bf16 v[120:123], v[152:155], v[160:163], v[120:123]
	v_mfma_f32_16x16x32_bf16 v[116:119], v[144:147], v[168:171], v[116:119]
	v_mfma_f32_16x16x32_bf16 v[112:115], v[152:155], v[168:171], v[112:115]
	v_mfma_f32_16x16x32_bf16 v[108:111], v[144:147], v[176:179], v[108:111]
	v_mfma_f32_16x16x32_bf16 v[104:107], v[152:155], v[176:179], v[104:107]
	v_mfma_f32_16x16x32_bf16 v[100:103], v[144:147], v[184:187], v[100:103]
	v_mfma_f32_16x16x32_bf16 v[96:99], v[152:155], v[184:187], v[96:99]
	s_setprio 0
	s_barrier
	ds_read_b128 v[188:191], v135
	ds_read_b128 v[192:195], v135 offset:1024
	ds_read_b128 v[202:205], v135 offset:2048
	ds_read_b128 v[206:209], v135 offset:3072
	s_mov_b32 m0, s28
	s_add_u32 s98, s10, s92
	s_addc_u32 s99, s11, s93
	global_load_lds_dwordx4 v129, s[98:99]
	s_mov_b32 m0, s29
	s_nop 0
	global_load_lds_dwordx4 v130, s[98:99]
	s_barrier
	s_waitcnt lgkmcnt(0)
	s_setprio 1
	s_waitcnt lgkmcnt(0)
	v_mfma_f32_16x16x32_bf16 v[92:95], v[188:191], v[156:159], v[92:95]
	v_mfma_f32_16x16x32_bf16 v[88:91], v[202:205], v[156:159], v[88:91]
	v_mfma_f32_16x16x32_bf16 v[84:87], v[188:191], v[164:167], v[84:87]
	v_mfma_f32_16x16x32_bf16 v[80:83], v[202:205], v[164:167], v[80:83]
	v_mfma_f32_16x16x32_bf16 v[76:79], v[188:191], v[172:175], v[76:79]
	v_mfma_f32_16x16x32_bf16 v[72:75], v[202:205], v[172:175], v[72:75]
	v_mfma_f32_16x16x32_bf16 v[68:71], v[188:191], v[180:183], v[68:71]
	v_mfma_f32_16x16x32_bf16 v[64:67], v[202:205], v[180:183], v[64:67]
	v_mfma_f32_16x16x32_bf16 v[92:95], v[192:195], v[160:163], v[92:95]
	v_mfma_f32_16x16x32_bf16 v[88:91], v[206:209], v[160:163], v[88:91]
	v_mfma_f32_16x16x32_bf16 v[84:87], v[192:195], v[168:171], v[84:87]
	v_mfma_f32_16x16x32_bf16 v[80:83], v[206:209], v[168:171], v[80:83]
	v_mfma_f32_16x16x32_bf16 v[76:79], v[192:195], v[176:179], v[76:79]
	v_mfma_f32_16x16x32_bf16 v[72:75], v[206:209], v[176:179], v[72:75]
	v_mfma_f32_16x16x32_bf16 v[68:71], v[192:195], v[184:187], v[68:71]
	v_mfma_f32_16x16x32_bf16 v[64:67], v[206:209], v[184:187], v[64:67]
	s_setprio 0
	v_mov_b32_e32 v210, v130
	s_barrier
	v_mov_b32_e32 v211, v197
	s_mov_b32 m0, s72
	s_add_u32 s98, s8, s96
	s_addc_u32 s99, s9, s97
	global_load_lds_dwordx4 v129, s[98:99]
	s_mov_b32 m0, s73
	s_nop 0
	global_load_lds_dwordx4 v130, s[98:99]
	s_waitcnt vmcnt(4)
	s_barrier
	v_mov_b32_e32 v196, v129
	s_mov_b32 m0, s33
	s_add_u32 s98, s10, vcc_lo
	s_addc_u32 s99, s11, vcc_hi
	global_load_lds_dwordx4 v129, s[98:99]
	s_mov_b32 m0, s74
	s_nop 0
	global_load_lds_dwordx4 v130, s[98:99]
	s_barrier
	s_add_i32 s38, s38, 2
	s_add_u32 s6, s6, 0x100
	s_addc_u32 s7, s7, 0
	s_cmpk_lt_u32 s38, 0x54
	s_cbranch_scc1 .Lh2_loop
	s_add_u32 s4, s4, 0x2b80
	s_addc_u32 s5, s5, 0
	s_mov_b32 m0, s76
	ds_read_b128 v[140:143], v138
	ds_read_b128 v[144:147], v138 offset:1024
	ds_read_b128 v[148:151], v138 offset:2048
	ds_read_b128 v[152:155], v138 offset:3072
	ds_read_b128 v[156:159], v134
	ds_read_b128 v[160:163], v134 offset:1024
	ds_read_b128 v[164:167], v133
	ds_read_b128 v[168:171], v133 offset:1024
	ds_read_b128 v[172:175], v132
	ds_read_b128 v[176:179], v132 offset:1024
	ds_read_b128 v[180:183], v131
	ds_read_b128 v[184:187], v131 offset:1024
	s_nop 0
	s_mov_b32 m0, s75
	s_nop 0
	s_barrier
	s_waitcnt lgkmcnt(0)
	s_setprio 1
	s_waitcnt lgkmcnt(0)
	v_mfma_f32_16x16x32_bf16 v[124:127], v[140:143], v[156:159], v[124:127]
	v_mfma_f32_16x16x32_bf16 v[120:123], v[148:151], v[156:159], v[120:123]
	v_mfma_f32_16x16x32_bf16 v[116:119], v[140:143], v[164:167], v[116:119]
	v_mfma_f32_16x16x32_bf16 v[112:115], v[148:151], v[164:167], v[112:115]
	v_mfma_f32_16x16x32_bf16 v[108:111], v[140:143], v[172:175], v[108:111]
	v_mfma_f32_16x16x32_bf16 v[100:103], v[140:143], v[180:183], v[100:103]
	v_mfma_f32_16x16x32_bf16 v[96:99], v[148:151], v[180:183], v[96:99]
	v_mfma_f32_16x16x32_bf16 v[124:127], v[144:147], v[160:163], v[124:127]
	v_mfma_f32_16x16x32_bf16 v[120:123], v[152:155], v[160:163], v[120:123]
	v_mfma_f32_16x16x32_bf16 v[116:119], v[144:147], v[168:171], v[116:119]
	v_mfma_f32_16x16x32_bf16 v[112:115], v[152:155], v[168:171], v[112:115]
	v_mfma_f32_16x16x32_bf16 v[108:111], v[144:147], v[176:179], v[108:111]
	v_mfma_f32_16x16x32_bf16 v[104:107], v[148:151], v[172:175], v[104:107]
	v_mfma_f32_16x16x32_bf16 v[100:103], v[144:147], v[184:187], v[100:103]
	v_mfma_f32_16x16x32_bf16 v[96:99], v[152:155], v[184:187], v[96:99]
	v_mfma_f32_16x16x32_bf16 v[188:191], v[152:155], v[176:179], v[104:107]
	s_setprio 0
	s_barrier
	s_nop 2
	ds_read_b128 v[104:107], v137
	ds_read_b128 v[192:195], v137 offset:1024
	ds_read_b128 v[202:205], v137 offset:2048
	ds_read_b128 v[206:209], v137 offset:3072
	s_barrier
	s_waitcnt lgkmcnt(0)
	s_setprio 1
	s_waitcnt lgkmcnt(0)
	v_mfma_f32_16x16x32_bf16 v[92:95], v[104:107], v[156:159], v[92:95]
	v_mfma_f32_16x16x32_bf16 v[88:91], v[202:205], v[156:159], v[88:91]
	v_mfma_f32_16x16x32_bf16 v[80:83], v[202:205], v[164:167], v[80:83]
	v_mfma_f32_16x16x32_bf16 v[72:75], v[202:205], v[172:175], v[72:75]
	v_mfma_f32_16x16x32_bf16 v[64:67], v[202:205], v[180:183], v[64:67]
	v_mfma_f32_16x16x32_bf16 v[92:95], v[192:195], v[160:163], v[92:95]
	v_mfma_f32_16x16x32_bf16 v[88:91], v[206:209], v[160:163], v[88:91]
	v_mfma_f32_16x16x32_bf16 v[84:87], v[104:107], v[164:167], v[84:87]
	v_mfma_f32_16x16x32_bf16 v[80:83], v[206:209], v[168:171], v[80:83]
	v_mfma_f32_16x16x32_bf16 v[76:79], v[104:107], v[172:175], v[76:79]
	v_mfma_f32_16x16x32_bf16 v[72:75], v[206:209], v[176:179], v[72:75]
	v_mfma_f32_16x16x32_bf16 v[68:71], v[104:107], v[180:183], v[68:71]
	v_mfma_f32_16x16x32_bf16 v[64:67], v[206:209], v[184:187], v[64:67]
	v_mfma_f32_16x16x32_bf16 v[156:159], v[192:195], v[168:171], v[84:87]
	v_mfma_f32_16x16x32_bf16 v[160:163], v[192:195], v[176:179], v[76:79]
	v_mfma_f32_16x16x32_bf16 v[164:167], v[192:195], v[184:187], v[68:71]
	s_setprio 0
	s_barrier
	s_nop 1
	s_waitcnt vmcnt(2)
	s_barrier
	s_waitcnt lgkmcnt(0)
	s_setprio 1
	s_waitcnt lgkmcnt(0)
	s_setprio 0
	s_setprio 1
	s_setprio 0
	s_barrier
	ds_read_b128 v[16:19], v136
	ds_read_b128 v[180:183], v136 offset:1024
	ds_read_b128 v[184:187], v136 offset:2048
	ds_read_b128 v[192:195], v136 offset:3072
	ds_read_b128 v[0:3], v134 offset:32768
	ds_read_b128 v[4:7], v134 offset:33792
	ds_read_b128 v[8:11], v133 offset:32768
	ds_read_b128 v[12:15], v133 offset:33792
	ds_read_b128 v[44:47], v132 offset:32768
	ds_read_b128 v[202:205], v132 offset:33792
	ds_read_b128 v[206:209], v131 offset:32768
	ds_read_b128 v[222:225], v131 offset:33792
	s_waitcnt vmcnt(0)
	s_barrier
	s_waitcnt lgkmcnt(0)
	s_setprio 1
	s_waitcnt lgkmcnt(0)
	v_mfma_f32_16x16x32_bf16 v[28:31], v[16:19], v[0:3], v[124:127]
	v_mfma_f32_16x16x32_bf16 v[52:55], v[180:183], v[4:7], v[28:31]
	v_mfma_f32_16x16x32_bf16 v[28:31], v[184:187], v[0:3], v[120:123]
	v_mfma_f32_16x16x32_bf16 v[104:107], v[192:195], v[4:7], v[28:31]
	v_mfma_f32_16x16x32_bf16 v[28:31], v[16:19], v[8:11], v[116:119]
	v_mfma_f32_16x16x32_bf16 v[68:71], v[180:183], v[12:15], v[28:31]
	v_mfma_f32_16x16x32_bf16 v[28:31], v[184:187], v[8:11], v[112:115]
	v_mfma_f32_16x16x32_bf16 v[116:119], v[192:195], v[12:15], v[28:31]
	v_mfma_f32_16x16x32_bf16 v[28:31], v[16:19], v[44:47], v[108:111]
	v_mfma_f32_16x16x32_bf16 v[76:79], v[180:183], v[202:205], v[28:31]
	v_mfma_f32_16x16x32_bf16 v[28:31], v[184:187], v[44:47], v[188:191]
	v_mfma_f32_16x16x32_bf16 v[108:111], v[192:195], v[202:205], v[28:31]
	v_mfma_f32_16x16x32_bf16 v[28:31], v[16:19], v[206:209], v[100:103]
	v_mfma_f32_16x16x32_bf16 v[84:87], v[180:183], v[222:225], v[28:31]
	v_mfma_f32_16x16x32_bf16 v[28:31], v[184:187], v[206:209], v[96:99]
	v_mfma_f32_16x16x32_bf16 v[96:99], v[192:195], v[222:225], v[28:31]
	s_setprio 0
	s_barrier
	ds_read_b128 v[188:191], v135
	ds_read_b128 v[228:231], v135 offset:1024
	ds_read_b128 v[232:235], v135 offset:2048
	ds_read_b128 v[236:239], v135 offset:3072
	s_waitcnt vmcnt(0)
	s_barrier
	s_waitcnt lgkmcnt(0)
	s_setprio 1
	s_waitcnt lgkmcnt(0)
	v_mfma_f32_16x16x32_bf16 v[28:31], v[188:191], v[0:3], v[92:95]
	v_mfma_f32_16x16x32_bf16 v[0:3], v[232:235], v[0:3], v[88:91]
	v_mfma_f32_16x16x32_bf16 v[28:31], v[228:231], v[4:7], v[28:31]
	v_mfma_f32_16x16x32_bf16 v[0:3], v[236:239], v[4:7], v[0:3]
	v_mfma_f32_16x16x32_bf16 v[4:7], v[188:191], v[8:11], v[156:159]
	v_mfma_f32_16x16x32_bf16 v[36:39], v[228:231], v[12:15], v[4:7]
	v_mfma_f32_16x16x32_bf16 v[4:7], v[232:235], v[8:11], v[80:83]
	v_mfma_f32_16x16x32_bf16 v[4:7], v[236:239], v[12:15], v[4:7]
	v_mfma_f32_16x16x32_bf16 v[8:11], v[188:191], v[44:47], v[160:163]
	v_mfma_f32_16x16x32_bf16 v[12:15], v[188:191], v[206:209], v[164:167]
	v_mfma_f32_16x16x32_bf16 v[40:43], v[228:231], v[202:205], v[8:11]
	v_mfma_f32_16x16x32_bf16 v[8:11], v[232:235], v[44:47], v[72:75]
	v_mfma_f32_16x16x32_bf16 v[44:47], v[228:231], v[222:225], v[12:15]
	v_mfma_f32_16x16x32_bf16 v[12:15], v[232:235], v[206:209], v[64:67]
	v_mfma_f32_16x16x32_bf16 v[8:11], v[236:239], v[202:205], v[8:11]
	v_mfma_f32_16x16x32_bf16 v[12:15], v[236:239], v[222:225], v[12:15]
	s_setprio 0
	s_barrier
	s_barrier
	s_waitcnt lgkmcnt(0)
	s_setprio 1
	s_waitcnt lgkmcnt(0)
	s_setprio 0
	s_setprio 1
	s_setprio 0
	s_movk_i32 s4, 0x100
	v_cmp_gt_u32_e32 vcc, s4, v128
	s_barrier
	s_and_saveexec_b64 s[4:5], vcc
	s_cbranch_execz .Lh2_epi
	s_barrier

.LBB0_138:
	ds_read_b128 v[140:143], v138
	ds_read_b128 v[144:147], v138 offset:1024
	ds_read_b128 v[148:151], v138 offset:2048
	ds_read_b128 v[152:155], v138 offset:3072
	s_add_u32 s8, s6, s65
	s_addc_u32 s9, s7, s66
	ds_read_b128 v[156:159], v134
	ds_read_b128 v[160:163], v134 offset:1024
	ds_read_b128 v[164:167], v133
	ds_read_b128 v[168:171], v133 offset:1024
	ds_read_b128 v[172:175], v132
	ds_read_b128 v[176:179], v132 offset:1024
	ds_read_b128 v[180:183], v131
	ds_read_b128 v[184:187], v131 offset:1024
	s_mov_b32 m0, s76
	s_add_u32 s98, s8, s44
	s_addc_u32 s99, s9, s45
	global_load_lds_dwordx4 v129, s[98:99]
	s_mov_b32 m0, s75
	s_nop 0
	global_load_lds_dwordx4 v130, s[98:99]
	s_waitcnt lgkmcnt(8)
	s_barrier
	s_waitcnt lgkmcnt(0)
	s_setprio 1
	s_waitcnt lgkmcnt(0)
	v_mfma_f32_16x16x32_bf16 v[124:127], v[140:143], v[156:159], v[124:127]
	v_mfma_f32_16x16x32_bf16 v[120:123], v[148:151], v[156:159], v[120:123]
	v_mfma_f32_16x16x32_bf16 v[116:119], v[140:143], v[164:167], v[116:119]
	v_mfma_f32_16x16x32_bf16 v[112:115], v[148:151], v[164:167], v[112:115]
	v_mfma_f32_16x16x32_bf16 v[108:111], v[140:143], v[172:175], v[108:111]
	v_mfma_f32_16x16x32_bf16 v[104:107], v[148:151], v[172:175], v[104:107]
	v_mfma_f32_16x16x32_bf16 v[100:103], v[140:143], v[180:183], v[100:103]
	v_mfma_f32_16x16x32_bf16 v[96:99], v[148:151], v[180:183], v[96:99]
	v_mfma_f32_16x16x32_bf16 v[124:127], v[144:147], v[160:163], v[124:127]
	v_mfma_f32_16x16x32_bf16 v[120:123], v[152:155], v[160:163], v[120:123]
	v_mfma_f32_16x16x32_bf16 v[116:119], v[144:147], v[168:171], v[116:119]
	v_mfma_f32_16x16x32_bf16 v[112:115], v[152:155], v[168:171], v[112:115]
	v_mfma_f32_16x16x32_bf16 v[108:111], v[144:147], v[176:179], v[108:111]
	v_mfma_f32_16x16x32_bf16 v[104:107], v[152:155], v[176:179], v[104:107]
	v_mfma_f32_16x16x32_bf16 v[100:103], v[144:147], v[184:187], v[100:103]
	v_mfma_f32_16x16x32_bf16 v[96:99], v[152:155], v[184:187], v[96:99]
	s_setprio 0
	s_barrier
	s_add_u32 s10, s6, s36
	s_addc_u32 s11, s7, s37
	ds_read_b128 v[188:191], v137
	ds_read_b128 v[192:195], v137 offset:1024
	ds_read_b128 v[202:205], v137 offset:2048
	ds_read_b128 v[206:209], v137 offset:3072
	s_mov_b32 m0, s63
	s_add_u32 s98, s10, s46
	s_addc_u32 s99, s11, s47
	global_load_lds_dwordx4 v129, s[98:99]
	s_mov_b32 m0, s64
	s_nop 0
	global_load_lds_dwordx4 v130, s[98:99]
	s_barrier
	s_waitcnt lgkmcnt(0)
	s_setprio 1
	s_waitcnt lgkmcnt(0)
	v_mfma_f32_16x16x32_bf16 v[92:95], v[188:191], v[156:159], v[92:95]
	v_mfma_f32_16x16x32_bf16 v[88:91], v[202:205], v[156:159], v[88:91]
	v_mfma_f32_16x16x32_bf16 v[84:87], v[188:191], v[164:167], v[84:87]
	v_mfma_f32_16x16x32_bf16 v[80:83], v[202:205], v[164:167], v[80:83]
	v_mfma_f32_16x16x32_bf16 v[76:79], v[188:191], v[172:175], v[76:79]
	v_mfma_f32_16x16x32_bf16 v[72:75], v[202:205], v[172:175], v[72:75]
	v_mfma_f32_16x16x32_bf16 v[68:71], v[188:191], v[180:183], v[68:71]
	v_mfma_f32_16x16x32_bf16 v[64:67], v[202:205], v[180:183], v[64:67]
	v_mfma_f32_16x16x32_bf16 v[92:95], v[192:195], v[160:163], v[92:95]
	v_mfma_f32_16x16x32_bf16 v[88:91], v[206:209], v[160:163], v[88:91]
	v_mfma_f32_16x16x32_bf16 v[84:87], v[192:195], v[168:171], v[84:87]
	v_mfma_f32_16x16x32_bf16 v[80:83], v[206:209], v[168:171], v[80:83]
	v_mfma_f32_16x16x32_bf16 v[76:79], v[192:195], v[176:179], v[76:79]
	v_mfma_f32_16x16x32_bf16 v[72:75], v[206:209], v[176:179], v[72:75]
	v_mfma_f32_16x16x32_bf16 v[68:71], v[192:195], v[184:187], v[68:71]
	v_mfma_f32_16x16x32_bf16 v[64:67], v[206:209], v[184:187], v[64:67]
	s_setprio 0
	s_barrier
	ds_read_b128 v[156:159], v134 offset:16384
	ds_read_b128 v[160:163], v134 offset:17408
	ds_read_b128 v[164:167], v133 offset:16384
	ds_read_b128 v[168:171], v133 offset:17408
	ds_read_b128 v[172:175], v132 offset:16384
	ds_read_b128 v[176:179], v132 offset:17408
	ds_read_b128 v[180:183], v131 offset:16384
	ds_read_b128 v[184:187], v131 offset:17408
	s_mov_b32 m0, s62
	s_add_u32 s98, s8, s48
	s_addc_u32 s99, s9, s49
	global_load_lds_dwordx4 v129, s[98:99]
	s_mov_b32 m0, s67
	s_nop 0
	global_load_lds_dwordx4 v130, s[98:99]
	s_barrier
	s_waitcnt lgkmcnt(0)
	s_setprio 1
	s_waitcnt lgkmcnt(0)
	v_mfma_f32_16x16x32_bf16 v[60:63], v[140:143], v[156:159], v[60:63]
	v_mfma_f32_16x16x32_bf16 v[56:59], v[148:151], v[156:159], v[56:59]
	v_mfma_f32_16x16x32_bf16 v[52:55], v[140:143], v[164:167], v[52:55]
	v_mfma_f32_16x16x32_bf16 v[48:51], v[148:151], v[164:167], v[48:51]
	v_mfma_f32_16x16x32_bf16 v[44:47], v[140:143], v[172:175], v[44:47]
	v_mfma_f32_16x16x32_bf16 v[40:43], v[148:151], v[172:175], v[40:43]
	v_mfma_f32_16x16x32_bf16 v[36:39], v[140:143], v[180:183], v[36:39]
	v_mfma_f32_16x16x32_bf16 v[32:35], v[148:151], v[180:183], v[32:35]
	v_mfma_f32_16x16x32_bf16 v[60:63], v[144:147], v[160:163], v[60:63]
	v_mfma_f32_16x16x32_bf16 v[56:59], v[152:155], v[160:163], v[56:59]
	v_mfma_f32_16x16x32_bf16 v[52:55], v[144:147], v[168:171], v[52:55]
	v_mfma_f32_16x16x32_bf16 v[48:51], v[152:155], v[168:171], v[48:51]
	v_mfma_f32_16x16x32_bf16 v[44:47], v[144:147], v[176:179], v[44:47]
	v_mfma_f32_16x16x32_bf16 v[40:43], v[152:155], v[176:179], v[40:43]
	v_mfma_f32_16x16x32_bf16 v[36:39], v[144:147], v[184:187], v[36:39]
	v_mfma_f32_16x16x32_bf16 v[32:35], v[152:155], v[184:187], v[32:35]
	s_setprio 0
	s_barrier
	s_mov_b32 m0, s68
	s_add_u32 s98, s10, s50
	s_addc_u32 s99, s11, s51
	global_load_lds_dwordx4 v129, s[98:99]
	s_mov_b32 m0, s69
	s_nop 0
	global_load_lds_dwordx4 v130, s[98:99]
	s_waitcnt vmcnt(6)
	s_barrier
	s_setprio 1
	v_mfma_f32_16x16x32_bf16 v[28:31], v[188:191], v[156:159], v[28:31]
	v_mfma_f32_16x16x32_bf16 v[24:27], v[202:205], v[156:159], v[24:27]
	v_mfma_f32_16x16x32_bf16 v[20:23], v[188:191], v[164:167], v[20:23]
	v_mfma_f32_16x16x32_bf16 v[16:19], v[202:205], v[164:167], v[16:19]
	v_mfma_f32_16x16x32_bf16 v[12:15], v[188:191], v[172:175], v[12:15]
	v_mfma_f32_16x16x32_bf16 v[8:11], v[202:205], v[172:175], v[8:11]
	v_mfma_f32_16x16x32_bf16 v[4:7], v[188:191], v[180:183], v[4:7]
	v_mfma_f32_16x16x32_bf16 v[0:3], v[202:205], v[180:183], v[0:3]
	v_mfma_f32_16x16x32_bf16 v[28:31], v[192:195], v[160:163], v[28:31]
	v_mfma_f32_16x16x32_bf16 v[24:27], v[206:209], v[160:163], v[24:27]
	v_mfma_f32_16x16x32_bf16 v[20:23], v[192:195], v[168:171], v[20:23]
	v_mfma_f32_16x16x32_bf16 v[16:19], v[206:209], v[168:171], v[16:19]
	v_mfma_f32_16x16x32_bf16 v[12:15], v[192:195], v[176:179], v[12:15]
	v_mfma_f32_16x16x32_bf16 v[8:11], v[206:209], v[176:179], v[8:11]
	v_mfma_f32_16x16x32_bf16 v[4:7], v[192:195], v[184:187], v[4:7]
	v_mfma_f32_16x16x32_bf16 v[0:3], v[206:209], v[184:187], v[0:3]
	s_setprio 0
	s_barrier
	ds_read_b128 v[140:143], v136
	ds_read_b128 v[144:147], v136 offset:1024
	ds_read_b128 v[148:151], v136 offset:2048
	ds_read_b128 v[152:155], v136 offset:3072
	ds_read_b128 v[156:159], v134 offset:32768
	ds_read_b128 v[160:163], v134 offset:33792
	ds_read_b128 v[164:167], v133 offset:32768
	ds_read_b128 v[168:171], v133 offset:33792
	ds_read_b128 v[172:175], v132 offset:32768
	ds_read_b128 v[176:179], v132 offset:33792
	ds_read_b128 v[180:183], v131 offset:32768
	ds_read_b128 v[184:187], v131 offset:33792
	s_mov_b32 m0, s70
	s_add_u32 s98, s8, s90
	s_addc_u32 s99, s9, s91
	global_load_lds_dwordx4 v129, s[98:99]
	s_mov_b32 m0, s71
	s_nop 0
	global_load_lds_dwordx4 v130, s[98:99]
	s_waitcnt lgkmcnt(8)
	s_barrier
	s_waitcnt lgkmcnt(0)
	s_setprio 1
	s_waitcnt lgkmcnt(0)
	v_mfma_f32_16x16x32_bf16 v[124:127], v[140:143], v[156:159], v[124:127]
	v_mfma_f32_16x16x32_bf16 v[120:123], v[148:151], v[156:159], v[120:123]
	v_mfma_f32_16x16x32_bf16 v[116:119], v[140:143], v[164:167], v[116:119]
	v_mfma_f32_16x16x32_bf16 v[112:115], v[148:151], v[164:167], v[112:115]
	v_mfma_f32_16x16x32_bf16 v[108:111], v[140:143], v[172:175], v[108:111]
	v_mfma_f32_16x16x32_bf16 v[104:107], v[148:151], v[172:175], v[104:107]
	v_mfma_f32_16x16x32_bf16 v[100:103], v[140:143], v[180:183], v[100:103]
	v_mfma_f32_16x16x32_bf16 v[96:99], v[148:151], v[180:183], v[96:99]
	v_mfma_f32_16x16x32_bf16 v[124:127], v[144:147], v[160:163], v[124:127]
	v_mfma_f32_16x16x32_bf16 v[120:123], v[152:155], v[160:163], v[120:123]
	v_mfma_f32_16x16x32_bf16 v[116:119], v[144:147], v[168:171], v[116:119]
	v_mfma_f32_16x16x32_bf16 v[112:115], v[152:155], v[168:171], v[112:115]
	v_mfma_f32_16x16x32_bf16 v[108:111], v[144:147], v[176:179], v[108:111]
	v_mfma_f32_16x16x32_bf16 v[104:107], v[152:155], v[176:179], v[104:107]
	v_mfma_f32_16x16x32_bf16 v[100:103], v[144:147], v[184:187], v[100:103]
	v_mfma_f32_16x16x32_bf16 v[96:99], v[152:155], v[184:187], v[96:99]
	s_setprio 0
	s_barrier
	ds_read_b128 v[188:191], v135
	ds_read_b128 v[192:195], v135 offset:1024
	ds_read_b128 v[202:205], v135 offset:2048
	ds_read_b128 v[206:209], v135 offset:3072
	s_mov_b32 m0, s28
	s_add_u32 s98, s10, s92
	s_addc_u32 s99, s11, s93
	global_load_lds_dwordx4 v129, s[98:99]
	s_mov_b32 m0, s29
	s_nop 0
	global_load_lds_dwordx4 v130, s[98:99]
	s_barrier
	s_waitcnt lgkmcnt(0)
	s_setprio 1
	s_waitcnt lgkmcnt(0)
	v_mfma_f32_16x16x32_bf16 v[92:95], v[188:191], v[156:159], v[92:95]
	v_mfma_f32_16x16x32_bf16 v[88:91], v[202:205], v[156:159], v[88:91]
	v_mfma_f32_16x16x32_bf16 v[84:87], v[188:191], v[164:167], v[84:87]
	v_mfma_f32_16x16x32_bf16 v[80:83], v[202:205], v[164:167], v[80:83]
	v_mfma_f32_16x16x32_bf16 v[76:79], v[188:191], v[172:175], v[76:79]
	v_mfma_f32_16x16x32_bf16 v[72:75], v[202:205], v[172:175], v[72:75]
	v_mfma_f32_16x16x32_bf16 v[68:71], v[188:191], v[180:183], v[68:71]
	v_mfma_f32_16x16x32_bf16 v[64:67], v[202:205], v[180:183], v[64:67]
	v_mfma_f32_16x16x32_bf16 v[92:95], v[192:195], v[160:163], v[92:95]
	v_mfma_f32_16x16x32_bf16 v[88:91], v[206:209], v[160:163], v[88:91]
	v_mfma_f32_16x16x32_bf16 v[84:87], v[192:195], v[168:171], v[84:87]
	v_mfma_f32_16x16x32_bf16 v[80:83], v[206:209], v[168:171], v[80:83]
	v_mfma_f32_16x16x32_bf16 v[76:79], v[192:195], v[176:179], v[76:79]
	v_mfma_f32_16x16x32_bf16 v[72:75], v[206:209], v[176:179], v[72:75]
	v_mfma_f32_16x16x32_bf16 v[68:71], v[192:195], v[184:187], v[68:71]
	v_mfma_f32_16x16x32_bf16 v[64:67], v[206:209], v[184:187], v[64:67]
	s_setprio 0
	v_mov_b32_e32 v210, v130
	s_barrier
	ds_read_b128 v[156:159], v134 offset:49152
	ds_read_b128 v[160:163], v134 offset:50176
	ds_read_b128 v[164:167], v133 offset:49152
	ds_read_b128 v[168:171], v133 offset:50176
	ds_read_b128 v[172:175], v132 offset:49152
	ds_read_b128 v[176:179], v132 offset:50176
	ds_read_b128 v[180:183], v131 offset:49152
	ds_read_b128 v[184:187], v131 offset:50176
	v_mov_b32_e32 v211, v197
	s_mov_b32 m0, s72
	s_add_u32 s98, s8, s96
	s_addc_u32 s99, s9, s97
	global_load_lds_dwordx4 v129, s[98:99]
	s_mov_b32 m0, s73
	s_nop 0
	global_load_lds_dwordx4 v130, s[98:99]
	s_barrier
	s_waitcnt lgkmcnt(0)
	s_setprio 1
	s_waitcnt lgkmcnt(0)
	v_mfma_f32_16x16x32_bf16 v[60:63], v[140:143], v[156:159], v[60:63]
	v_mfma_f32_16x16x32_bf16 v[56:59], v[148:151], v[156:159], v[56:59]
	v_mfma_f32_16x16x32_bf16 v[52:55], v[140:143], v[164:167], v[52:55]
	v_mfma_f32_16x16x32_bf16 v[48:51], v[148:151], v[164:167], v[48:51]
	v_mfma_f32_16x16x32_bf16 v[44:47], v[140:143], v[172:175], v[44:47]
	v_mfma_f32_16x16x32_bf16 v[40:43], v[148:151], v[172:175], v[40:43]
	v_mfma_f32_16x16x32_bf16 v[36:39], v[140:143], v[180:183], v[36:39]
	v_mfma_f32_16x16x32_bf16 v[32:35], v[148:151], v[180:183], v[32:35]
	v_mfma_f32_16x16x32_bf16 v[60:63], v[144:147], v[160:163], v[60:63]
	v_mfma_f32_16x16x32_bf16 v[56:59], v[152:155], v[160:163], v[56:59]
	v_mfma_f32_16x16x32_bf16 v[52:55], v[144:147], v[168:171], v[52:55]
	v_mfma_f32_16x16x32_bf16 v[48:51], v[152:155], v[168:171], v[48:51]
	v_mfma_f32_16x16x32_bf16 v[44:47], v[144:147], v[176:179], v[44:47]
	v_mfma_f32_16x16x32_bf16 v[40:43], v[152:155], v[176:179], v[40:43]
	v_mfma_f32_16x16x32_bf16 v[36:39], v[144:147], v[184:187], v[36:39]
	v_mfma_f32_16x16x32_bf16 v[32:35], v[152:155], v[184:187], v[32:35]
	s_setprio 0
	s_barrier
	v_mov_b32_e32 v196, v129
	s_mov_b32 m0, s33
	s_add_u32 s98, s10, vcc_lo
	s_addc_u32 s99, s11, vcc_hi
	global_load_lds_dwordx4 v129, s[98:99]
	s_mov_b32 m0, s74
	s_nop 0
	global_load_lds_dwordx4 v130, s[98:99]
	s_waitcnt vmcnt(6)
	s_barrier
	s_setprio 1
	v_mfma_f32_16x16x32_bf16 v[28:31], v[188:191], v[156:159], v[28:31]
	v_mfma_f32_16x16x32_bf16 v[24:27], v[202:205], v[156:159], v[24:27]
	v_mfma_f32_16x16x32_bf16 v[20:23], v[188:191], v[164:167], v[20:23]
	v_mfma_f32_16x16x32_bf16 v[16:19], v[202:205], v[164:167], v[16:19]
	v_mfma_f32_16x16x32_bf16 v[12:15], v[188:191], v[172:175], v[12:15]
	v_mfma_f32_16x16x32_bf16 v[8:11], v[202:205], v[172:175], v[8:11]
	v_mfma_f32_16x16x32_bf16 v[4:7], v[188:191], v[180:183], v[4:7]
	v_mfma_f32_16x16x32_bf16 v[0:3], v[202:205], v[180:183], v[0:3]
	v_mfma_f32_16x16x32_bf16 v[28:31], v[192:195], v[160:163], v[28:31]
	v_mfma_f32_16x16x32_bf16 v[24:27], v[206:209], v[160:163], v[24:27]
	v_mfma_f32_16x16x32_bf16 v[20:23], v[192:195], v[168:171], v[20:23]
	v_mfma_f32_16x16x32_bf16 v[16:19], v[206:209], v[168:171], v[16:19]
	v_mfma_f32_16x16x32_bf16 v[12:15], v[192:195], v[176:179], v[12:15]
	v_mfma_f32_16x16x32_bf16 v[8:11], v[206:209], v[176:179], v[8:11]
	v_mfma_f32_16x16x32_bf16 v[4:7], v[192:195], v[184:187], v[4:7]
	v_mfma_f32_16x16x32_bf16 v[0:3], v[206:209], v[184:187], v[0:3]
	s_setprio 0
	s_add_i32 s38, s38, 2
	s_add_u32 s6, s6, 0x100
	s_addc_u32 s7, s7, 0
	s_cmpk_lt_u32 s38, 0x54
	s_barrier
	s_cbranch_scc1 .LBB0_138
	s_add_u32 s4, s4, 0x2b80
	s_addc_u32 s5, s5, 0
	s_mov_b32 m0, s76
	ds_read_b128 v[140:143], v138
	ds_read_b128 v[144:147], v138 offset:1024
	ds_read_b128 v[148:151], v138 offset:2048
	ds_read_b128 v[152:155], v138 offset:3072
	ds_read_b128 v[156:159], v134
	ds_read_b128 v[160:163], v134 offset:1024
	ds_read_b128 v[164:167], v133
	ds_read_b128 v[168:171], v133 offset:1024
	ds_read_b128 v[172:175], v132
	ds_read_b128 v[176:179], v132 offset:1024
	ds_read_b128 v[180:183], v131
	ds_read_b128 v[184:187], v131 offset:1024
	s_nop 0
	global_load_lds_dwordx4 v129, s[4:5]
	s_mov_b32 m0, s75
	s_nop 0
	global_load_lds_dwordx4 v130, s[4:5]
	s_barrier
	s_waitcnt lgkmcnt(0)
	s_setprio 1
	s_waitcnt lgkmcnt(0)
	v_mfma_f32_16x16x32_bf16 v[124:127], v[140:143], v[156:159], v[124:127]
	v_mfma_f32_16x16x32_bf16 v[120:123], v[148:151], v[156:159], v[120:123]
	v_mfma_f32_16x16x32_bf16 v[116:119], v[140:143], v[164:167], v[116:119]
	v_mfma_f32_16x16x32_bf16 v[112:115], v[148:151], v[164:167], v[112:115]
	v_mfma_f32_16x16x32_bf16 v[108:111], v[140:143], v[172:175], v[108:111]
	v_mfma_f32_16x16x32_bf16 v[100:103], v[140:143], v[180:183], v[100:103]
	v_mfma_f32_16x16x32_bf16 v[96:99], v[148:151], v[180:183], v[96:99]
	v_mfma_f32_16x16x32_bf16 v[124:127], v[144:147], v[160:163], v[124:127]
	v_mfma_f32_16x16x32_bf16 v[120:123], v[152:155], v[160:163], v[120:123]
	v_mfma_f32_16x16x32_bf16 v[116:119], v[144:147], v[168:171], v[116:119]
	v_mfma_f32_16x16x32_bf16 v[112:115], v[152:155], v[168:171], v[112:115]
	v_mfma_f32_16x16x32_bf16 v[108:111], v[144:147], v[176:179], v[108:111]
	v_mfma_f32_16x16x32_bf16 v[104:107], v[148:151], v[172:175], v[104:107]
	v_mfma_f32_16x16x32_bf16 v[100:103], v[144:147], v[184:187], v[100:103]
	v_mfma_f32_16x16x32_bf16 v[96:99], v[152:155], v[184:187], v[96:99]
	v_mfma_f32_16x16x32_bf16 v[188:191], v[152:155], v[176:179], v[104:107]
	s_setprio 0
	s_barrier
	s_nop 2
	ds_read_b128 v[104:107], v137
	ds_read_b128 v[192:195], v137 offset:1024
	ds_read_b128 v[202:205], v137 offset:2048
	ds_read_b128 v[206:209], v137 offset:3072
	s_barrier
	s_waitcnt lgkmcnt(0)
	s_setprio 1
	s_waitcnt lgkmcnt(0)
	v_mfma_f32_16x16x32_bf16 v[92:95], v[104:107], v[156:159], v[92:95]
	v_mfma_f32_16x16x32_bf16 v[88:91], v[202:205], v[156:159], v[88:91]
	v_mfma_f32_16x16x32_bf16 v[80:83], v[202:205], v[164:167], v[80:83]
	v_mfma_f32_16x16x32_bf16 v[72:75], v[202:205], v[172:175], v[72:75]
	v_mfma_f32_16x16x32_bf16 v[64:67], v[202:205], v[180:183], v[64:67]
	v_mfma_f32_16x16x32_bf16 v[92:95], v[192:195], v[160:163], v[92:95]
	v_mfma_f32_16x16x32_bf16 v[88:91], v[206:209], v[160:163], v[88:91]
	v_mfma_f32_16x16x32_bf16 v[84:87], v[104:107], v[164:167], v[84:87]
	v_mfma_f32_16x16x32_bf16 v[80:83], v[206:209], v[168:171], v[80:83]
	v_mfma_f32_16x16x32_bf16 v[76:79], v[104:107], v[172:175], v[76:79]
	v_mfma_f32_16x16x32_bf16 v[72:75], v[206:209], v[176:179], v[72:75]
	v_mfma_f32_16x16x32_bf16 v[68:71], v[104:107], v[180:183], v[68:71]
	v_mfma_f32_16x16x32_bf16 v[64:67], v[206:209], v[184:187], v[64:67]
	v_mfma_f32_16x16x32_bf16 v[156:159], v[192:195], v[168:171], v[84:87]
	v_mfma_f32_16x16x32_bf16 v[160:163], v[192:195], v[176:179], v[76:79]
	v_mfma_f32_16x16x32_bf16 v[164:167], v[192:195], v[184:187], v[68:71]
	s_setprio 0
	s_barrier
	s_nop 1
	ds_read_b128 v[68:71], v134 offset:16384
	ds_read_b128 v[76:79], v134 offset:17408
	ds_read_b128 v[84:87], v133 offset:16384
	ds_read_b128 v[168:171], v133 offset:17408
	ds_read_b128 v[172:175], v132 offset:16384
	ds_read_b128 v[176:179], v132 offset:17408
	ds_read_b128 v[180:183], v131 offset:16384
	ds_read_b128 v[184:187], v131 offset:17408
	s_waitcnt vmcnt(4)
	s_barrier
	s_waitcnt lgkmcnt(0)
	s_setprio 1
	s_waitcnt lgkmcnt(0)
	v_mfma_f32_16x16x32_bf16 v[60:63], v[140:143], v[68:71], v[60:63]
	v_mfma_f32_16x16x32_bf16 v[56:59], v[148:151], v[68:71], v[56:59]
	v_mfma_f32_16x16x32_bf16 v[48:51], v[148:151], v[84:87], v[48:51]
	v_mfma_f32_16x16x32_bf16 v[32:35], v[148:151], v[180:183], v[32:35]
	v_mfma_f32_16x16x32_bf16 v[60:63], v[144:147], v[76:79], v[60:63]
	v_mfma_f32_16x16x32_bf16 v[56:59], v[152:155], v[76:79], v[56:59]
	v_mfma_f32_16x16x32_bf16 v[52:55], v[140:143], v[84:87], v[52:55]
	v_mfma_f32_16x16x32_bf16 v[48:51], v[152:155], v[168:171], v[48:51]
	v_mfma_f32_16x16x32_bf16 v[44:47], v[140:143], v[172:175], v[44:47]
	v_mfma_f32_16x16x32_bf16 v[40:43], v[148:151], v[172:175], v[40:43]
	v_mfma_f32_16x16x32_bf16 v[36:39], v[140:143], v[180:183], v[36:39]
	v_mfma_f32_16x16x32_bf16 v[32:35], v[152:155], v[184:187], v[32:35]
	v_mfma_f32_16x16x32_bf16 v[210:213], v[144:147], v[168:171], v[52:55]
	v_mfma_f32_16x16x32_bf16 v[214:217], v[144:147], v[176:179], v[44:47]
	v_mfma_f32_16x16x32_bf16 v[218:221], v[152:155], v[176:179], v[40:43]
	v_mfma_f32_16x16x32_bf16 v[138:141], v[144:147], v[184:187], v[36:39]
	s_setprio 0
	s_setprio 1
	v_mfma_f32_16x16x32_bf16 v[24:27], v[202:205], v[68:71], v[24:27]
	v_mfma_f32_16x16x32_bf16 v[20:23], v[104:107], v[84:87], v[20:23]
	v_mfma_f32_16x16x32_bf16 v[28:31], v[104:107], v[68:71], v[28:31]
	v_mfma_f32_16x16x32_bf16 v[24:27], v[206:209], v[76:79], v[24:27]
	v_mfma_f32_16x16x32_bf16 v[20:23], v[192:195], v[168:171], v[20:23]
	v_mfma_f32_16x16x32_bf16 v[16:19], v[202:205], v[84:87], v[16:19]
	v_mfma_f32_16x16x32_bf16 v[12:15], v[104:107], v[172:175], v[12:15]
	v_mfma_f32_16x16x32_bf16 v[8:11], v[202:205], v[172:175], v[8:11]
	v_mfma_f32_16x16x32_bf16 v[4:7], v[104:107], v[180:183], v[4:7]
	v_mfma_f32_16x16x32_bf16 v[0:3], v[202:205], v[180:183], v[0:3]
	v_mfma_f32_16x16x32_bf16 v[142:145], v[192:195], v[76:79], v[28:31]
	v_mfma_f32_16x16x32_bf16 v[146:149], v[206:209], v[168:171], v[16:19]
	v_mfma_f32_16x16x32_bf16 v[150:153], v[192:195], v[176:179], v[12:15]
	v_mfma_f32_16x16x32_bf16 v[168:171], v[206:209], v[176:179], v[8:11]
	v_mfma_f32_16x16x32_bf16 v[172:175], v[192:195], v[184:187], v[4:7]
	v_mfma_f32_16x16x32_bf16 v[176:179], v[206:209], v[184:187], v[0:3]
	s_setprio 0
	s_barrier
	ds_read_b128 v[16:19], v136
	ds_read_b128 v[180:183], v136 offset:1024
	ds_read_b128 v[184:187], v136 offset:2048
	ds_read_b128 v[192:195], v136 offset:3072
	ds_read_b128 v[0:3], v134 offset:32768
	ds_read_b128 v[4:7], v134 offset:33792
	ds_read_b128 v[8:11], v133 offset:32768
	ds_read_b128 v[12:15], v133 offset:33792
	ds_read_b128 v[44:47], v132 offset:32768
	ds_read_b128 v[202:205], v132 offset:33792
	ds_read_b128 v[206:209], v131 offset:32768
	ds_read_b128 v[222:225], v131 offset:33792
	s_waitcnt vmcnt(2)
	s_barrier
	s_waitcnt lgkmcnt(0)
	s_setprio 1
	s_waitcnt lgkmcnt(0)
	v_mfma_f32_16x16x32_bf16 v[28:31], v[16:19], v[0:3], v[124:127]
	v_mfma_f32_16x16x32_bf16 v[52:55], v[180:183], v[4:7], v[28:31]
	v_mfma_f32_16x16x32_bf16 v[28:31], v[184:187], v[0:3], v[120:123]
	v_mfma_f32_16x16x32_bf16 v[104:107], v[192:195], v[4:7], v[28:31]
	v_mfma_f32_16x16x32_bf16 v[28:31], v[16:19], v[8:11], v[116:119]
	v_mfma_f32_16x16x32_bf16 v[68:71], v[180:183], v[12:15], v[28:31]
	v_mfma_f32_16x16x32_bf16 v[28:31], v[184:187], v[8:11], v[112:115]
	v_mfma_f32_16x16x32_bf16 v[116:119], v[192:195], v[12:15], v[28:31]
	v_mfma_f32_16x16x32_bf16 v[28:31], v[16:19], v[44:47], v[108:111]
	v_mfma_f32_16x16x32_bf16 v[76:79], v[180:183], v[202:205], v[28:31]
	v_mfma_f32_16x16x32_bf16 v[28:31], v[184:187], v[44:47], v[188:191]
	v_mfma_f32_16x16x32_bf16 v[108:111], v[192:195], v[202:205], v[28:31]
	v_mfma_f32_16x16x32_bf16 v[28:31], v[16:19], v[206:209], v[100:103]
	v_mfma_f32_16x16x32_bf16 v[84:87], v[180:183], v[222:225], v[28:31]
	v_mfma_f32_16x16x32_bf16 v[28:31], v[184:187], v[206:209], v[96:99]
	v_mfma_f32_16x16x32_bf16 v[96:99], v[192:195], v[222:225], v[28:31]
	s_setprio 0
	s_barrier
	ds_read_b128 v[188:191], v135
	ds_read_b128 v[228:231], v135 offset:1024
	ds_read_b128 v[232:235], v135 offset:2048
	ds_read_b128 v[236:239], v135 offset:3072
	s_waitcnt vmcnt(0)
	s_barrier
	s_waitcnt lgkmcnt(0)
	s_setprio 1
	s_waitcnt lgkmcnt(0)
	v_mfma_f32_16x16x32_bf16 v[28:31], v[188:191], v[0:3], v[92:95]
	v_mfma_f32_16x16x32_bf16 v[0:3], v[232:235], v[0:3], v[88:91]
	v_mfma_f32_16x16x32_bf16 v[28:31], v[228:231], v[4:7], v[28:31]
	v_mfma_f32_16x16x32_bf16 v[0:3], v[236:239], v[4:7], v[0:3]
	v_mfma_f32_16x16x32_bf16 v[4:7], v[188:191], v[8:11], v[156:159]
	v_mfma_f32_16x16x32_bf16 v[36:39], v[228:231], v[12:15], v[4:7]
	v_mfma_f32_16x16x32_bf16 v[4:7], v[232:235], v[8:11], v[80:83]
	v_mfma_f32_16x16x32_bf16 v[4:7], v[236:239], v[12:15], v[4:7]
	v_mfma_f32_16x16x32_bf16 v[8:11], v[188:191], v[44:47], v[160:163]
	v_mfma_f32_16x16x32_bf16 v[12:15], v[188:191], v[206:209], v[164:167]
	v_mfma_f32_16x16x32_bf16 v[40:43], v[228:231], v[202:205], v[8:11]
	v_mfma_f32_16x16x32_bf16 v[8:11], v[232:235], v[44:47], v[72:75]
	v_mfma_f32_16x16x32_bf16 v[44:47], v[228:231], v[222:225], v[12:15]
	v_mfma_f32_16x16x32_bf16 v[12:15], v[232:235], v[206:209], v[64:67]
	v_mfma_f32_16x16x32_bf16 v[8:11], v[236:239], v[202:205], v[8:11]
	v_mfma_f32_16x16x32_bf16 v[12:15], v[236:239], v[222:225], v[12:15]
	s_setprio 0
	s_barrier
	ds_read_b128 v[64:67], v134 offset:49152
	ds_read_b128 v[134:137], v134 offset:50176
	ds_read_b128 v[154:157], v133 offset:49152
	ds_read_b128 v[158:161], v133 offset:50176
	ds_read_b128 v[162:165], v132 offset:49152
	ds_read_b128 v[202:205], v132 offset:50176
	ds_read_b128 v[206:209], v131 offset:49152
	ds_read_b128 v[130:133], v131 offset:50176
	s_barrier
	s_waitcnt lgkmcnt(0)
	s_setprio 1
	s_waitcnt lgkmcnt(0)
	v_mfma_f32_16x16x32_bf16 v[56:59], v[184:187], v[64:67], v[56:59]
	v_mfma_f32_16x16x32_bf16 v[48:51], v[184:187], v[154:157], v[48:51]
	v_mfma_f32_16x16x32_bf16 v[60:63], v[16:19], v[64:67], v[60:63]
	v_mfma_f32_16x16x32_bf16 v[92:95], v[192:195], v[134:137], v[56:59]
	v_mfma_f32_16x16x32_bf16 v[56:59], v[16:19], v[154:157], v[210:213]
	v_mfma_f32_16x16x32_bf16 v[88:91], v[192:195], v[158:161], v[48:51]
	v_mfma_f32_16x16x32_bf16 v[48:51], v[16:19], v[162:165], v[214:217]
	v_mfma_f32_16x16x32_bf16 v[16:19], v[16:19], v[206:209], v[138:141]
	v_mfma_f32_16x16x32_bf16 v[120:123], v[180:183], v[202:205], v[48:51]
	v_mfma_f32_16x16x32_bf16 v[48:51], v[184:187], v[162:165], v[218:221]
	v_mfma_f32_16x16x32_bf16 v[124:127], v[180:183], v[130:133], v[16:19]
	v_mfma_f32_16x16x32_bf16 v[16:19], v[184:187], v[206:209], v[32:35]
	v_mfma_f32_16x16x32_bf16 v[100:103], v[180:183], v[134:137], v[60:63]
	v_mfma_f32_16x16x32_bf16 v[112:115], v[180:183], v[158:161], v[56:59]
	v_mfma_f32_16x16x32_bf16 v[80:83], v[192:195], v[202:205], v[48:51]
	v_mfma_f32_16x16x32_bf16 v[72:75], v[192:195], v[130:133], v[16:19]
	s_setprio 0
	s_setprio 1
	v_mfma_f32_16x16x32_bf16 v[16:19], v[188:191], v[64:67], v[142:145]
	v_mfma_f32_16x16x32_bf16 v[48:51], v[228:231], v[134:137], v[16:19]
	v_mfma_f32_16x16x32_bf16 v[16:19], v[232:235], v[64:67], v[24:27]
	v_mfma_f32_16x16x32_bf16 v[20:23], v[188:191], v[154:157], v[20:23]
	v_mfma_f32_16x16x32_bf16 v[24:27], v[188:191], v[162:165], v[150:153]
	v_mfma_f32_16x16x32_bf16 v[32:35], v[188:191], v[206:209], v[172:175]
	v_mfma_f32_16x16x32_bf16 v[56:59], v[228:231], v[158:161], v[20:23]
	v_mfma_f32_16x16x32_bf16 v[20:23], v[232:235], v[154:157], v[146:149]
	v_mfma_f32_16x16x32_bf16 v[60:63], v[228:231], v[202:205], v[24:27]
	v_mfma_f32_16x16x32_bf16 v[24:27], v[232:235], v[162:165], v[168:171]
	v_mfma_f32_16x16x32_bf16 v[64:67], v[228:231], v[130:133], v[32:35]
	v_mfma_f32_16x16x32_bf16 v[32:35], v[232:235], v[206:209], v[176:179]
	v_mfma_f32_16x16x32_bf16 v[16:19], v[236:239], v[134:137], v[16:19]
	v_mfma_f32_16x16x32_bf16 v[20:23], v[236:239], v[158:161], v[20:23]
	v_mfma_f32_16x16x32_bf16 v[24:27], v[236:239], v[202:205], v[24:27]
	v_mfma_f32_16x16x32_bf16 v[32:35], v[236:239], v[130:133], v[32:35]
	s_setprio 0
	s_movk_i32 s4, 0x100
	v_cmp_gt_u32_e32 vcc, s4, v128
	s_barrier
	s_and_saveexec_b64 s[4:5], vcc
	s_cbranch_execz .LBB0_95
	s_barrier
	s_branch .LBB0_95

.Lhf_192:
	ds_read_b128 v[140:143], v129
	ds_read_b128 v[144:147], v129 offset:1024
	ds_read_b128 v[148:151], v129 offset:2048
	ds_read_b128 v[152:155], v129 offset:3072
	s_add_u32 s28, s56, s4
	s_addc_u32 s29, s57, s5
	ds_read_b128 v[156:159], v136
	ds_read_b128 v[160:163], v136 offset:1024
	ds_read_b128 v[164:167], v135
	ds_read_b128 v[168:171], v135 offset:1024
	ds_read_b128 v[172:175], v134
	ds_read_b128 v[176:179], v134 offset:1024
	ds_read_b128 v[180:183], v133
	ds_read_b128 v[184:187], v133 offset:1024
	s_add_i32 s40, s52, 0xc000
	s_mov_b32 m0, s40
	s_add_i32 s39, s52, 0xe000
	s_mov_b32 m0, s39
	s_nop 0
	s_waitcnt lgkmcnt(8)
	s_barrier
	s_waitcnt lgkmcnt(0)
	s_setprio 1
	s_waitcnt lgkmcnt(0)
	v_mfma_f32_16x16x32_bf16 v[124:127], v[140:143], v[156:159], v[124:127]
	v_mfma_f32_16x16x32_bf16 v[120:123], v[148:151], v[156:159], v[120:123]
	v_mfma_f32_16x16x32_bf16 v[116:119], v[140:143], v[164:167], v[116:119]
	v_mfma_f32_16x16x32_bf16 v[112:115], v[148:151], v[164:167], v[112:115]
	v_mfma_f32_16x16x32_bf16 v[108:111], v[140:143], v[172:175], v[108:111]
	v_mfma_f32_16x16x32_bf16 v[104:107], v[148:151], v[172:175], v[104:107]
	v_mfma_f32_16x16x32_bf16 v[100:103], v[140:143], v[180:183], v[100:103]
	v_mfma_f32_16x16x32_bf16 v[96:99], v[148:151], v[180:183], v[96:99]
	v_mfma_f32_16x16x32_bf16 v[124:127], v[144:147], v[160:163], v[124:127]
	v_mfma_f32_16x16x32_bf16 v[120:123], v[152:155], v[160:163], v[120:123]
	v_mfma_f32_16x16x32_bf16 v[116:119], v[144:147], v[168:171], v[116:119]
	v_mfma_f32_16x16x32_bf16 v[112:115], v[152:155], v[168:171], v[112:115]
	v_mfma_f32_16x16x32_bf16 v[108:111], v[144:147], v[176:179], v[108:111]
	v_mfma_f32_16x16x32_bf16 v[104:107], v[152:155], v[176:179], v[104:107]
	v_mfma_f32_16x16x32_bf16 v[100:103], v[144:147], v[184:187], v[100:103]
	v_mfma_f32_16x16x32_bf16 v[96:99], v[152:155], v[184:187], v[96:99]
	s_setprio 0
	s_barrier
	s_add_u32 s58, s56, s36
	s_addc_u32 s59, s57, s37
	ds_read_b128 v[188:191], v139
	ds_read_b128 v[192:195], v139 offset:1024
	ds_read_b128 v[202:205], v139 offset:2048
	ds_read_b128 v[206:209], v139 offset:3072
	s_add_i32 m0, s52, 0x10000
	s_add_u32 s98, s58, s46
	s_addc_u32 s99, s59, s47
	global_load_lds_dwordx4 v128, s[98:99]
	s_add_i32 m0, s52, 0x12000
	s_nop 0
	global_load_lds_dwordx4 v130, s[98:99]
	s_barrier
	s_waitcnt lgkmcnt(0)
	s_setprio 1
	s_waitcnt lgkmcnt(0)
	v_mfma_f32_16x16x32_bf16 v[92:95], v[188:191], v[156:159], v[92:95]
	v_mfma_f32_16x16x32_bf16 v[88:91], v[202:205], v[156:159], v[88:91]
	v_mfma_f32_16x16x32_bf16 v[84:87], v[188:191], v[164:167], v[84:87]
	v_mfma_f32_16x16x32_bf16 v[80:83], v[202:205], v[164:167], v[80:83]
	v_mfma_f32_16x16x32_bf16 v[76:79], v[188:191], v[172:175], v[76:79]
	v_mfma_f32_16x16x32_bf16 v[72:75], v[202:205], v[172:175], v[72:75]
	v_mfma_f32_16x16x32_bf16 v[68:71], v[188:191], v[180:183], v[68:71]
	v_mfma_f32_16x16x32_bf16 v[64:67], v[202:205], v[180:183], v[64:67]
	v_mfma_f32_16x16x32_bf16 v[92:95], v[192:195], v[160:163], v[92:95]
	v_mfma_f32_16x16x32_bf16 v[88:91], v[206:209], v[160:163], v[88:91]
	v_mfma_f32_16x16x32_bf16 v[84:87], v[192:195], v[168:171], v[84:87]
	v_mfma_f32_16x16x32_bf16 v[80:83], v[206:209], v[168:171], v[80:83]
	v_mfma_f32_16x16x32_bf16 v[76:79], v[192:195], v[176:179], v[76:79]
	v_mfma_f32_16x16x32_bf16 v[72:75], v[206:209], v[176:179], v[72:75]
	v_mfma_f32_16x16x32_bf16 v[68:71], v[192:195], v[184:187], v[68:71]
	v_mfma_f32_16x16x32_bf16 v[64:67], v[206:209], v[184:187], v[64:67]
	s_setprio 0
	s_barrier
	s_mov_b32 m0, s52
	s_add_u32 s98, s28, s48
	s_addc_u32 s99, s29, s49
	global_load_lds_dwordx4 v128, s[98:99]
	s_add_i32 m0, s52, 0x2000
	s_nop 0
	global_load_lds_dwordx4 v130, s[98:99]
	s_waitcnt vmcnt(4)
	s_barrier
	s_add_i32 m0, s52, 0x14000
	s_add_u32 s98, s58, s50
	s_addc_u32 s99, s59, s51
	global_load_lds_dwordx4 v128, s[98:99]
	s_add_i32 m0, s52, 0x16000
	s_nop 0
	global_load_lds_dwordx4 v130, s[98:99]
	s_barrier
	ds_read_b128 v[140:143], v138
	ds_read_b128 v[144:147], v138 offset:1024
	ds_read_b128 v[148:151], v138 offset:2048
	ds_read_b128 v[152:155], v138 offset:3072
	ds_read_b128 v[156:159], v136 offset:32768
	ds_read_b128 v[160:163], v136 offset:33792
	ds_read_b128 v[164:167], v135 offset:32768
	ds_read_b128 v[168:171], v135 offset:33792
	ds_read_b128 v[172:175], v134 offset:32768
	ds_read_b128 v[176:179], v134 offset:33792
	ds_read_b128 v[180:183], v133 offset:32768
	ds_read_b128 v[184:187], v133 offset:33792
	s_add_i32 m0, s52, 0x4000
	s_add_i32 m0, s52, 0x6000
	s_nop 0
	s_waitcnt lgkmcnt(8)
	s_barrier
	s_waitcnt lgkmcnt(0)
	s_setprio 1
	s_waitcnt lgkmcnt(0)
	v_mfma_f32_16x16x32_bf16 v[124:127], v[140:143], v[156:159], v[124:127]
	v_mfma_f32_16x16x32_bf16 v[120:123], v[148:151], v[156:159], v[120:123]
	v_mfma_f32_16x16x32_bf16 v[116:119], v[140:143], v[164:167], v[116:119]
	v_mfma_f32_16x16x32_bf16 v[112:115], v[148:151], v[164:167], v[112:115]
	v_mfma_f32_16x16x32_bf16 v[108:111], v[140:143], v[172:175], v[108:111]
	v_mfma_f32_16x16x32_bf16 v[104:107], v[148:151], v[172:175], v[104:107]
	v_mfma_f32_16x16x32_bf16 v[100:103], v[140:143], v[180:183], v[100:103]
	v_mfma_f32_16x16x32_bf16 v[96:99], v[148:151], v[180:183], v[96:99]
	v_mfma_f32_16x16x32_bf16 v[124:127], v[144:147], v[160:163], v[124:127]
	v_mfma_f32_16x16x32_bf16 v[120:123], v[152:155], v[160:163], v[120:123]
	v_mfma_f32_16x16x32_bf16 v[116:119], v[144:147], v[168:171], v[116:119]
	v_mfma_f32_16x16x32_bf16 v[112:115], v[152:155], v[168:171], v[112:115]
	v_mfma_f32_16x16x32_bf16 v[108:111], v[144:147], v[176:179], v[108:111]
	v_mfma_f32_16x16x32_bf16 v[104:107], v[152:155], v[176:179], v[104:107]
	v_mfma_f32_16x16x32_bf16 v[100:103], v[144:147], v[184:187], v[100:103]
	v_mfma_f32_16x16x32_bf16 v[96:99], v[152:155], v[184:187], v[96:99]
	s_setprio 0
	s_barrier
	ds_read_b128 v[188:191], v137
	ds_read_b128 v[192:195], v137 offset:1024
	ds_read_b128 v[202:205], v137 offset:2048
	ds_read_b128 v[206:209], v137 offset:3072
	s_mov_b32 m0, s7
	s_add_u32 s98, s58, s68
	s_addc_u32 s99, s59, s69
	global_load_lds_dwordx4 v128, s[98:99]
	s_mov_b32 m0, s53
	s_nop 0
	global_load_lds_dwordx4 v130, s[98:99]
	s_barrier
	s_waitcnt lgkmcnt(0)
	s_setprio 1
	s_waitcnt lgkmcnt(0)
	v_mfma_f32_16x16x32_bf16 v[92:95], v[188:191], v[156:159], v[92:95]
	v_mfma_f32_16x16x32_bf16 v[88:91], v[202:205], v[156:159], v[88:91]
	v_mfma_f32_16x16x32_bf16 v[84:87], v[188:191], v[164:167], v[84:87]
	v_mfma_f32_16x16x32_bf16 v[80:83], v[202:205], v[164:167], v[80:83]
	v_mfma_f32_16x16x32_bf16 v[76:79], v[188:191], v[172:175], v[76:79]
	v_mfma_f32_16x16x32_bf16 v[72:75], v[202:205], v[172:175], v[72:75]
	v_mfma_f32_16x16x32_bf16 v[68:71], v[188:191], v[180:183], v[68:71]
	v_mfma_f32_16x16x32_bf16 v[64:67], v[202:205], v[180:183], v[64:67]
	v_mfma_f32_16x16x32_bf16 v[92:95], v[192:195], v[160:163], v[92:95]
	v_mfma_f32_16x16x32_bf16 v[88:91], v[206:209], v[160:163], v[88:91]
	v_mfma_f32_16x16x32_bf16 v[84:87], v[192:195], v[168:171], v[84:87]
	v_mfma_f32_16x16x32_bf16 v[80:83], v[206:209], v[168:171], v[80:83]
	v_mfma_f32_16x16x32_bf16 v[76:79], v[192:195], v[176:179], v[76:79]
	v_mfma_f32_16x16x32_bf16 v[72:75], v[206:209], v[176:179], v[72:75]
	v_mfma_f32_16x16x32_bf16 v[68:71], v[192:195], v[184:187], v[68:71]
	v_mfma_f32_16x16x32_bf16 v[64:67], v[206:209], v[184:187], v[64:67]
	s_setprio 0
	v_mov_b32_e32 v210, v130
	s_barrier
	v_mov_b32_e32 v211, v197
	s_mov_b32 m0, s9
	s_add_u32 s98, s28, s70
	s_addc_u32 s99, s29, s71
	global_load_lds_dwordx4 v128, s[98:99]
	s_mov_b32 m0, s33
	s_nop 0
	global_load_lds_dwordx4 v130, s[98:99]
	s_waitcnt vmcnt(4)
	s_barrier
	v_mov_b32_e32 v196, v128
	s_mov_b32 m0, s65
	s_add_u32 s98, s58, s72
	s_addc_u32 s99, s59, s73
	global_load_lds_dwordx4 v128, s[98:99]
	s_mov_b32 m0, s66
	s_nop 0
	global_load_lds_dwordx4 v130, s[98:99]
	s_barrier
	s_add_i32 s38, s38, 2
	s_add_u32 s56, s56, 0x100
	s_addc_u32 s57, s57, 0
	s_cmp_lt_u32 s38, 28
	s_cbranch_scc1 .Lhf_192
	s_lshl_b64 s[4:5], s[10:11], 12
	v_readlane_b32 s10, v254, 12
	v_readlane_b32 s11, v254, 13
	s_add_u32 s4, s10, s4
	s_addc_u32 s5, s11, s5
	ds_read_b128 v[140:143], v129
	ds_read_b128 v[144:147], v129 offset:1024
	ds_read_b128 v[148:151], v129 offset:2048
	ds_read_b128 v[152:155], v129 offset:3072
	ds_read_b128 v[156:159], v136
	ds_read_b128 v[160:163], v136 offset:1024
	ds_read_b128 v[164:167], v135
	ds_read_b128 v[168:171], v135 offset:1024
	ds_read_b128 v[172:175], v134
	ds_read_b128 v[176:179], v134 offset:1024
	ds_read_b128 v[180:183], v133
	ds_read_b128 v[184:187], v133 offset:1024
	v_mov_b32_e32 v129, v197
	v_lshl_add_u64 v[128:129], s[4:5], 0, v[128:129]
	s_mov_b64 s[10:11], 0xf80
	s_mov_b32 m0, s40
	v_lshl_add_u64 v[128:129], v[128:129], 0, s[10:11]
	v_mov_b32_e32 v131, v197
	v_lshl_add_u64 v[128:129], s[4:5], 0, v[130:131]
	v_lshl_add_u64 v[128:129], v[128:129], 0, s[10:11]
	s_mov_b32 m0, s39
	s_nop 0
	s_barrier
	s_waitcnt lgkmcnt(0)
	s_setprio 1
	s_waitcnt lgkmcnt(0)
	v_mfma_f32_16x16x32_bf16 v[124:127], v[140:143], v[156:159], v[124:127]
	v_mfma_f32_16x16x32_bf16 v[116:119], v[140:143], v[164:167], v[116:119]
	v_mfma_f32_16x16x32_bf16 v[112:115], v[148:151], v[164:167], v[112:115]
	v_mfma_f32_16x16x32_bf16 v[108:111], v[140:143], v[172:175], v[108:111]
	v_mfma_f32_16x16x32_bf16 v[104:107], v[148:151], v[172:175], v[104:107]
	v_mfma_f32_16x16x32_bf16 v[100:103], v[140:143], v[180:183], v[100:103]
	v_mfma_f32_16x16x32_bf16 v[96:99], v[148:151], v[180:183], v[96:99]
	v_mfma_f32_16x16x32_bf16 v[124:127], v[144:147], v[160:163], v[124:127]
	v_mfma_f32_16x16x32_bf16 v[120:123], v[148:151], v[156:159], v[120:123]
	v_mfma_f32_16x16x32_bf16 v[116:119], v[144:147], v[168:171], v[116:119]
	v_mfma_f32_16x16x32_bf16 v[112:115], v[152:155], v[168:171], v[112:115]
	v_mfma_f32_16x16x32_bf16 v[108:111], v[144:147], v[176:179], v[108:111]
	v_mfma_f32_16x16x32_bf16 v[104:107], v[152:155], v[176:179], v[104:107]
	v_mfma_f32_16x16x32_bf16 v[100:103], v[144:147], v[184:187], v[100:103]
	v_mfma_f32_16x16x32_bf16 v[96:99], v[152:155], v[184:187], v[96:99]
	v_mfma_f32_16x16x32_bf16 v[128:131], v[152:155], v[160:163], v[120:123]
	s_setprio 0
	s_barrier
	s_nop 0
	ds_read_b128 v[120:123], v139
	ds_read_b128 v[188:191], v139 offset:1024
	ds_read_b128 v[192:195], v139 offset:2048
	ds_read_b128 v[202:205], v139 offset:3072
	s_barrier
	s_waitcnt lgkmcnt(0)
	s_setprio 1
	s_waitcnt lgkmcnt(0)
	v_mfma_f32_16x16x32_bf16 v[76:79], v[120:123], v[172:175], v[76:79]
	v_mfma_f32_16x16x32_bf16 v[68:71], v[120:123], v[180:183], v[68:71]
	v_mfma_f32_16x16x32_bf16 v[64:67], v[192:195], v[180:183], v[64:67]
	v_mfma_f32_16x16x32_bf16 v[92:95], v[120:123], v[156:159], v[92:95]
	v_mfma_f32_16x16x32_bf16 v[88:91], v[192:195], v[156:159], v[88:91]
	v_mfma_f32_16x16x32_bf16 v[84:87], v[120:123], v[164:167], v[84:87]
	v_mfma_f32_16x16x32_bf16 v[80:83], v[192:195], v[164:167], v[80:83]
	v_mfma_f32_16x16x32_bf16 v[76:79], v[188:191], v[176:179], v[76:79]
	v_mfma_f32_16x16x32_bf16 v[72:75], v[192:195], v[172:175], v[72:75]
	v_mfma_f32_16x16x32_bf16 v[68:71], v[188:191], v[184:187], v[68:71]
	v_mfma_f32_16x16x32_bf16 v[64:67], v[202:205], v[184:187], v[64:67]
	v_mfma_f32_16x16x32_bf16 v[206:209], v[188:191], v[160:163], v[92:95]
	v_mfma_f32_16x16x32_bf16 v[156:159], v[202:205], v[160:163], v[88:91]
	v_mfma_f32_16x16x32_bf16 v[160:163], v[188:191], v[168:171], v[84:87]
	v_mfma_f32_16x16x32_bf16 v[164:167], v[202:205], v[168:171], v[80:83]
	v_mfma_f32_16x16x32_bf16 v[168:171], v[202:205], v[176:179], v[72:75]
	s_setprio 0
	s_barrier
	s_nop 0
	s_waitcnt vmcnt(2)
	s_barrier
	s_waitcnt lgkmcnt(0)
	s_setprio 1
	s_waitcnt lgkmcnt(0)
	s_setprio 0
	s_setprio 1
	s_setprio 0
	s_barrier
	s_nop 0
	ds_read_b128 v[8:11], v138
	ds_read_b128 v[16:19], v138 offset:1024
	ds_read_b128 v[176:179], v138 offset:2048
	ds_read_b128 v[180:183], v138 offset:3072
	ds_read_b128 v[20:23], v136 offset:32768
	ds_read_b128 v[24:27], v136 offset:33792
	ds_read_b128 v[28:31], v135 offset:32768
	ds_read_b128 v[56:59], v135 offset:33792
	ds_read_b128 v[188:191], v134 offset:32768
	ds_read_b128 v[192:195], v134 offset:33792
	ds_read_b128 v[202:205], v133 offset:32768
	ds_read_b128 v[210:213], v133 offset:33792
	s_waitcnt vmcnt(0)
	s_barrier
	s_waitcnt lgkmcnt(0)
	s_setprio 1
	s_waitcnt lgkmcnt(0)
	v_mfma_f32_16x16x32_bf16 v[72:75], v[8:11], v[20:23], v[124:127]
	v_mfma_f32_16x16x32_bf16 v[120:123], v[16:19], v[24:27], v[72:75]
	v_mfma_f32_16x16x32_bf16 v[72:75], v[176:179], v[20:23], v[128:131]
	v_mfma_f32_16x16x32_bf16 v[124:127], v[180:183], v[24:27], v[72:75]
	v_mfma_f32_16x16x32_bf16 v[72:75], v[8:11], v[28:31], v[116:119]
	v_mfma_f32_16x16x32_bf16 v[116:119], v[16:19], v[56:59], v[72:75]
	v_mfma_f32_16x16x32_bf16 v[72:75], v[176:179], v[28:31], v[112:115]
	v_mfma_f32_16x16x32_bf16 v[112:115], v[180:183], v[56:59], v[72:75]
	v_mfma_f32_16x16x32_bf16 v[72:75], v[8:11], v[188:191], v[108:111]
	v_mfma_f32_16x16x32_bf16 v[88:91], v[16:19], v[192:195], v[72:75]
	v_mfma_f32_16x16x32_bf16 v[72:75], v[176:179], v[188:191], v[104:107]
	v_mfma_f32_16x16x32_bf16 v[92:95], v[180:183], v[192:195], v[72:75]
	v_mfma_f32_16x16x32_bf16 v[72:75], v[8:11], v[202:205], v[100:103]
	v_mfma_f32_16x16x32_bf16 v[84:87], v[16:19], v[210:213], v[72:75]
	v_mfma_f32_16x16x32_bf16 v[72:75], v[176:179], v[202:205], v[96:99]
	v_mfma_f32_16x16x32_bf16 v[80:83], v[180:183], v[210:213], v[72:75]
	s_setprio 0
	s_barrier
	ds_read_b128 v[128:131], v137
	ds_read_b128 v[214:217], v137 offset:1024
	ds_read_b128 v[218:221], v137 offset:2048
	ds_read_b128 v[222:225], v137 offset:3072
	s_waitcnt vmcnt(0)
	s_barrier
	s_waitcnt lgkmcnt(0)
	s_setprio 1
	s_waitcnt lgkmcnt(0)
	v_mfma_f32_16x16x32_bf16 v[72:75], v[128:131], v[20:23], v[206:209]
	v_mfma_f32_16x16x32_bf16 v[20:23], v[218:221], v[20:23], v[156:159]
	v_mfma_f32_16x16x32_bf16 v[108:111], v[222:225], v[24:27], v[20:23]
	v_mfma_f32_16x16x32_bf16 v[20:23], v[128:131], v[28:31], v[160:163]
	v_mfma_f32_16x16x32_bf16 v[100:103], v[214:217], v[56:59], v[20:23]
	v_mfma_f32_16x16x32_bf16 v[20:23], v[218:221], v[28:31], v[164:167]
	v_mfma_f32_16x16x32_bf16 v[96:99], v[222:225], v[56:59], v[20:23]
	v_mfma_f32_16x16x32_bf16 v[20:23], v[128:131], v[188:191], v[76:79]
	v_mfma_f32_16x16x32_bf16 v[104:107], v[214:217], v[24:27], v[72:75]
	v_mfma_f32_16x16x32_bf16 v[72:75], v[214:217], v[192:195], v[20:23]
	v_mfma_f32_16x16x32_bf16 v[20:23], v[218:221], v[188:191], v[168:171]
	v_mfma_f32_16x16x32_bf16 v[76:79], v[222:225], v[192:195], v[20:23]
	v_mfma_f32_16x16x32_bf16 v[20:23], v[128:131], v[202:205], v[68:71]
	v_mfma_f32_16x16x32_bf16 v[68:71], v[214:217], v[210:213], v[20:23]
	v_mfma_f32_16x16x32_bf16 v[20:23], v[218:221], v[202:205], v[64:67]
	v_mfma_f32_16x16x32_bf16 v[64:67], v[222:225], v[210:213], v[20:23]
	s_setprio 0
	s_barrier
	s_barrier
	s_waitcnt lgkmcnt(0)
	s_setprio 1
	s_waitcnt lgkmcnt(0)
	s_setprio 0
	s_setprio 1
	s_setprio 0
	s_movk_i32 s4, 0x100
	v_cmp_gt_u32_e32 vcc, s4, v132
	s_barrier
	s_and_saveexec_b64 s[4:5], vcc
	s_cbranch_execz .Lhf_195
	s_barrier

.LBB0_192:
	ds_read_b128 v[140:143], v129
	ds_read_b128 v[144:147], v129 offset:1024
	ds_read_b128 v[148:151], v129 offset:2048
	ds_read_b128 v[152:155], v129 offset:3072
	s_add_u32 s28, s56, s4
	s_addc_u32 s29, s57, s5
	ds_read_b128 v[156:159], v136
	ds_read_b128 v[160:163], v136 offset:1024
	ds_read_b128 v[164:167], v135
	ds_read_b128 v[168:171], v135 offset:1024
	ds_read_b128 v[172:175], v134
	ds_read_b128 v[176:179], v134 offset:1024
	ds_read_b128 v[180:183], v133
	ds_read_b128 v[184:187], v133 offset:1024
	s_add_i32 s40, s52, 0xc000
	s_mov_b32 m0, s40
	s_add_i32 s39, s52, 0xe000
	s_add_u32 s98, s28, s44
	s_addc_u32 s99, s29, s45
	global_load_lds_dwordx4 v128, s[98:99]
	s_mov_b32 m0, s39
	s_nop 0
	global_load_lds_dwordx4 v130, s[98:99]
	s_waitcnt lgkmcnt(8)
	s_barrier
	s_waitcnt lgkmcnt(0)
	s_setprio 1
	s_waitcnt lgkmcnt(0)
	v_mfma_f32_16x16x32_bf16 v[124:127], v[140:143], v[156:159], v[124:127]
	v_mfma_f32_16x16x32_bf16 v[120:123], v[148:151], v[156:159], v[120:123]
	v_mfma_f32_16x16x32_bf16 v[116:119], v[140:143], v[164:167], v[116:119]
	v_mfma_f32_16x16x32_bf16 v[112:115], v[148:151], v[164:167], v[112:115]
	v_mfma_f32_16x16x32_bf16 v[108:111], v[140:143], v[172:175], v[108:111]
	v_mfma_f32_16x16x32_bf16 v[104:107], v[148:151], v[172:175], v[104:107]
	v_mfma_f32_16x16x32_bf16 v[100:103], v[140:143], v[180:183], v[100:103]
	v_mfma_f32_16x16x32_bf16 v[96:99], v[148:151], v[180:183], v[96:99]
	v_mfma_f32_16x16x32_bf16 v[124:127], v[144:147], v[160:163], v[124:127]
	v_mfma_f32_16x16x32_bf16 v[120:123], v[152:155], v[160:163], v[120:123]
	v_mfma_f32_16x16x32_bf16 v[116:119], v[144:147], v[168:171], v[116:119]
	v_mfma_f32_16x16x32_bf16 v[112:115], v[152:155], v[168:171], v[112:115]
	v_mfma_f32_16x16x32_bf16 v[108:111], v[144:147], v[176:179], v[108:111]
	v_mfma_f32_16x16x32_bf16 v[104:107], v[152:155], v[176:179], v[104:107]
	v_mfma_f32_16x16x32_bf16 v[100:103], v[144:147], v[184:187], v[100:103]
	v_mfma_f32_16x16x32_bf16 v[96:99], v[152:155], v[184:187], v[96:99]
	s_setprio 0
	s_barrier
	s_add_u32 s58, s56, s36
	s_addc_u32 s59, s57, s37
	ds_read_b128 v[188:191], v139
	ds_read_b128 v[192:195], v139 offset:1024
	ds_read_b128 v[202:205], v139 offset:2048
	ds_read_b128 v[206:209], v139 offset:3072
	s_add_i32 m0, s52, 0x10000
	s_add_u32 s98, s58, s46
	s_addc_u32 s99, s59, s47
	global_load_lds_dwordx4 v128, s[98:99]
	s_add_i32 m0, s52, 0x12000
	s_nop 0
	global_load_lds_dwordx4 v130, s[98:99]
	s_barrier
	s_waitcnt lgkmcnt(0)
	s_setprio 1
	s_waitcnt lgkmcnt(0)
	v_mfma_f32_16x16x32_bf16 v[92:95], v[188:191], v[156:159], v[92:95]
	v_mfma_f32_16x16x32_bf16 v[88:91], v[202:205], v[156:159], v[88:91]
	v_mfma_f32_16x16x32_bf16 v[84:87], v[188:191], v[164:167], v[84:87]
	v_mfma_f32_16x16x32_bf16 v[80:83], v[202:205], v[164:167], v[80:83]
	v_mfma_f32_16x16x32_bf16 v[76:79], v[188:191], v[172:175], v[76:79]
	v_mfma_f32_16x16x32_bf16 v[72:75], v[202:205], v[172:175], v[72:75]
	v_mfma_f32_16x16x32_bf16 v[68:71], v[188:191], v[180:183], v[68:71]
	v_mfma_f32_16x16x32_bf16 v[64:67], v[202:205], v[180:183], v[64:67]
	v_mfma_f32_16x16x32_bf16 v[92:95], v[192:195], v[160:163], v[92:95]
	v_mfma_f32_16x16x32_bf16 v[88:91], v[206:209], v[160:163], v[88:91]
	v_mfma_f32_16x16x32_bf16 v[84:87], v[192:195], v[168:171], v[84:87]
	v_mfma_f32_16x16x32_bf16 v[80:83], v[206:209], v[168:171], v[80:83]
	v_mfma_f32_16x16x32_bf16 v[76:79], v[192:195], v[176:179], v[76:79]
	v_mfma_f32_16x16x32_bf16 v[72:75], v[206:209], v[176:179], v[72:75]
	v_mfma_f32_16x16x32_bf16 v[68:71], v[192:195], v[184:187], v[68:71]
	v_mfma_f32_16x16x32_bf16 v[64:67], v[206:209], v[184:187], v[64:67]
	s_setprio 0
	s_barrier
	ds_read_b128 v[156:159], v136 offset:16384
	ds_read_b128 v[160:163], v136 offset:17408
	ds_read_b128 v[164:167], v135 offset:16384
	ds_read_b128 v[168:171], v135 offset:17408
	ds_read_b128 v[172:175], v134 offset:16384
	ds_read_b128 v[176:179], v134 offset:17408
	ds_read_b128 v[180:183], v133 offset:16384
	ds_read_b128 v[184:187], v133 offset:17408
	s_mov_b32 m0, s52
	s_add_u32 s98, s28, s48
	s_addc_u32 s99, s29, s49
	global_load_lds_dwordx4 v128, s[98:99]
	s_add_i32 m0, s52, 0x2000
	s_nop 0
	global_load_lds_dwordx4 v130, s[98:99]
	s_barrier
	s_waitcnt lgkmcnt(0)
	s_setprio 1
	s_waitcnt lgkmcnt(0)
	v_mfma_f32_16x16x32_bf16 v[60:63], v[140:143], v[156:159], v[60:63]
	v_mfma_f32_16x16x32_bf16 v[56:59], v[148:151], v[156:159], v[56:59]
	v_mfma_f32_16x16x32_bf16 v[52:55], v[140:143], v[164:167], v[52:55]
	v_mfma_f32_16x16x32_bf16 v[48:51], v[148:151], v[164:167], v[48:51]
	v_mfma_f32_16x16x32_bf16 v[44:47], v[140:143], v[172:175], v[44:47]
	v_mfma_f32_16x16x32_bf16 v[40:43], v[148:151], v[172:175], v[40:43]
	v_mfma_f32_16x16x32_bf16 v[36:39], v[140:143], v[180:183], v[36:39]
	v_mfma_f32_16x16x32_bf16 v[32:35], v[148:151], v[180:183], v[32:35]
	v_mfma_f32_16x16x32_bf16 v[60:63], v[144:147], v[160:163], v[60:63]
	v_mfma_f32_16x16x32_bf16 v[56:59], v[152:155], v[160:163], v[56:59]
	v_mfma_f32_16x16x32_bf16 v[52:55], v[144:147], v[168:171], v[52:55]
	v_mfma_f32_16x16x32_bf16 v[48:51], v[152:155], v[168:171], v[48:51]
	v_mfma_f32_16x16x32_bf16 v[44:47], v[144:147], v[176:179], v[44:47]
	v_mfma_f32_16x16x32_bf16 v[40:43], v[152:155], v[176:179], v[40:43]
	v_mfma_f32_16x16x32_bf16 v[36:39], v[144:147], v[184:187], v[36:39]
	v_mfma_f32_16x16x32_bf16 v[32:35], v[152:155], v[184:187], v[32:35]
	s_setprio 0
	s_barrier
	s_add_i32 m0, s52, 0x14000
	s_add_u32 s98, s58, s50
	s_addc_u32 s99, s59, s51
	global_load_lds_dwordx4 v128, s[98:99]
	s_add_i32 m0, s52, 0x16000
	s_nop 0
	global_load_lds_dwordx4 v130, s[98:99]
	s_waitcnt vmcnt(6)
	s_barrier
	s_setprio 1
	v_mfma_f32_16x16x32_bf16 v[28:31], v[188:191], v[156:159], v[28:31]
	v_mfma_f32_16x16x32_bf16 v[24:27], v[202:205], v[156:159], v[24:27]
	v_mfma_f32_16x16x32_bf16 v[20:23], v[188:191], v[164:167], v[20:23]
	v_mfma_f32_16x16x32_bf16 v[16:19], v[202:205], v[164:167], v[16:19]
	v_mfma_f32_16x16x32_bf16 v[12:15], v[188:191], v[172:175], v[12:15]
	v_mfma_f32_16x16x32_bf16 v[8:11], v[202:205], v[172:175], v[8:11]
	v_mfma_f32_16x16x32_bf16 v[4:7], v[188:191], v[180:183], v[4:7]
	v_mfma_f32_16x16x32_bf16 v[0:3], v[202:205], v[180:183], v[0:3]
	v_mfma_f32_16x16x32_bf16 v[28:31], v[192:195], v[160:163], v[28:31]
	v_mfma_f32_16x16x32_bf16 v[24:27], v[206:209], v[160:163], v[24:27]
	v_mfma_f32_16x16x32_bf16 v[20:23], v[192:195], v[168:171], v[20:23]
	v_mfma_f32_16x16x32_bf16 v[16:19], v[206:209], v[168:171], v[16:19]
	v_mfma_f32_16x16x32_bf16 v[12:15], v[192:195], v[176:179], v[12:15]
	v_mfma_f32_16x16x32_bf16 v[8:11], v[206:209], v[176:179], v[8:11]
	v_mfma_f32_16x16x32_bf16 v[4:7], v[192:195], v[184:187], v[4:7]
	v_mfma_f32_16x16x32_bf16 v[0:3], v[206:209], v[184:187], v[0:3]
	s_setprio 0
	s_barrier
	ds_read_b128 v[140:143], v138
	ds_read_b128 v[144:147], v138 offset:1024
	ds_read_b128 v[148:151], v138 offset:2048
	ds_read_b128 v[152:155], v138 offset:3072
	ds_read_b128 v[156:159], v136 offset:32768
	ds_read_b128 v[160:163], v136 offset:33792
	ds_read_b128 v[164:167], v135 offset:32768
	ds_read_b128 v[168:171], v135 offset:33792
	ds_read_b128 v[172:175], v134 offset:32768
	ds_read_b128 v[176:179], v134 offset:33792
	ds_read_b128 v[180:183], v133 offset:32768
	ds_read_b128 v[184:187], v133 offset:33792
	s_add_i32 m0, s52, 0x4000
	s_add_u32 s98, s28, s54
	s_addc_u32 s99, s29, s55
	global_load_lds_dwordx4 v128, s[98:99]
	s_add_i32 m0, s52, 0x6000
	s_nop 0
	global_load_lds_dwordx4 v130, s[98:99]
	s_waitcnt lgkmcnt(8)
	s_barrier
	s_waitcnt lgkmcnt(0)
	s_setprio 1
	s_waitcnt lgkmcnt(0)
	v_mfma_f32_16x16x32_bf16 v[124:127], v[140:143], v[156:159], v[124:127]
	v_mfma_f32_16x16x32_bf16 v[120:123], v[148:151], v[156:159], v[120:123]
	v_mfma_f32_16x16x32_bf16 v[116:119], v[140:143], v[164:167], v[116:119]
	v_mfma_f32_16x16x32_bf16 v[112:115], v[148:151], v[164:167], v[112:115]
	v_mfma_f32_16x16x32_bf16 v[108:111], v[140:143], v[172:175], v[108:111]
	v_mfma_f32_16x16x32_bf16 v[104:107], v[148:151], v[172:175], v[104:107]
	v_mfma_f32_16x16x32_bf16 v[100:103], v[140:143], v[180:183], v[100:103]
	v_mfma_f32_16x16x32_bf16 v[96:99], v[148:151], v[180:183], v[96:99]
	v_mfma_f32_16x16x32_bf16 v[124:127], v[144:147], v[160:163], v[124:127]
	v_mfma_f32_16x16x32_bf16 v[120:123], v[152:155], v[160:163], v[120:123]
	v_mfma_f32_16x16x32_bf16 v[116:119], v[144:147], v[168:171], v[116:119]
	v_mfma_f32_16x16x32_bf16 v[112:115], v[152:155], v[168:171], v[112:115]
	v_mfma_f32_16x16x32_bf16 v[108:111], v[144:147], v[176:179], v[108:111]
	v_mfma_f32_16x16x32_bf16 v[104:107], v[152:155], v[176:179], v[104:107]
	v_mfma_f32_16x16x32_bf16 v[100:103], v[144:147], v[184:187], v[100:103]
	v_mfma_f32_16x16x32_bf16 v[96:99], v[152:155], v[184:187], v[96:99]
	s_setprio 0
	s_barrier
	ds_read_b128 v[188:191], v137
	ds_read_b128 v[192:195], v137 offset:1024
	ds_read_b128 v[202:205], v137 offset:2048
	ds_read_b128 v[206:209], v137 offset:3072
	s_mov_b32 m0, s7
	s_add_u32 s98, s58, s68
	s_addc_u32 s99, s59, s69
	global_load_lds_dwordx4 v128, s[98:99]
	s_mov_b32 m0, s53
	s_nop 0
	global_load_lds_dwordx4 v130, s[98:99]
	s_barrier
	s_waitcnt lgkmcnt(0)
	s_setprio 1
	s_waitcnt lgkmcnt(0)
	v_mfma_f32_16x16x32_bf16 v[92:95], v[188:191], v[156:159], v[92:95]
	v_mfma_f32_16x16x32_bf16 v[88:91], v[202:205], v[156:159], v[88:91]
	v_mfma_f32_16x16x32_bf16 v[84:87], v[188:191], v[164:167], v[84:87]
	v_mfma_f32_16x16x32_bf16 v[80:83], v[202:205], v[164:167], v[80:83]
	v_mfma_f32_16x16x32_bf16 v[76:79], v[188:191], v[172:175], v[76:79]
	v_mfma_f32_16x16x32_bf16 v[72:75], v[202:205], v[172:175], v[72:75]
	v_mfma_f32_16x16x32_bf16 v[68:71], v[188:191], v[180:183], v[68:71]
	v_mfma_f32_16x16x32_bf16 v[64:67], v[202:205], v[180:183], v[64:67]
	v_mfma_f32_16x16x32_bf16 v[92:95], v[192:195], v[160:163], v[92:95]
	v_mfma_f32_16x16x32_bf16 v[88:91], v[206:209], v[160:163], v[88:91]
	v_mfma_f32_16x16x32_bf16 v[84:87], v[192:195], v[168:171], v[84:87]
	v_mfma_f32_16x16x32_bf16 v[80:83], v[206:209], v[168:171], v[80:83]
	v_mfma_f32_16x16x32_bf16 v[76:79], v[192:195], v[176:179], v[76:79]
	v_mfma_f32_16x16x32_bf16 v[72:75], v[206:209], v[176:179], v[72:75]
	v_mfma_f32_16x16x32_bf16 v[68:71], v[192:195], v[184:187], v[68:71]
	v_mfma_f32_16x16x32_bf16 v[64:67], v[206:209], v[184:187], v[64:67]
	s_setprio 0
	v_mov_b32_e32 v210, v130
	s_barrier
	ds_read_b128 v[156:159], v136 offset:49152
	ds_read_b128 v[160:163], v136 offset:50176
	ds_read_b128 v[164:167], v135 offset:49152
	ds_read_b128 v[168:171], v135 offset:50176
	ds_read_b128 v[172:175], v134 offset:49152
	ds_read_b128 v[176:179], v134 offset:50176
	ds_read_b128 v[180:183], v133 offset:49152
	ds_read_b128 v[184:187], v133 offset:50176
	v_mov_b32_e32 v211, v197
	s_mov_b32 m0, s9
	s_add_u32 s98, s28, s70
	s_addc_u32 s99, s29, s71
	global_load_lds_dwordx4 v128, s[98:99]
	s_mov_b32 m0, s33
	s_nop 0
	global_load_lds_dwordx4 v130, s[98:99]
	s_barrier
	s_waitcnt lgkmcnt(0)
	s_setprio 1
	s_waitcnt lgkmcnt(0)
	v_mfma_f32_16x16x32_bf16 v[60:63], v[140:143], v[156:159], v[60:63]
	v_mfma_f32_16x16x32_bf16 v[56:59], v[148:151], v[156:159], v[56:59]
	v_mfma_f32_16x16x32_bf16 v[52:55], v[140:143], v[164:167], v[52:55]
	v_mfma_f32_16x16x32_bf16 v[48:51], v[148:151], v[164:167], v[48:51]
	v_mfma_f32_16x16x32_bf16 v[44:47], v[140:143], v[172:175], v[44:47]
	v_mfma_f32_16x16x32_bf16 v[40:43], v[148:151], v[172:175], v[40:43]
	v_mfma_f32_16x16x32_bf16 v[36:39], v[140:143], v[180:183], v[36:39]
	v_mfma_f32_16x16x32_bf16 v[32:35], v[148:151], v[180:183], v[32:35]
	v_mfma_f32_16x16x32_bf16 v[60:63], v[144:147], v[160:163], v[60:63]
	v_mfma_f32_16x16x32_bf16 v[56:59], v[152:155], v[160:163], v[56:59]
	v_mfma_f32_16x16x32_bf16 v[52:55], v[144:147], v[168:171], v[52:55]
	v_mfma_f32_16x16x32_bf16 v[48:51], v[152:155], v[168:171], v[48:51]
	v_mfma_f32_16x16x32_bf16 v[44:47], v[144:147], v[176:179], v[44:47]
	v_mfma_f32_16x16x32_bf16 v[40:43], v[152:155], v[176:179], v[40:43]
	v_mfma_f32_16x16x32_bf16 v[36:39], v[144:147], v[184:187], v[36:39]
	v_mfma_f32_16x16x32_bf16 v[32:35], v[152:155], v[184:187], v[32:35]
	s_setprio 0
	s_barrier
	v_mov_b32_e32 v196, v128
	s_mov_b32 m0, s65
	s_add_u32 s98, s58, s72
	s_addc_u32 s99, s59, s73
	global_load_lds_dwordx4 v128, s[98:99]
	s_mov_b32 m0, s66
	s_nop 0
	global_load_lds_dwordx4 v130, s[98:99]
	s_waitcnt vmcnt(6)
	s_barrier
	s_setprio 1
	v_mfma_f32_16x16x32_bf16 v[28:31], v[188:191], v[156:159], v[28:31]
	v_mfma_f32_16x16x32_bf16 v[24:27], v[202:205], v[156:159], v[24:27]
	v_mfma_f32_16x16x32_bf16 v[20:23], v[188:191], v[164:167], v[20:23]
	v_mfma_f32_16x16x32_bf16 v[16:19], v[202:205], v[164:167], v[16:19]
	v_mfma_f32_16x16x32_bf16 v[12:15], v[188:191], v[172:175], v[12:15]
	v_mfma_f32_16x16x32_bf16 v[8:11], v[202:205], v[172:175], v[8:11]
	v_mfma_f32_16x16x32_bf16 v[4:7], v[188:191], v[180:183], v[4:7]
	v_mfma_f32_16x16x32_bf16 v[0:3], v[202:205], v[180:183], v[0:3]
	v_mfma_f32_16x16x32_bf16 v[28:31], v[192:195], v[160:163], v[28:31]
	v_mfma_f32_16x16x32_bf16 v[24:27], v[206:209], v[160:163], v[24:27]
	v_mfma_f32_16x16x32_bf16 v[20:23], v[192:195], v[168:171], v[20:23]
	v_mfma_f32_16x16x32_bf16 v[16:19], v[206:209], v[168:171], v[16:19]
	v_mfma_f32_16x16x32_bf16 v[12:15], v[192:195], v[176:179], v[12:15]
	v_mfma_f32_16x16x32_bf16 v[8:11], v[206:209], v[176:179], v[8:11]
	v_mfma_f32_16x16x32_bf16 v[4:7], v[192:195], v[184:187], v[4:7]
	v_mfma_f32_16x16x32_bf16 v[0:3], v[206:209], v[184:187], v[0:3]
	s_setprio 0
	s_add_i32 s38, s38, 2
	s_add_u32 s56, s56, 0x100
	s_addc_u32 s57, s57, 0
	s_cmp_lt_u32 s38, 28
	s_barrier
	s_cbranch_scc1 .LBB0_192
	s_lshl_b64 s[4:5], s[10:11], 12
	v_readlane_b32 s10, v254, 12
	v_readlane_b32 s11, v254, 13
	s_add_u32 s4, s10, s4
	s_addc_u32 s5, s11, s5
	ds_read_b128 v[140:143], v129
	ds_read_b128 v[144:147], v129 offset:1024
	ds_read_b128 v[148:151], v129 offset:2048
	ds_read_b128 v[152:155], v129 offset:3072
	ds_read_b128 v[156:159], v136
	ds_read_b128 v[160:163], v136 offset:1024
	ds_read_b128 v[164:167], v135
	ds_read_b128 v[168:171], v135 offset:1024
	ds_read_b128 v[172:175], v134
	ds_read_b128 v[176:179], v134 offset:1024
	ds_read_b128 v[180:183], v133
	ds_read_b128 v[184:187], v133 offset:1024
	v_mov_b32_e32 v129, v197
	v_lshl_add_u64 v[128:129], s[4:5], 0, v[128:129]
	s_mov_b64 s[10:11], 0xf80
	s_mov_b32 m0, s40
	v_lshl_add_u64 v[128:129], v[128:129], 0, s[10:11]
	v_mov_b32_e32 v131, v197
	global_load_lds_dwordx4 v[128:129], off
	v_lshl_add_u64 v[128:129], s[4:5], 0, v[130:131]
	v_lshl_add_u64 v[128:129], v[128:129], 0, s[10:11]
	s_mov_b32 m0, s39
	s_nop 0
	global_load_lds_dwordx4 v[128:129], off
	s_barrier
	s_waitcnt lgkmcnt(0)
	s_setprio 1
	s_waitcnt lgkmcnt(0)
	v_mfma_f32_16x16x32_bf16 v[124:127], v[140:143], v[156:159], v[124:127]
	v_mfma_f32_16x16x32_bf16 v[116:119], v[140:143], v[164:167], v[116:119]
	v_mfma_f32_16x16x32_bf16 v[112:115], v[148:151], v[164:167], v[112:115]
	v_mfma_f32_16x16x32_bf16 v[108:111], v[140:143], v[172:175], v[108:111]
	v_mfma_f32_16x16x32_bf16 v[104:107], v[148:151], v[172:175], v[104:107]
	v_mfma_f32_16x16x32_bf16 v[100:103], v[140:143], v[180:183], v[100:103]
	v_mfma_f32_16x16x32_bf16 v[96:99], v[148:151], v[180:183], v[96:99]
	v_mfma_f32_16x16x32_bf16 v[124:127], v[144:147], v[160:163], v[124:127]
	v_mfma_f32_16x16x32_bf16 v[120:123], v[148:151], v[156:159], v[120:123]
	v_mfma_f32_16x16x32_bf16 v[116:119], v[144:147], v[168:171], v[116:119]
	v_mfma_f32_16x16x32_bf16 v[112:115], v[152:155], v[168:171], v[112:115]
	v_mfma_f32_16x16x32_bf16 v[108:111], v[144:147], v[176:179], v[108:111]
	v_mfma_f32_16x16x32_bf16 v[104:107], v[152:155], v[176:179], v[104:107]
	v_mfma_f32_16x16x32_bf16 v[100:103], v[144:147], v[184:187], v[100:103]
	v_mfma_f32_16x16x32_bf16 v[96:99], v[152:155], v[184:187], v[96:99]
	v_mfma_f32_16x16x32_bf16 v[128:131], v[152:155], v[160:163], v[120:123]
	s_setprio 0
	s_barrier
	s_nop 0
	ds_read_b128 v[120:123], v139
	ds_read_b128 v[188:191], v139 offset:1024
	ds_read_b128 v[192:195], v139 offset:2048
	ds_read_b128 v[202:205], v139 offset:3072
	s_barrier
	s_waitcnt lgkmcnt(0)
	s_setprio 1
	s_waitcnt lgkmcnt(0)
	v_mfma_f32_16x16x32_bf16 v[76:79], v[120:123], v[172:175], v[76:79]
	v_mfma_f32_16x16x32_bf16 v[68:71], v[120:123], v[180:183], v[68:71]
	v_mfma_f32_16x16x32_bf16 v[64:67], v[192:195], v[180:183], v[64:67]
	v_mfma_f32_16x16x32_bf16 v[92:95], v[120:123], v[156:159], v[92:95]
	v_mfma_f32_16x16x32_bf16 v[88:91], v[192:195], v[156:159], v[88:91]
	v_mfma_f32_16x16x32_bf16 v[84:87], v[120:123], v[164:167], v[84:87]
	v_mfma_f32_16x16x32_bf16 v[80:83], v[192:195], v[164:167], v[80:83]
	v_mfma_f32_16x16x32_bf16 v[76:79], v[188:191], v[176:179], v[76:79]
	v_mfma_f32_16x16x32_bf16 v[72:75], v[192:195], v[172:175], v[72:75]
	v_mfma_f32_16x16x32_bf16 v[68:71], v[188:191], v[184:187], v[68:71]
	v_mfma_f32_16x16x32_bf16 v[64:67], v[202:205], v[184:187], v[64:67]
	v_mfma_f32_16x16x32_bf16 v[206:209], v[188:191], v[160:163], v[92:95]
	v_mfma_f32_16x16x32_bf16 v[156:159], v[202:205], v[160:163], v[88:91]
	v_mfma_f32_16x16x32_bf16 v[160:163], v[188:191], v[168:171], v[84:87]
	v_mfma_f32_16x16x32_bf16 v[164:167], v[202:205], v[168:171], v[80:83]
	v_mfma_f32_16x16x32_bf16 v[168:171], v[202:205], v[176:179], v[72:75]
	s_setprio 0
	s_barrier
	s_nop 0
	ds_read_b128 v[72:75], v136 offset:16384
	ds_read_b128 v[80:83], v136 offset:17408
	ds_read_b128 v[84:87], v135 offset:16384
	ds_read_b128 v[88:91], v135 offset:17408
	ds_read_b128 v[92:95], v134 offset:16384
	ds_read_b128 v[172:175], v134 offset:17408
	ds_read_b128 v[176:179], v133 offset:16384
	ds_read_b128 v[180:183], v133 offset:17408
	s_waitcnt vmcnt(4)
	s_barrier
	s_waitcnt lgkmcnt(0)
	s_setprio 1
	s_waitcnt lgkmcnt(0)
	v_mfma_f32_16x16x32_bf16 v[60:63], v[140:143], v[72:75], v[60:63]
	v_mfma_f32_16x16x32_bf16 v[52:55], v[140:143], v[84:87], v[52:55]
	v_mfma_f32_16x16x32_bf16 v[48:51], v[148:151], v[84:87], v[48:51]
	v_mfma_f32_16x16x32_bf16 v[44:47], v[140:143], v[92:95], v[44:47]
	v_mfma_f32_16x16x32_bf16 v[40:43], v[148:151], v[92:95], v[40:43]
	v_mfma_f32_16x16x32_bf16 v[36:39], v[140:143], v[176:179], v[36:39]
	v_mfma_f32_16x16x32_bf16 v[32:35], v[148:151], v[176:179], v[32:35]
	v_mfma_f32_16x16x32_bf16 v[60:63], v[144:147], v[80:83], v[60:63]
	v_mfma_f32_16x16x32_bf16 v[56:59], v[148:151], v[72:75], v[56:59]
	v_mfma_f32_16x16x32_bf16 v[52:55], v[144:147], v[88:91], v[52:55]
	v_mfma_f32_16x16x32_bf16 v[48:51], v[152:155], v[88:91], v[48:51]
	v_mfma_f32_16x16x32_bf16 v[44:47], v[144:147], v[172:175], v[44:47]
	v_mfma_f32_16x16x32_bf16 v[40:43], v[152:155], v[172:175], v[40:43]
	v_mfma_f32_16x16x32_bf16 v[36:39], v[144:147], v[180:183], v[36:39]
	v_mfma_f32_16x16x32_bf16 v[32:35], v[152:155], v[180:183], v[32:35]
	v_mfma_f32_16x16x32_bf16 v[184:187], v[152:155], v[80:83], v[56:59]
	s_setprio 0
	s_setprio 1
	v_mfma_f32_16x16x32_bf16 v[12:15], v[120:123], v[92:95], v[12:15]
	v_mfma_f32_16x16x32_bf16 v[4:7], v[120:123], v[176:179], v[4:7]
	v_mfma_f32_16x16x32_bf16 v[0:3], v[192:195], v[176:179], v[0:3]
	v_mfma_f32_16x16x32_bf16 v[28:31], v[120:123], v[72:75], v[28:31]
	v_mfma_f32_16x16x32_bf16 v[24:27], v[192:195], v[72:75], v[24:27]
	v_mfma_f32_16x16x32_bf16 v[20:23], v[120:123], v[84:87], v[20:23]
	v_mfma_f32_16x16x32_bf16 v[16:19], v[192:195], v[84:87], v[16:19]
	v_mfma_f32_16x16x32_bf16 v[12:15], v[188:191], v[172:175], v[12:15]
	v_mfma_f32_16x16x32_bf16 v[8:11], v[192:195], v[92:95], v[8:11]
	v_mfma_f32_16x16x32_bf16 v[4:7], v[188:191], v[180:183], v[4:7]
	v_mfma_f32_16x16x32_bf16 v[0:3], v[202:205], v[180:183], v[0:3]
	v_mfma_f32_16x16x32_bf16 v[140:143], v[188:191], v[80:83], v[28:31]
	v_mfma_f32_16x16x32_bf16 v[144:147], v[202:205], v[80:83], v[24:27]
	v_mfma_f32_16x16x32_bf16 v[148:151], v[188:191], v[88:91], v[20:23]
	v_mfma_f32_16x16x32_bf16 v[152:155], v[202:205], v[88:91], v[16:19]
	v_mfma_f32_16x16x32_bf16 v[172:175], v[202:205], v[172:175], v[8:11]
	s_setprio 0
	s_barrier
	s_nop 0
	ds_read_b128 v[8:11], v138
	ds_read_b128 v[16:19], v138 offset:1024
	ds_read_b128 v[176:179], v138 offset:2048
	ds_read_b128 v[180:183], v138 offset:3072
	ds_read_b128 v[20:23], v136 offset:32768
	ds_read_b128 v[24:27], v136 offset:33792
	ds_read_b128 v[28:31], v135 offset:32768
	ds_read_b128 v[56:59], v135 offset:33792
	ds_read_b128 v[188:191], v134 offset:32768
	ds_read_b128 v[192:195], v134 offset:33792
	ds_read_b128 v[202:205], v133 offset:32768
	ds_read_b128 v[210:213], v133 offset:33792
	s_waitcnt vmcnt(2)
	s_barrier
	s_waitcnt lgkmcnt(0)
	s_setprio 1
	s_waitcnt lgkmcnt(0)
	v_mfma_f32_16x16x32_bf16 v[72:75], v[8:11], v[20:23], v[124:127]
	v_mfma_f32_16x16x32_bf16 v[120:123], v[16:19], v[24:27], v[72:75]
	v_mfma_f32_16x16x32_bf16 v[72:75], v[176:179], v[20:23], v[128:131]
	v_mfma_f32_16x16x32_bf16 v[124:127], v[180:183], v[24:27], v[72:75]
	v_mfma_f32_16x16x32_bf16 v[72:75], v[8:11], v[28:31], v[116:119]
	v_mfma_f32_16x16x32_bf16 v[116:119], v[16:19], v[56:59], v[72:75]
	v_mfma_f32_16x16x32_bf16 v[72:75], v[176:179], v[28:31], v[112:115]
	v_mfma_f32_16x16x32_bf16 v[112:115], v[180:183], v[56:59], v[72:75]
	v_mfma_f32_16x16x32_bf16 v[72:75], v[8:11], v[188:191], v[108:111]
	v_mfma_f32_16x16x32_bf16 v[88:91], v[16:19], v[192:195], v[72:75]
	v_mfma_f32_16x16x32_bf16 v[72:75], v[176:179], v[188:191], v[104:107]
	v_mfma_f32_16x16x32_bf16 v[92:95], v[180:183], v[192:195], v[72:75]
	v_mfma_f32_16x16x32_bf16 v[72:75], v[8:11], v[202:205], v[100:103]
	v_mfma_f32_16x16x32_bf16 v[84:87], v[16:19], v[210:213], v[72:75]
	v_mfma_f32_16x16x32_bf16 v[72:75], v[176:179], v[202:205], v[96:99]
	v_mfma_f32_16x16x32_bf16 v[80:83], v[180:183], v[210:213], v[72:75]
	s_setprio 0
	s_barrier
	ds_read_b128 v[128:131], v137
	ds_read_b128 v[214:217], v137 offset:1024
	ds_read_b128 v[218:221], v137 offset:2048
	ds_read_b128 v[222:225], v137 offset:3072
	s_waitcnt vmcnt(0)
	s_barrier
	s_waitcnt lgkmcnt(0)
	s_setprio 1
	s_waitcnt lgkmcnt(0)
	v_mfma_f32_16x16x32_bf16 v[72:75], v[128:131], v[20:23], v[206:209]
	v_mfma_f32_16x16x32_bf16 v[20:23], v[218:221], v[20:23], v[156:159]
	v_mfma_f32_16x16x32_bf16 v[108:111], v[222:225], v[24:27], v[20:23]
	v_mfma_f32_16x16x32_bf16 v[20:23], v[128:131], v[28:31], v[160:163]
	v_mfma_f32_16x16x32_bf16 v[100:103], v[214:217], v[56:59], v[20:23]
	v_mfma_f32_16x16x32_bf16 v[20:23], v[218:221], v[28:31], v[164:167]
	v_mfma_f32_16x16x32_bf16 v[96:99], v[222:225], v[56:59], v[20:23]
	v_mfma_f32_16x16x32_bf16 v[20:23], v[128:131], v[188:191], v[76:79]
	v_mfma_f32_16x16x32_bf16 v[104:107], v[214:217], v[24:27], v[72:75]
	v_mfma_f32_16x16x32_bf16 v[72:75], v[214:217], v[192:195], v[20:23]
	v_mfma_f32_16x16x32_bf16 v[20:23], v[218:221], v[188:191], v[168:171]
	v_mfma_f32_16x16x32_bf16 v[76:79], v[222:225], v[192:195], v[20:23]
	v_mfma_f32_16x16x32_bf16 v[20:23], v[128:131], v[202:205], v[68:71]
	v_mfma_f32_16x16x32_bf16 v[68:71], v[214:217], v[210:213], v[20:23]
	v_mfma_f32_16x16x32_bf16 v[20:23], v[218:221], v[202:205], v[64:67]
	v_mfma_f32_16x16x32_bf16 v[64:67], v[222:225], v[210:213], v[20:23]
	s_setprio 0
	s_barrier
	ds_read_b128 v[156:159], v136 offset:49152
	ds_read_b128 v[136:139], v136 offset:50176
	ds_read_b128 v[160:163], v135 offset:49152
	ds_read_b128 v[164:167], v135 offset:50176
	ds_read_b128 v[168:171], v134 offset:49152
	ds_read_b128 v[188:191], v134 offset:50176
	ds_read_b128 v[192:195], v133 offset:49152
	ds_read_b128 v[202:205], v133 offset:50176
	s_barrier
	s_waitcnt lgkmcnt(0)
	s_setprio 1
	s_waitcnt lgkmcnt(0)
	v_mfma_f32_16x16x32_bf16 v[20:23], v[8:11], v[156:159], v[60:63]
	v_mfma_f32_16x16x32_bf16 v[56:59], v[16:19], v[136:139], v[20:23]
	v_mfma_f32_16x16x32_bf16 v[20:23], v[176:179], v[156:159], v[184:187]
	v_mfma_f32_16x16x32_bf16 v[60:63], v[180:183], v[136:139], v[20:23]
	v_mfma_f32_16x16x32_bf16 v[20:23], v[8:11], v[160:163], v[52:55]
	v_mfma_f32_16x16x32_bf16 v[52:55], v[16:19], v[164:167], v[20:23]
	v_mfma_f32_16x16x32_bf16 v[20:23], v[176:179], v[160:163], v[48:51]
	v_mfma_f32_16x16x32_bf16 v[48:51], v[180:183], v[164:167], v[20:23]
	v_mfma_f32_16x16x32_bf16 v[20:23], v[8:11], v[168:171], v[44:47]
	v_mfma_f32_16x16x32_bf16 v[24:27], v[16:19], v[188:191], v[20:23]
	v_mfma_f32_16x16x32_bf16 v[20:23], v[176:179], v[168:171], v[40:43]
	v_mfma_f32_16x16x32_bf16 v[8:11], v[8:11], v[192:195], v[36:39]
	v_mfma_f32_16x16x32_bf16 v[28:31], v[180:183], v[188:191], v[20:23]
	v_mfma_f32_16x16x32_bf16 v[20:23], v[16:19], v[202:205], v[8:11]
	v_mfma_f32_16x16x32_bf16 v[8:11], v[176:179], v[192:195], v[32:35]
	v_mfma_f32_16x16x32_bf16 v[16:19], v[180:183], v[202:205], v[8:11]
	s_setprio 0
	s_setprio 1
	v_mfma_f32_16x16x32_bf16 v[8:11], v[128:131], v[156:159], v[140:143]
	v_mfma_f32_16x16x32_bf16 v[40:43], v[214:217], v[136:139], v[8:11]
	v_mfma_f32_16x16x32_bf16 v[8:11], v[218:221], v[156:159], v[144:147]
	v_mfma_f32_16x16x32_bf16 v[44:47], v[222:225], v[136:139], v[8:11]
	v_mfma_f32_16x16x32_bf16 v[8:11], v[128:131], v[160:163], v[148:151]
	v_mfma_f32_16x16x32_bf16 v[36:39], v[214:217], v[164:167], v[8:11]
	v_mfma_f32_16x16x32_bf16 v[8:11], v[218:221], v[160:163], v[152:155]
	v_mfma_f32_16x16x32_bf16 v[32:35], v[222:225], v[164:167], v[8:11]
	v_mfma_f32_16x16x32_bf16 v[8:11], v[128:131], v[168:171], v[12:15]
	v_mfma_f32_16x16x32_bf16 v[12:15], v[218:221], v[168:171], v[172:175]
	v_mfma_f32_16x16x32_bf16 v[4:7], v[128:131], v[192:195], v[4:7]
	v_mfma_f32_16x16x32_bf16 v[0:3], v[218:221], v[192:195], v[0:3]
	v_mfma_f32_16x16x32_bf16 v[8:11], v[214:217], v[188:191], v[8:11]
	v_mfma_f32_16x16x32_bf16 v[12:15], v[222:225], v[188:191], v[12:15]
	v_mfma_f32_16x16x32_bf16 v[4:7], v[214:217], v[202:205], v[4:7]
	v_mfma_f32_16x16x32_bf16 v[0:3], v[222:225], v[202:205], v[0:3]
	s_setprio 0
	s_movk_i32 s4, 0x100
	v_cmp_gt_u32_e32 vcc, s4, v132
	s_barrier
	s_and_saveexec_b64 s[4:5], vcc
	s_cbranch_execz .LBB0_195
	s_barrier

.Lh1_loop:
	ds_read_b128 v[140:143], v129
	ds_read_b128 v[144:147], v129 offset:1024
	ds_read_b128 v[148:151], v129 offset:2048
	ds_read_b128 v[152:155], v129 offset:3072
	s_add_u32 s28, s60, s56
	s_addc_u32 s29, s61, s57
	ds_read_b128 v[156:159], v136
	ds_read_b128 v[160:163], v136 offset:1024
	ds_read_b128 v[164:167], v135
	ds_read_b128 v[168:171], v135 offset:1024
	ds_read_b128 v[172:175], v134
	ds_read_b128 v[176:179], v134 offset:1024
	ds_read_b128 v[180:183], v133
	ds_read_b128 v[184:187], v133 offset:1024
	s_add_i32 s40, s53, 0xc000
	s_mov_b32 m0, s40
	s_add_i32 s39, s53, 0xe000
	s_mov_b32 m0, s39
	s_nop 0
	s_waitcnt lgkmcnt(8)
	s_barrier
	s_waitcnt lgkmcnt(0)
	s_setprio 1
	s_waitcnt lgkmcnt(0)
	v_mfma_f32_16x16x32_bf16 v[124:127], v[140:143], v[156:159], v[124:127]
	v_mfma_f32_16x16x32_bf16 v[120:123], v[148:151], v[156:159], v[120:123]
	v_mfma_f32_16x16x32_bf16 v[116:119], v[140:143], v[164:167], v[116:119]
	v_mfma_f32_16x16x32_bf16 v[112:115], v[148:151], v[164:167], v[112:115]
	v_mfma_f32_16x16x32_bf16 v[108:111], v[140:143], v[172:175], v[108:111]
	v_mfma_f32_16x16x32_bf16 v[104:107], v[148:151], v[172:175], v[104:107]
	v_mfma_f32_16x16x32_bf16 v[100:103], v[140:143], v[180:183], v[100:103]
	v_mfma_f32_16x16x32_bf16 v[96:99], v[148:151], v[180:183], v[96:99]
	v_mfma_f32_16x16x32_bf16 v[124:127], v[144:147], v[160:163], v[124:127]
	v_mfma_f32_16x16x32_bf16 v[120:123], v[152:155], v[160:163], v[120:123]
	v_mfma_f32_16x16x32_bf16 v[116:119], v[144:147], v[168:171], v[116:119]
	v_mfma_f32_16x16x32_bf16 v[112:115], v[152:155], v[168:171], v[112:115]
	v_mfma_f32_16x16x32_bf16 v[108:111], v[144:147], v[176:179], v[108:111]
	v_mfma_f32_16x16x32_bf16 v[104:107], v[152:155], v[176:179], v[104:107]
	v_mfma_f32_16x16x32_bf16 v[100:103], v[144:147], v[184:187], v[100:103]
	v_mfma_f32_16x16x32_bf16 v[96:99], v[152:155], v[184:187], v[96:99]
	s_setprio 0
	s_barrier
	s_add_u32 s62, s60, s36
	s_addc_u32 s63, s61, s37
	ds_read_b128 v[188:191], v139
	ds_read_b128 v[192:195], v139 offset:1024
	ds_read_b128 v[202:205], v139 offset:2048
	ds_read_b128 v[206:209], v139 offset:3072
	s_mov_b32 m0, s68
	s_add_u32 s98, s62, s46
	s_addc_u32 s99, s63, s47
	global_load_lds_dwordx4 v128, s[98:99]
	s_mov_b32 m0, s69
	s_nop 0
	global_load_lds_dwordx4 v130, s[98:99]
	s_barrier
	s_waitcnt lgkmcnt(0)
	s_setprio 1
	s_waitcnt lgkmcnt(0)
	v_mfma_f32_16x16x32_bf16 v[92:95], v[188:191], v[156:159], v[92:95]
	v_mfma_f32_16x16x32_bf16 v[88:91], v[202:205], v[156:159], v[88:91]
	v_mfma_f32_16x16x32_bf16 v[84:87], v[188:191], v[164:167], v[84:87]
	v_mfma_f32_16x16x32_bf16 v[80:83], v[202:205], v[164:167], v[80:83]
	v_mfma_f32_16x16x32_bf16 v[76:79], v[188:191], v[172:175], v[76:79]
	v_mfma_f32_16x16x32_bf16 v[72:75], v[202:205], v[172:175], v[72:75]
	v_mfma_f32_16x16x32_bf16 v[68:71], v[188:191], v[180:183], v[68:71]
	v_mfma_f32_16x16x32_bf16 v[64:67], v[202:205], v[180:183], v[64:67]
	v_mfma_f32_16x16x32_bf16 v[92:95], v[192:195], v[160:163], v[92:95]
	v_mfma_f32_16x16x32_bf16 v[88:91], v[206:209], v[160:163], v[88:91]
	v_mfma_f32_16x16x32_bf16 v[84:87], v[192:195], v[168:171], v[84:87]
	v_mfma_f32_16x16x32_bf16 v[80:83], v[206:209], v[168:171], v[80:83]
	v_mfma_f32_16x16x32_bf16 v[76:79], v[192:195], v[176:179], v[76:79]
	v_mfma_f32_16x16x32_bf16 v[72:75], v[206:209], v[176:179], v[72:75]
	v_mfma_f32_16x16x32_bf16 v[68:71], v[192:195], v[184:187], v[68:71]
	v_mfma_f32_16x16x32_bf16 v[64:67], v[206:209], v[184:187], v[64:67]
	s_setprio 0
	s_barrier
	s_mov_b32 m0, s53
	s_add_u32 s98, s28, s48
	s_addc_u32 s99, s29, s49
	global_load_lds_dwordx4 v128, s[98:99]
	s_mov_b32 m0, s11
	s_nop 0
	global_load_lds_dwordx4 v130, s[98:99]
	s_waitcnt vmcnt(4)
	s_barrier
	s_mov_b32 m0, s9
	s_add_u32 s98, s62, s50
	s_addc_u32 s99, s63, s51
	global_load_lds_dwordx4 v128, s[98:99]
	s_mov_b32 m0, s70
	s_nop 0
	global_load_lds_dwordx4 v130, s[98:99]
	s_barrier
	ds_read_b128 v[140:143], v138
	ds_read_b128 v[144:147], v138 offset:1024
	ds_read_b128 v[148:151], v138 offset:2048
	ds_read_b128 v[152:155], v138 offset:3072
	ds_read_b128 v[156:159], v136 offset:32768
	ds_read_b128 v[160:163], v136 offset:33792
	ds_read_b128 v[164:167], v135 offset:32768
	ds_read_b128 v[168:171], v135 offset:33792
	ds_read_b128 v[172:175], v134 offset:32768
	ds_read_b128 v[176:179], v134 offset:33792
	ds_read_b128 v[180:183], v133 offset:32768
	ds_read_b128 v[184:187], v133 offset:33792
	s_mov_b32 m0, s71
	s_mov_b32 m0, s72
	s_nop 0
	s_waitcnt lgkmcnt(8)
	s_barrier
	s_waitcnt lgkmcnt(0)
	s_setprio 1
	s_waitcnt lgkmcnt(0)
	v_mfma_f32_16x16x32_bf16 v[124:127], v[140:143], v[156:159], v[124:127]
	v_mfma_f32_16x16x32_bf16 v[120:123], v[148:151], v[156:159], v[120:123]
	v_mfma_f32_16x16x32_bf16 v[116:119], v[140:143], v[164:167], v[116:119]
	v_mfma_f32_16x16x32_bf16 v[112:115], v[148:151], v[164:167], v[112:115]
	v_mfma_f32_16x16x32_bf16 v[108:111], v[140:143], v[172:175], v[108:111]
	v_mfma_f32_16x16x32_bf16 v[104:107], v[148:151], v[172:175], v[104:107]
	v_mfma_f32_16x16x32_bf16 v[100:103], v[140:143], v[180:183], v[100:103]
	v_mfma_f32_16x16x32_bf16 v[96:99], v[148:151], v[180:183], v[96:99]
	v_mfma_f32_16x16x32_bf16 v[124:127], v[144:147], v[160:163], v[124:127]
	v_mfma_f32_16x16x32_bf16 v[120:123], v[152:155], v[160:163], v[120:123]
	v_mfma_f32_16x16x32_bf16 v[116:119], v[144:147], v[168:171], v[116:119]
	v_mfma_f32_16x16x32_bf16 v[112:115], v[152:155], v[168:171], v[112:115]
	v_mfma_f32_16x16x32_bf16 v[108:111], v[144:147], v[176:179], v[108:111]
	v_mfma_f32_16x16x32_bf16 v[104:107], v[152:155], v[176:179], v[104:107]
	v_mfma_f32_16x16x32_bf16 v[100:103], v[144:147], v[184:187], v[100:103]
	v_mfma_f32_16x16x32_bf16 v[96:99], v[152:155], v[184:187], v[96:99]
	s_setprio 0
	s_barrier
	ds_read_b128 v[188:191], v137
	ds_read_b128 v[192:195], v137 offset:1024
	ds_read_b128 v[202:205], v137 offset:2048
	ds_read_b128 v[206:209], v137 offset:3072
	s_mov_b32 m0, s66
	s_add_u32 s98, s62, s90
	s_addc_u32 s99, s63, s91
	global_load_lds_dwordx4 v128, s[98:99]
	s_mov_b32 m0, s64
	s_nop 0
	global_load_lds_dwordx4 v130, s[98:99]
	s_barrier
	s_waitcnt lgkmcnt(0)
	s_setprio 1
	s_waitcnt lgkmcnt(0)
	v_mfma_f32_16x16x32_bf16 v[92:95], v[188:191], v[156:159], v[92:95]
	v_mfma_f32_16x16x32_bf16 v[88:91], v[202:205], v[156:159], v[88:91]
	v_mfma_f32_16x16x32_bf16 v[84:87], v[188:191], v[164:167], v[84:87]
	v_mfma_f32_16x16x32_bf16 v[80:83], v[202:205], v[164:167], v[80:83]
	v_mfma_f32_16x16x32_bf16 v[76:79], v[188:191], v[172:175], v[76:79]
	v_mfma_f32_16x16x32_bf16 v[72:75], v[202:205], v[172:175], v[72:75]
	v_mfma_f32_16x16x32_bf16 v[68:71], v[188:191], v[180:183], v[68:71]
	v_mfma_f32_16x16x32_bf16 v[64:67], v[202:205], v[180:183], v[64:67]
	v_mfma_f32_16x16x32_bf16 v[92:95], v[192:195], v[160:163], v[92:95]
	v_mfma_f32_16x16x32_bf16 v[88:91], v[206:209], v[160:163], v[88:91]
	v_mfma_f32_16x16x32_bf16 v[84:87], v[192:195], v[168:171], v[84:87]
	v_mfma_f32_16x16x32_bf16 v[80:83], v[206:209], v[168:171], v[80:83]
	v_mfma_f32_16x16x32_bf16 v[76:79], v[192:195], v[176:179], v[76:79]
	v_mfma_f32_16x16x32_bf16 v[72:75], v[206:209], v[176:179], v[72:75]
	v_mfma_f32_16x16x32_bf16 v[68:71], v[192:195], v[184:187], v[68:71]
	v_mfma_f32_16x16x32_bf16 v[64:67], v[206:209], v[184:187], v[64:67]
	s_setprio 0
	v_mov_b32_e32 v210, v130
	s_barrier
	v_mov_b32_e32 v211, v197
	s_mov_b32 m0, s65
	s_add_u32 s98, s28, s92
	s_addc_u32 s99, s29, s93
	global_load_lds_dwordx4 v128, s[98:99]
	s_mov_b32 m0, s67
	s_nop 0
	global_load_lds_dwordx4 v130, s[98:99]
	s_waitcnt vmcnt(4)
	s_barrier
	v_mov_b32_e32 v196, v128
	s_mov_b32 m0, s33
	s_add_u32 s98, s62, s96
	s_addc_u32 s99, s63, s97
	global_load_lds_dwordx4 v128, s[98:99]
	s_mov_b32 m0, s73
	s_nop 0
	global_load_lds_dwordx4 v130, s[98:99]
	s_barrier
	s_add_i32 s38, s38, 2
	s_add_u32 s60, s60, 0x100
	s_addc_u32 s61, s61, 0
	s_cmp_lt_u32 s38, 28
	s_cbranch_scc1 .Lh1_loop
	ds_read_b128 v[140:143], v129
	ds_read_b128 v[144:147], v129 offset:1024
	ds_read_b128 v[148:151], v129 offset:2048
	ds_read_b128 v[152:155], v129 offset:3072
	ds_read_b128 v[156:159], v136
	ds_read_b128 v[160:163], v136 offset:1024
	ds_read_b128 v[164:167], v135
	ds_read_b128 v[168:171], v135 offset:1024
	ds_read_b128 v[172:175], v134
	ds_read_b128 v[176:179], v134 offset:1024
	ds_read_b128 v[180:183], v133
	ds_read_b128 v[184:187], v133 offset:1024
	v_mov_b32_e32 v129, v197
	v_lshl_add_u64 v[128:129], s[58:59], 0, v[128:129]
	s_mov_b64 s[28:29], 0xf80
	s_mov_b32 m0, s40
	v_lshl_add_u64 v[128:129], v[128:129], 0, s[28:29]
	v_mov_b32_e32 v131, v197
	v_lshl_add_u64 v[128:129], s[58:59], 0, v[130:131]
	v_lshl_add_u64 v[128:129], v[128:129], 0, s[28:29]
	s_mov_b32 m0, s39
	s_nop 0
	s_barrier
	s_waitcnt lgkmcnt(0)
	s_setprio 1
	s_waitcnt lgkmcnt(0)
	v_mfma_f32_16x16x32_bf16 v[124:127], v[140:143], v[156:159], v[124:127]
	v_mfma_f32_16x16x32_bf16 v[120:123], v[148:151], v[156:159], v[120:123]
	v_mfma_f32_16x16x32_bf16 v[116:119], v[140:143], v[164:167], v[116:119]
	v_mfma_f32_16x16x32_bf16 v[112:115], v[148:151], v[164:167], v[112:115]
	v_mfma_f32_16x16x32_bf16 v[108:111], v[140:143], v[172:175], v[108:111]
	v_mfma_f32_16x16x32_bf16 v[100:103], v[140:143], v[180:183], v[100:103]
	v_mfma_f32_16x16x32_bf16 v[96:99], v[148:151], v[180:183], v[96:99]
	v_mfma_f32_16x16x32_bf16 v[124:127], v[144:147], v[160:163], v[124:127]
	v_mfma_f32_16x16x32_bf16 v[120:123], v[152:155], v[160:163], v[120:123]
	v_mfma_f32_16x16x32_bf16 v[116:119], v[144:147], v[168:171], v[116:119]
	v_mfma_f32_16x16x32_bf16 v[112:115], v[152:155], v[168:171], v[112:115]
	v_mfma_f32_16x16x32_bf16 v[108:111], v[144:147], v[176:179], v[108:111]
	v_mfma_f32_16x16x32_bf16 v[104:107], v[148:151], v[172:175], v[104:107]
	v_mfma_f32_16x16x32_bf16 v[100:103], v[144:147], v[184:187], v[100:103]
	v_mfma_f32_16x16x32_bf16 v[96:99], v[152:155], v[184:187], v[96:99]
	v_mfma_f32_16x16x32_bf16 v[128:131], v[152:155], v[176:179], v[104:107]
	s_setprio 0
	s_barrier
	s_nop 2
	ds_read_b128 v[104:107], v139
	ds_read_b128 v[188:191], v139 offset:1024
	ds_read_b128 v[192:195], v139 offset:2048
	ds_read_b128 v[202:205], v139 offset:3072
	s_barrier
	s_waitcnt lgkmcnt(0)
	s_setprio 1
	s_waitcnt lgkmcnt(0)
	v_mfma_f32_16x16x32_bf16 v[92:95], v[104:107], v[156:159], v[92:95]
	v_mfma_f32_16x16x32_bf16 v[84:87], v[104:107], v[164:167], v[84:87]
	v_mfma_f32_16x16x32_bf16 v[76:79], v[104:107], v[172:175], v[76:79]
	v_mfma_f32_16x16x32_bf16 v[68:71], v[104:107], v[180:183], v[68:71]
	v_mfma_f32_16x16x32_bf16 v[64:67], v[192:195], v[180:183], v[64:67]
	v_mfma_f32_16x16x32_bf16 v[92:95], v[188:191], v[160:163], v[92:95]
	v_mfma_f32_16x16x32_bf16 v[88:91], v[192:195], v[156:159], v[88:91]
	v_mfma_f32_16x16x32_bf16 v[84:87], v[188:191], v[168:171], v[84:87]
	v_mfma_f32_16x16x32_bf16 v[80:83], v[192:195], v[164:167], v[80:83]
	v_mfma_f32_16x16x32_bf16 v[76:79], v[188:191], v[176:179], v[76:79]
	v_mfma_f32_16x16x32_bf16 v[72:75], v[192:195], v[172:175], v[72:75]
	v_mfma_f32_16x16x32_bf16 v[68:71], v[188:191], v[184:187], v[68:71]
	v_mfma_f32_16x16x32_bf16 v[64:67], v[202:205], v[184:187], v[64:67]
	v_mfma_f32_16x16x32_bf16 v[156:159], v[202:205], v[160:163], v[88:91]
	v_mfma_f32_16x16x32_bf16 v[160:163], v[202:205], v[168:171], v[80:83]
	v_mfma_f32_16x16x32_bf16 v[164:167], v[202:205], v[176:179], v[72:75]
	s_setprio 0
	s_barrier
	s_nop 0
	s_waitcnt vmcnt(2)
	s_barrier
	s_waitcnt lgkmcnt(0)
	s_setprio 1
	s_waitcnt lgkmcnt(0)
	s_setprio 0
	s_setprio 1
	s_setprio 0
	s_barrier
	ds_read_b128 v[16:19], v138
	ds_read_b128 v[180:183], v138 offset:1024
	ds_read_b128 v[184:187], v138 offset:2048
	ds_read_b128 v[188:191], v138 offset:3072
	ds_read_b128 v[0:3], v136 offset:32768
	ds_read_b128 v[4:7], v136 offset:33792
	ds_read_b128 v[8:11], v135 offset:32768
	ds_read_b128 v[12:15], v135 offset:33792
	ds_read_b128 v[44:47], v134 offset:32768
	ds_read_b128 v[192:195], v134 offset:33792
	ds_read_b128 v[202:205], v133 offset:32768
	ds_read_b128 v[218:221], v133 offset:33792
	s_waitcnt vmcnt(0)
	s_barrier
	s_waitcnt lgkmcnt(0)
	s_setprio 1
	s_waitcnt lgkmcnt(0)
	v_mfma_f32_16x16x32_bf16 v[28:31], v[16:19], v[0:3], v[124:127]
	v_mfma_f32_16x16x32_bf16 v[52:55], v[180:183], v[4:7], v[28:31]
	v_mfma_f32_16x16x32_bf16 v[28:31], v[184:187], v[0:3], v[120:123]
	v_mfma_f32_16x16x32_bf16 v[104:107], v[188:191], v[4:7], v[28:31]
	v_mfma_f32_16x16x32_bf16 v[28:31], v[16:19], v[8:11], v[116:119]
	v_mfma_f32_16x16x32_bf16 v[72:75], v[180:183], v[12:15], v[28:31]
	v_mfma_f32_16x16x32_bf16 v[28:31], v[184:187], v[8:11], v[112:115]
	v_mfma_f32_16x16x32_bf16 v[116:119], v[188:191], v[12:15], v[28:31]
	v_mfma_f32_16x16x32_bf16 v[28:31], v[16:19], v[44:47], v[108:111]
	v_mfma_f32_16x16x32_bf16 v[80:83], v[180:183], v[192:195], v[28:31]
	v_mfma_f32_16x16x32_bf16 v[28:31], v[184:187], v[44:47], v[128:131]
	v_mfma_f32_16x16x32_bf16 v[108:111], v[188:191], v[192:195], v[28:31]
	v_mfma_f32_16x16x32_bf16 v[28:31], v[16:19], v[202:205], v[100:103]
	v_mfma_f32_16x16x32_bf16 v[88:91], v[180:183], v[218:221], v[28:31]
	v_mfma_f32_16x16x32_bf16 v[28:31], v[184:187], v[202:205], v[96:99]
	v_mfma_f32_16x16x32_bf16 v[96:99], v[188:191], v[218:221], v[28:31]
	s_setprio 0
	s_barrier
	ds_read_b128 v[128:131], v137
	ds_read_b128 v[222:225], v137 offset:1024
	ds_read_b128 v[228:231], v137 offset:2048
	ds_read_b128 v[232:235], v137 offset:3072
	s_waitcnt vmcnt(0)
	s_barrier
	s_waitcnt lgkmcnt(0)
	s_setprio 1
	s_waitcnt lgkmcnt(0)
	v_mfma_f32_16x16x32_bf16 v[28:31], v[128:131], v[0:3], v[92:95]
	v_mfma_f32_16x16x32_bf16 v[0:3], v[228:231], v[0:3], v[156:159]
	v_mfma_f32_16x16x32_bf16 v[28:31], v[222:225], v[4:7], v[28:31]
	v_mfma_f32_16x16x32_bf16 v[0:3], v[232:235], v[4:7], v[0:3]
	v_mfma_f32_16x16x32_bf16 v[4:7], v[128:131], v[8:11], v[84:87]
	v_mfma_f32_16x16x32_bf16 v[36:39], v[222:225], v[12:15], v[4:7]
	v_mfma_f32_16x16x32_bf16 v[4:7], v[228:231], v[8:11], v[160:163]
	v_mfma_f32_16x16x32_bf16 v[4:7], v[232:235], v[12:15], v[4:7]
	v_mfma_f32_16x16x32_bf16 v[8:11], v[128:131], v[44:47], v[76:79]
	v_mfma_f32_16x16x32_bf16 v[12:15], v[128:131], v[202:205], v[68:71]
	v_mfma_f32_16x16x32_bf16 v[40:43], v[222:225], v[192:195], v[8:11]
	v_mfma_f32_16x16x32_bf16 v[8:11], v[228:231], v[44:47], v[164:167]
	v_mfma_f32_16x16x32_bf16 v[44:47], v[222:225], v[218:221], v[12:15]
	v_mfma_f32_16x16x32_bf16 v[12:15], v[228:231], v[202:205], v[64:67]
	v_mfma_f32_16x16x32_bf16 v[8:11], v[232:235], v[192:195], v[8:11]
	v_mfma_f32_16x16x32_bf16 v[12:15], v[232:235], v[218:221], v[12:15]
	s_setprio 0
	s_barrier
	s_barrier
	s_waitcnt lgkmcnt(0)
	s_setprio 1
	s_waitcnt lgkmcnt(0)
	s_setprio 0
	s_setprio 1
	s_setprio 0
	s_movk_i32 s9, 0x100
	v_cmp_gt_u32_e32 vcc, s9, v132
	s_barrier
	s_and_saveexec_b64 s[28:29], vcc
	s_cbranch_execz .Lh1_epi
	s_barrier

.LBB0_255:
	ds_read_b128 v[140:143], v129
	ds_read_b128 v[144:147], v129 offset:1024
	ds_read_b128 v[148:151], v129 offset:2048
	ds_read_b128 v[152:155], v129 offset:3072
	s_add_u32 s28, s60, s56
	s_addc_u32 s29, s61, s57
	ds_read_b128 v[156:159], v136
	ds_read_b128 v[160:163], v136 offset:1024
	ds_read_b128 v[164:167], v135
	ds_read_b128 v[168:171], v135 offset:1024
	ds_read_b128 v[172:175], v134
	ds_read_b128 v[176:179], v134 offset:1024
	ds_read_b128 v[180:183], v133
	ds_read_b128 v[184:187], v133 offset:1024
	s_add_i32 s40, s53, 0xc000
	s_mov_b32 m0, s40
	s_add_i32 s39, s53, 0xe000
	s_add_u32 s98, s28, s44
	s_addc_u32 s99, s29, s45
	global_load_lds_dwordx4 v128, s[98:99]
	s_mov_b32 m0, s39
	s_nop 0
	global_load_lds_dwordx4 v130, s[98:99]
	s_waitcnt lgkmcnt(8)
	s_barrier
	s_waitcnt lgkmcnt(0)
	s_setprio 1
	s_waitcnt lgkmcnt(0)
	v_mfma_f32_16x16x32_bf16 v[124:127], v[140:143], v[156:159], v[124:127]
	v_mfma_f32_16x16x32_bf16 v[120:123], v[148:151], v[156:159], v[120:123]
	v_mfma_f32_16x16x32_bf16 v[116:119], v[140:143], v[164:167], v[116:119]
	v_mfma_f32_16x16x32_bf16 v[112:115], v[148:151], v[164:167], v[112:115]
	v_mfma_f32_16x16x32_bf16 v[108:111], v[140:143], v[172:175], v[108:111]
	v_mfma_f32_16x16x32_bf16 v[104:107], v[148:151], v[172:175], v[104:107]
	v_mfma_f32_16x16x32_bf16 v[100:103], v[140:143], v[180:183], v[100:103]
	v_mfma_f32_16x16x32_bf16 v[96:99], v[148:151], v[180:183], v[96:99]
	v_mfma_f32_16x16x32_bf16 v[124:127], v[144:147], v[160:163], v[124:127]
	v_mfma_f32_16x16x32_bf16 v[120:123], v[152:155], v[160:163], v[120:123]
	v_mfma_f32_16x16x32_bf16 v[116:119], v[144:147], v[168:171], v[116:119]
	v_mfma_f32_16x16x32_bf16 v[112:115], v[152:155], v[168:171], v[112:115]
	v_mfma_f32_16x16x32_bf16 v[108:111], v[144:147], v[176:179], v[108:111]
	v_mfma_f32_16x16x32_bf16 v[104:107], v[152:155], v[176:179], v[104:107]
	v_mfma_f32_16x16x32_bf16 v[100:103], v[144:147], v[184:187], v[100:103]
	v_mfma_f32_16x16x32_bf16 v[96:99], v[152:155], v[184:187], v[96:99]
	s_setprio 0
	s_barrier
	s_add_u32 s62, s60, s36
	s_addc_u32 s63, s61, s37
	ds_read_b128 v[188:191], v139
	ds_read_b128 v[192:195], v139 offset:1024
	ds_read_b128 v[202:205], v139 offset:2048
	ds_read_b128 v[206:209], v139 offset:3072
	s_mov_b32 m0, s68
	s_add_u32 s98, s62, s46
	s_addc_u32 s99, s63, s47
	global_load_lds_dwordx4 v128, s[98:99]
	s_mov_b32 m0, s69
	s_nop 0
	global_load_lds_dwordx4 v130, s[98:99]
	s_barrier
	s_waitcnt lgkmcnt(0)
	s_setprio 1
	s_waitcnt lgkmcnt(0)
	v_mfma_f32_16x16x32_bf16 v[92:95], v[188:191], v[156:159], v[92:95]
	v_mfma_f32_16x16x32_bf16 v[88:91], v[202:205], v[156:159], v[88:91]
	v_mfma_f32_16x16x32_bf16 v[84:87], v[188:191], v[164:167], v[84:87]
	v_mfma_f32_16x16x32_bf16 v[80:83], v[202:205], v[164:167], v[80:83]
	v_mfma_f32_16x16x32_bf16 v[76:79], v[188:191], v[172:175], v[76:79]
	v_mfma_f32_16x16x32_bf16 v[72:75], v[202:205], v[172:175], v[72:75]
	v_mfma_f32_16x16x32_bf16 v[68:71], v[188:191], v[180:183], v[68:71]
	v_mfma_f32_16x16x32_bf16 v[64:67], v[202:205], v[180:183], v[64:67]
	v_mfma_f32_16x16x32_bf16 v[92:95], v[192:195], v[160:163], v[92:95]
	v_mfma_f32_16x16x32_bf16 v[88:91], v[206:209], v[160:163], v[88:91]
	v_mfma_f32_16x16x32_bf16 v[84:87], v[192:195], v[168:171], v[84:87]
	v_mfma_f32_16x16x32_bf16 v[80:83], v[206:209], v[168:171], v[80:83]
	v_mfma_f32_16x16x32_bf16 v[76:79], v[192:195], v[176:179], v[76:79]
	v_mfma_f32_16x16x32_bf16 v[72:75], v[206:209], v[176:179], v[72:75]
	v_mfma_f32_16x16x32_bf16 v[68:71], v[192:195], v[184:187], v[68:71]
	v_mfma_f32_16x16x32_bf16 v[64:67], v[206:209], v[184:187], v[64:67]
	s_setprio 0
	s_barrier
	ds_read_b128 v[156:159], v136 offset:16384
	ds_read_b128 v[160:163], v136 offset:17408
	ds_read_b128 v[164:167], v135 offset:16384
	ds_read_b128 v[168:171], v135 offset:17408
	ds_read_b128 v[172:175], v134 offset:16384
	ds_read_b128 v[176:179], v134 offset:17408
	ds_read_b128 v[180:183], v133 offset:16384
	ds_read_b128 v[184:187], v133 offset:17408
	s_mov_b32 m0, s53
	s_add_u32 s98, s28, s48
	s_addc_u32 s99, s29, s49
	global_load_lds_dwordx4 v128, s[98:99]
	s_mov_b32 m0, s11
	s_nop 0
	global_load_lds_dwordx4 v130, s[98:99]
	s_barrier
	s_waitcnt lgkmcnt(0)
	s_setprio 1
	s_waitcnt lgkmcnt(0)
	v_mfma_f32_16x16x32_bf16 v[60:63], v[140:143], v[156:159], v[60:63]
	v_mfma_f32_16x16x32_bf16 v[56:59], v[148:151], v[156:159], v[56:59]
	v_mfma_f32_16x16x32_bf16 v[52:55], v[140:143], v[164:167], v[52:55]
	v_mfma_f32_16x16x32_bf16 v[48:51], v[148:151], v[164:167], v[48:51]
	v_mfma_f32_16x16x32_bf16 v[44:47], v[140:143], v[172:175], v[44:47]
	v_mfma_f32_16x16x32_bf16 v[40:43], v[148:151], v[172:175], v[40:43]
	v_mfma_f32_16x16x32_bf16 v[36:39], v[140:143], v[180:183], v[36:39]
	v_mfma_f32_16x16x32_bf16 v[32:35], v[148:151], v[180:183], v[32:35]
	v_mfma_f32_16x16x32_bf16 v[60:63], v[144:147], v[160:163], v[60:63]
	v_mfma_f32_16x16x32_bf16 v[56:59], v[152:155], v[160:163], v[56:59]
	v_mfma_f32_16x16x32_bf16 v[52:55], v[144:147], v[168:171], v[52:55]
	v_mfma_f32_16x16x32_bf16 v[48:51], v[152:155], v[168:171], v[48:51]
	v_mfma_f32_16x16x32_bf16 v[44:47], v[144:147], v[176:179], v[44:47]
	v_mfma_f32_16x16x32_bf16 v[40:43], v[152:155], v[176:179], v[40:43]
	v_mfma_f32_16x16x32_bf16 v[36:39], v[144:147], v[184:187], v[36:39]
	v_mfma_f32_16x16x32_bf16 v[32:35], v[152:155], v[184:187], v[32:35]
	s_setprio 0
	s_barrier
	s_mov_b32 m0, s9
	s_add_u32 s98, s62, s50
	s_addc_u32 s99, s63, s51
	global_load_lds_dwordx4 v128, s[98:99]
	s_mov_b32 m0, s70
	s_nop 0
	global_load_lds_dwordx4 v130, s[98:99]
	s_waitcnt vmcnt(6)
	s_barrier
	s_setprio 1
	v_mfma_f32_16x16x32_bf16 v[28:31], v[188:191], v[156:159], v[28:31]
	v_mfma_f32_16x16x32_bf16 v[24:27], v[202:205], v[156:159], v[24:27]
	v_mfma_f32_16x16x32_bf16 v[20:23], v[188:191], v[164:167], v[20:23]
	v_mfma_f32_16x16x32_bf16 v[16:19], v[202:205], v[164:167], v[16:19]
	v_mfma_f32_16x16x32_bf16 v[12:15], v[188:191], v[172:175], v[12:15]
	v_mfma_f32_16x16x32_bf16 v[8:11], v[202:205], v[172:175], v[8:11]
	v_mfma_f32_16x16x32_bf16 v[4:7], v[188:191], v[180:183], v[4:7]
	v_mfma_f32_16x16x32_bf16 v[0:3], v[202:205], v[180:183], v[0:3]
	v_mfma_f32_16x16x32_bf16 v[28:31], v[192:195], v[160:163], v[28:31]
	v_mfma_f32_16x16x32_bf16 v[24:27], v[206:209], v[160:163], v[24:27]
	v_mfma_f32_16x16x32_bf16 v[20:23], v[192:195], v[168:171], v[20:23]
	v_mfma_f32_16x16x32_bf16 v[16:19], v[206:209], v[168:171], v[16:19]
	v_mfma_f32_16x16x32_bf16 v[12:15], v[192:195], v[176:179], v[12:15]
	v_mfma_f32_16x16x32_bf16 v[8:11], v[206:209], v[176:179], v[8:11]
	v_mfma_f32_16x16x32_bf16 v[4:7], v[192:195], v[184:187], v[4:7]
	v_mfma_f32_16x16x32_bf16 v[0:3], v[206:209], v[184:187], v[0:3]
	s_setprio 0
	s_barrier
	ds_read_b128 v[140:143], v138
	ds_read_b128 v[144:147], v138 offset:1024
	ds_read_b128 v[148:151], v138 offset:2048
	ds_read_b128 v[152:155], v138 offset:3072
	ds_read_b128 v[156:159], v136 offset:32768
	ds_read_b128 v[160:163], v136 offset:33792
	ds_read_b128 v[164:167], v135 offset:32768
	ds_read_b128 v[168:171], v135 offset:33792
	ds_read_b128 v[172:175], v134 offset:32768
	ds_read_b128 v[176:179], v134 offset:33792
	ds_read_b128 v[180:183], v133 offset:32768
	ds_read_b128 v[184:187], v133 offset:33792
	s_mov_b32 m0, s71
	s_add_u32 s98, s28, s74
	s_addc_u32 s99, s29, s75
	global_load_lds_dwordx4 v128, s[98:99]
	s_mov_b32 m0, s72
	s_nop 0
	global_load_lds_dwordx4 v130, s[98:99]
	s_waitcnt lgkmcnt(8)
	s_barrier
	s_waitcnt lgkmcnt(0)
	s_setprio 1
	s_waitcnt lgkmcnt(0)
	v_mfma_f32_16x16x32_bf16 v[124:127], v[140:143], v[156:159], v[124:127]
	v_mfma_f32_16x16x32_bf16 v[120:123], v[148:151], v[156:159], v[120:123]
	v_mfma_f32_16x16x32_bf16 v[116:119], v[140:143], v[164:167], v[116:119]
	v_mfma_f32_16x16x32_bf16 v[112:115], v[148:151], v[164:167], v[112:115]
	v_mfma_f32_16x16x32_bf16 v[108:111], v[140:143], v[172:175], v[108:111]
	v_mfma_f32_16x16x32_bf16 v[104:107], v[148:151], v[172:175], v[104:107]
	v_mfma_f32_16x16x32_bf16 v[100:103], v[140:143], v[180:183], v[100:103]
	v_mfma_f32_16x16x32_bf16 v[96:99], v[148:151], v[180:183], v[96:99]
	v_mfma_f32_16x16x32_bf16 v[124:127], v[144:147], v[160:163], v[124:127]
	v_mfma_f32_16x16x32_bf16 v[120:123], v[152:155], v[160:163], v[120:123]
	v_mfma_f32_16x16x32_bf16 v[116:119], v[144:147], v[168:171], v[116:119]
	v_mfma_f32_16x16x32_bf16 v[112:115], v[152:155], v[168:171], v[112:115]
	v_mfma_f32_16x16x32_bf16 v[108:111], v[144:147], v[176:179], v[108:111]
	v_mfma_f32_16x16x32_bf16 v[104:107], v[152:155], v[176:179], v[104:107]
	v_mfma_f32_16x16x32_bf16 v[100:103], v[144:147], v[184:187], v[100:103]
	v_mfma_f32_16x16x32_bf16 v[96:99], v[152:155], v[184:187], v[96:99]
	s_setprio 0
	s_barrier
	ds_read_b128 v[188:191], v137
	ds_read_b128 v[192:195], v137 offset:1024
	ds_read_b128 v[202:205], v137 offset:2048
	ds_read_b128 v[206:209], v137 offset:3072
	s_mov_b32 m0, s66
	s_add_u32 s98, s62, s90
	s_addc_u32 s99, s63, s91
	global_load_lds_dwordx4 v128, s[98:99]
	s_mov_b32 m0, s64
	s_nop 0
	global_load_lds_dwordx4 v130, s[98:99]
	s_barrier
	s_waitcnt lgkmcnt(0)
	s_setprio 1
	s_waitcnt lgkmcnt(0)
	v_mfma_f32_16x16x32_bf16 v[92:95], v[188:191], v[156:159], v[92:95]
	v_mfma_f32_16x16x32_bf16 v[88:91], v[202:205], v[156:159], v[88:91]
	v_mfma_f32_16x16x32_bf16 v[84:87], v[188:191], v[164:167], v[84:87]
	v_mfma_f32_16x16x32_bf16 v[80:83], v[202:205], v[164:167], v[80:83]
	v_mfma_f32_16x16x32_bf16 v[76:79], v[188:191], v[172:175], v[76:79]
	v_mfma_f32_16x16x32_bf16 v[72:75], v[202:205], v[172:175], v[72:75]
	v_mfma_f32_16x16x32_bf16 v[68:71], v[188:191], v[180:183], v[68:71]
	v_mfma_f32_16x16x32_bf16 v[64:67], v[202:205], v[180:183], v[64:67]
	v_mfma_f32_16x16x32_bf16 v[92:95], v[192:195], v[160:163], v[92:95]
	v_mfma_f32_16x16x32_bf16 v[88:91], v[206:209], v[160:163], v[88:91]
	v_mfma_f32_16x16x32_bf16 v[84:87], v[192:195], v[168:171], v[84:87]
	v_mfma_f32_16x16x32_bf16 v[80:83], v[206:209], v[168:171], v[80:83]
	v_mfma_f32_16x16x32_bf16 v[76:79], v[192:195], v[176:179], v[76:79]
	v_mfma_f32_16x16x32_bf16 v[72:75], v[206:209], v[176:179], v[72:75]
	v_mfma_f32_16x16x32_bf16 v[68:71], v[192:195], v[184:187], v[68:71]
	v_mfma_f32_16x16x32_bf16 v[64:67], v[206:209], v[184:187], v[64:67]
	s_setprio 0
	v_mov_b32_e32 v210, v130
	s_barrier
	ds_read_b128 v[156:159], v136 offset:49152
	ds_read_b128 v[160:163], v136 offset:50176
	ds_read_b128 v[164:167], v135 offset:49152
	ds_read_b128 v[168:171], v135 offset:50176
	ds_read_b128 v[172:175], v134 offset:49152
	ds_read_b128 v[176:179], v134 offset:50176
	ds_read_b128 v[180:183], v133 offset:49152
	ds_read_b128 v[184:187], v133 offset:50176
	v_mov_b32_e32 v211, v197
	s_mov_b32 m0, s65
	s_add_u32 s98, s28, s92
	s_addc_u32 s99, s29, s93
	global_load_lds_dwordx4 v128, s[98:99]
	s_mov_b32 m0, s67
	s_nop 0
	global_load_lds_dwordx4 v130, s[98:99]
	s_barrier
	s_waitcnt lgkmcnt(0)
	s_setprio 1
	s_waitcnt lgkmcnt(0)
	v_mfma_f32_16x16x32_bf16 v[60:63], v[140:143], v[156:159], v[60:63]
	v_mfma_f32_16x16x32_bf16 v[56:59], v[148:151], v[156:159], v[56:59]
	v_mfma_f32_16x16x32_bf16 v[52:55], v[140:143], v[164:167], v[52:55]
	v_mfma_f32_16x16x32_bf16 v[48:51], v[148:151], v[164:167], v[48:51]
	v_mfma_f32_16x16x32_bf16 v[44:47], v[140:143], v[172:175], v[44:47]
	v_mfma_f32_16x16x32_bf16 v[40:43], v[148:151], v[172:175], v[40:43]
	v_mfma_f32_16x16x32_bf16 v[36:39], v[140:143], v[180:183], v[36:39]
	v_mfma_f32_16x16x32_bf16 v[32:35], v[148:151], v[180:183], v[32:35]
	v_mfma_f32_16x16x32_bf16 v[60:63], v[144:147], v[160:163], v[60:63]
	v_mfma_f32_16x16x32_bf16 v[56:59], v[152:155], v[160:163], v[56:59]
	v_mfma_f32_16x16x32_bf16 v[52:55], v[144:147], v[168:171], v[52:55]
	v_mfma_f32_16x16x32_bf16 v[48:51], v[152:155], v[168:171], v[48:51]
	v_mfma_f32_16x16x32_bf16 v[44:47], v[144:147], v[176:179], v[44:47]
	v_mfma_f32_16x16x32_bf16 v[40:43], v[152:155], v[176:179], v[40:43]
	v_mfma_f32_16x16x32_bf16 v[36:39], v[144:147], v[184:187], v[36:39]
	v_mfma_f32_16x16x32_bf16 v[32:35], v[152:155], v[184:187], v[32:35]
	s_setprio 0
	s_barrier
	v_mov_b32_e32 v196, v128
	s_mov_b32 m0, s33
	s_add_u32 s98, s62, s96
	s_addc_u32 s99, s63, s97
	global_load_lds_dwordx4 v128, s[98:99]
	s_mov_b32 m0, s73
	s_nop 0
	global_load_lds_dwordx4 v130, s[98:99]
	s_waitcnt vmcnt(6)
	s_barrier
	s_setprio 1
	v_mfma_f32_16x16x32_bf16 v[28:31], v[188:191], v[156:159], v[28:31]
	v_mfma_f32_16x16x32_bf16 v[24:27], v[202:205], v[156:159], v[24:27]
	v_mfma_f32_16x16x32_bf16 v[20:23], v[188:191], v[164:167], v[20:23]
	v_mfma_f32_16x16x32_bf16 v[16:19], v[202:205], v[164:167], v[16:19]
	v_mfma_f32_16x16x32_bf16 v[12:15], v[188:191], v[172:175], v[12:15]
	v_mfma_f32_16x16x32_bf16 v[8:11], v[202:205], v[172:175], v[8:11]
	v_mfma_f32_16x16x32_bf16 v[4:7], v[188:191], v[180:183], v[4:7]
	v_mfma_f32_16x16x32_bf16 v[0:3], v[202:205], v[180:183], v[0:3]
	v_mfma_f32_16x16x32_bf16 v[28:31], v[192:195], v[160:163], v[28:31]
	v_mfma_f32_16x16x32_bf16 v[24:27], v[206:209], v[160:163], v[24:27]
	v_mfma_f32_16x16x32_bf16 v[20:23], v[192:195], v[168:171], v[20:23]
	v_mfma_f32_16x16x32_bf16 v[16:19], v[206:209], v[168:171], v[16:19]
	v_mfma_f32_16x16x32_bf16 v[12:15], v[192:195], v[176:179], v[12:15]
	v_mfma_f32_16x16x32_bf16 v[8:11], v[206:209], v[176:179], v[8:11]
	v_mfma_f32_16x16x32_bf16 v[4:7], v[192:195], v[184:187], v[4:7]
	v_mfma_f32_16x16x32_bf16 v[0:3], v[206:209], v[184:187], v[0:3]
	s_setprio 0
	s_add_i32 s38, s38, 2
	s_add_u32 s60, s60, 0x100
	s_addc_u32 s61, s61, 0
	s_cmp_lt_u32 s38, 28
	s_barrier
	s_cbranch_scc1 .LBB0_255
	ds_read_b128 v[140:143], v129
	ds_read_b128 v[144:147], v129 offset:1024
	ds_read_b128 v[148:151], v129 offset:2048
	ds_read_b128 v[152:155], v129 offset:3072
	ds_read_b128 v[156:159], v136
	ds_read_b128 v[160:163], v136 offset:1024
	ds_read_b128 v[164:167], v135
	ds_read_b128 v[168:171], v135 offset:1024
	ds_read_b128 v[172:175], v134
	ds_read_b128 v[176:179], v134 offset:1024
	ds_read_b128 v[180:183], v133
	ds_read_b128 v[184:187], v133 offset:1024
	v_mov_b32_e32 v129, v197
	v_lshl_add_u64 v[128:129], s[58:59], 0, v[128:129]
	s_mov_b64 s[28:29], 0xf80
	s_mov_b32 m0, s40
	v_lshl_add_u64 v[128:129], v[128:129], 0, s[28:29]
	v_mov_b32_e32 v131, v197
	global_load_lds_dwordx4 v[128:129], off
	v_lshl_add_u64 v[128:129], s[58:59], 0, v[130:131]
	v_lshl_add_u64 v[128:129], v[128:129], 0, s[28:29]
	s_mov_b32 m0, s39
	s_nop 0
	global_load_lds_dwordx4 v[128:129], off
	s_barrier
	s_waitcnt lgkmcnt(0)
	s_setprio 1
	s_waitcnt lgkmcnt(0)
	v_mfma_f32_16x16x32_bf16 v[124:127], v[140:143], v[156:159], v[124:127]
	v_mfma_f32_16x16x32_bf16 v[120:123], v[148:151], v[156:159], v[120:123]
	v_mfma_f32_16x16x32_bf16 v[116:119], v[140:143], v[164:167], v[116:119]
	v_mfma_f32_16x16x32_bf16 v[112:115], v[148:151], v[164:167], v[112:115]
	v_mfma_f32_16x16x32_bf16 v[108:111], v[140:143], v[172:175], v[108:111]
	v_mfma_f32_16x16x32_bf16 v[100:103], v[140:143], v[180:183], v[100:103]
	v_mfma_f32_16x16x32_bf16 v[96:99], v[148:151], v[180:183], v[96:99]
	v_mfma_f32_16x16x32_bf16 v[124:127], v[144:147], v[160:163], v[124:127]
	v_mfma_f32_16x16x32_bf16 v[120:123], v[152:155], v[160:163], v[120:123]
	v_mfma_f32_16x16x32_bf16 v[116:119], v[144:147], v[168:171], v[116:119]
	v_mfma_f32_16x16x32_bf16 v[112:115], v[152:155], v[168:171], v[112:115]
	v_mfma_f32_16x16x32_bf16 v[108:111], v[144:147], v[176:179], v[108:111]
	v_mfma_f32_16x16x32_bf16 v[104:107], v[148:151], v[172:175], v[104:107]
	v_mfma_f32_16x16x32_bf16 v[100:103], v[144:147], v[184:187], v[100:103]
	v_mfma_f32_16x16x32_bf16 v[96:99], v[152:155], v[184:187], v[96:99]
	v_mfma_f32_16x16x32_bf16 v[128:131], v[152:155], v[176:179], v[104:107]
	s_setprio 0
	s_barrier
	s_nop 2
	ds_read_b128 v[104:107], v139
	ds_read_b128 v[188:191], v139 offset:1024
	ds_read_b128 v[192:195], v139 offset:2048
	ds_read_b128 v[202:205], v139 offset:3072
	s_barrier
	s_waitcnt lgkmcnt(0)
	s_setprio 1
	s_waitcnt lgkmcnt(0)
	v_mfma_f32_16x16x32_bf16 v[92:95], v[104:107], v[156:159], v[92:95]
	v_mfma_f32_16x16x32_bf16 v[84:87], v[104:107], v[164:167], v[84:87]
	v_mfma_f32_16x16x32_bf16 v[76:79], v[104:107], v[172:175], v[76:79]
	v_mfma_f32_16x16x32_bf16 v[68:71], v[104:107], v[180:183], v[68:71]
	v_mfma_f32_16x16x32_bf16 v[64:67], v[192:195], v[180:183], v[64:67]
	v_mfma_f32_16x16x32_bf16 v[92:95], v[188:191], v[160:163], v[92:95]
	v_mfma_f32_16x16x32_bf16 v[88:91], v[192:195], v[156:159], v[88:91]
	v_mfma_f32_16x16x32_bf16 v[84:87], v[188:191], v[168:171], v[84:87]
	v_mfma_f32_16x16x32_bf16 v[80:83], v[192:195], v[164:167], v[80:83]
	v_mfma_f32_16x16x32_bf16 v[76:79], v[188:191], v[176:179], v[76:79]
	v_mfma_f32_16x16x32_bf16 v[72:75], v[192:195], v[172:175], v[72:75]
	v_mfma_f32_16x16x32_bf16 v[68:71], v[188:191], v[184:187], v[68:71]
	v_mfma_f32_16x16x32_bf16 v[64:67], v[202:205], v[184:187], v[64:67]
	v_mfma_f32_16x16x32_bf16 v[156:159], v[202:205], v[160:163], v[88:91]
	v_mfma_f32_16x16x32_bf16 v[160:163], v[202:205], v[168:171], v[80:83]
	v_mfma_f32_16x16x32_bf16 v[164:167], v[202:205], v[176:179], v[72:75]
	s_setprio 0
	s_barrier
	s_nop 0
	ds_read_b128 v[72:75], v136 offset:16384
	ds_read_b128 v[80:83], v136 offset:17408
	ds_read_b128 v[88:91], v135 offset:16384
	ds_read_b128 v[168:171], v135 offset:17408
	ds_read_b128 v[172:175], v134 offset:16384
	ds_read_b128 v[176:179], v134 offset:17408
	ds_read_b128 v[180:183], v133 offset:16384
	ds_read_b128 v[184:187], v133 offset:17408
	s_waitcnt vmcnt(4)
	s_barrier
	s_waitcnt lgkmcnt(0)
	s_setprio 1
	s_waitcnt lgkmcnt(0)
	v_mfma_f32_16x16x32_bf16 v[60:63], v[140:143], v[72:75], v[60:63]
	v_mfma_f32_16x16x32_bf16 v[56:59], v[148:151], v[72:75], v[56:59]
	v_mfma_f32_16x16x32_bf16 v[48:51], v[148:151], v[88:91], v[48:51]
	v_mfma_f32_16x16x32_bf16 v[32:35], v[148:151], v[180:183], v[32:35]
	v_mfma_f32_16x16x32_bf16 v[60:63], v[144:147], v[80:83], v[60:63]
	v_mfma_f32_16x16x32_bf16 v[56:59], v[152:155], v[80:83], v[56:59]
	v_mfma_f32_16x16x32_bf16 v[52:55], v[140:143], v[88:91], v[52:55]
	v_mfma_f32_16x16x32_bf16 v[48:51], v[152:155], v[168:171], v[48:51]
	v_mfma_f32_16x16x32_bf16 v[44:47], v[140:143], v[172:175], v[44:47]
	v_mfma_f32_16x16x32_bf16 v[40:43], v[148:151], v[172:175], v[40:43]
	v_mfma_f32_16x16x32_bf16 v[36:39], v[140:143], v[180:183], v[36:39]
	v_mfma_f32_16x16x32_bf16 v[32:35], v[152:155], v[184:187], v[32:35]
	v_mfma_f32_16x16x32_bf16 v[206:209], v[144:147], v[168:171], v[52:55]
	v_mfma_f32_16x16x32_bf16 v[210:213], v[144:147], v[176:179], v[44:47]
	v_mfma_f32_16x16x32_bf16 v[214:217], v[152:155], v[176:179], v[40:43]
	v_mfma_f32_16x16x32_bf16 v[140:143], v[144:147], v[184:187], v[36:39]
	s_setprio 0
	s_setprio 1
	v_mfma_f32_16x16x32_bf16 v[24:27], v[192:195], v[72:75], v[24:27]
	v_mfma_f32_16x16x32_bf16 v[20:23], v[104:107], v[88:91], v[20:23]
	v_mfma_f32_16x16x32_bf16 v[28:31], v[104:107], v[72:75], v[28:31]
	v_mfma_f32_16x16x32_bf16 v[24:27], v[202:205], v[80:83], v[24:27]
	v_mfma_f32_16x16x32_bf16 v[20:23], v[188:191], v[168:171], v[20:23]
	v_mfma_f32_16x16x32_bf16 v[16:19], v[192:195], v[88:91], v[16:19]
	v_mfma_f32_16x16x32_bf16 v[12:15], v[104:107], v[172:175], v[12:15]
	v_mfma_f32_16x16x32_bf16 v[8:11], v[192:195], v[172:175], v[8:11]
	v_mfma_f32_16x16x32_bf16 v[4:7], v[104:107], v[180:183], v[4:7]
	v_mfma_f32_16x16x32_bf16 v[0:3], v[192:195], v[180:183], v[0:3]
	v_mfma_f32_16x16x32_bf16 v[144:147], v[188:191], v[80:83], v[28:31]
	v_mfma_f32_16x16x32_bf16 v[148:151], v[202:205], v[168:171], v[16:19]
	v_mfma_f32_16x16x32_bf16 v[152:155], v[188:191], v[176:179], v[12:15]
	v_mfma_f32_16x16x32_bf16 v[168:171], v[202:205], v[176:179], v[8:11]
	v_mfma_f32_16x16x32_bf16 v[172:175], v[188:191], v[184:187], v[4:7]
	v_mfma_f32_16x16x32_bf16 v[176:179], v[202:205], v[184:187], v[0:3]
	s_setprio 0
	s_barrier
	ds_read_b128 v[16:19], v138
	ds_read_b128 v[180:183], v138 offset:1024
	ds_read_b128 v[184:187], v138 offset:2048
	ds_read_b128 v[188:191], v138 offset:3072
	ds_read_b128 v[0:3], v136 offset:32768
	ds_read_b128 v[4:7], v136 offset:33792
	ds_read_b128 v[8:11], v135 offset:32768
	ds_read_b128 v[12:15], v135 offset:33792
	ds_read_b128 v[44:47], v134 offset:32768
	ds_read_b128 v[192:195], v134 offset:33792
	ds_read_b128 v[202:205], v133 offset:32768
	ds_read_b128 v[218:221], v133 offset:33792
	s_waitcnt vmcnt(2)
	s_barrier
	s_waitcnt lgkmcnt(0)
	s_setprio 1
	s_waitcnt lgkmcnt(0)
	v_mfma_f32_16x16x32_bf16 v[28:31], v[16:19], v[0:3], v[124:127]
	v_mfma_f32_16x16x32_bf16 v[52:55], v[180:183], v[4:7], v[28:31]
	v_mfma_f32_16x16x32_bf16 v[28:31], v[184:187], v[0:3], v[120:123]
	v_mfma_f32_16x16x32_bf16 v[104:107], v[188:191], v[4:7], v[28:31]
	v_mfma_f32_16x16x32_bf16 v[28:31], v[16:19], v[8:11], v[116:119]
	v_mfma_f32_16x16x32_bf16 v[72:75], v[180:183], v[12:15], v[28:31]
	v_mfma_f32_16x16x32_bf16 v[28:31], v[184:187], v[8:11], v[112:115]
	v_mfma_f32_16x16x32_bf16 v[116:119], v[188:191], v[12:15], v[28:31]
	v_mfma_f32_16x16x32_bf16 v[28:31], v[16:19], v[44:47], v[108:111]
	v_mfma_f32_16x16x32_bf16 v[80:83], v[180:183], v[192:195], v[28:31]
	v_mfma_f32_16x16x32_bf16 v[28:31], v[184:187], v[44:47], v[128:131]
	v_mfma_f32_16x16x32_bf16 v[108:111], v[188:191], v[192:195], v[28:31]
	v_mfma_f32_16x16x32_bf16 v[28:31], v[16:19], v[202:205], v[100:103]
	v_mfma_f32_16x16x32_bf16 v[88:91], v[180:183], v[218:221], v[28:31]
	v_mfma_f32_16x16x32_bf16 v[28:31], v[184:187], v[202:205], v[96:99]
	v_mfma_f32_16x16x32_bf16 v[96:99], v[188:191], v[218:221], v[28:31]
	s_setprio 0
	s_barrier
	ds_read_b128 v[128:131], v137
	ds_read_b128 v[222:225], v137 offset:1024
	ds_read_b128 v[228:231], v137 offset:2048
	ds_read_b128 v[232:235], v137 offset:3072
	s_waitcnt vmcnt(0)
	s_barrier
	s_waitcnt lgkmcnt(0)
	s_setprio 1
	s_waitcnt lgkmcnt(0)
	v_mfma_f32_16x16x32_bf16 v[28:31], v[128:131], v[0:3], v[92:95]
	v_mfma_f32_16x16x32_bf16 v[0:3], v[228:231], v[0:3], v[156:159]
	v_mfma_f32_16x16x32_bf16 v[28:31], v[222:225], v[4:7], v[28:31]
	v_mfma_f32_16x16x32_bf16 v[0:3], v[232:235], v[4:7], v[0:3]
	v_mfma_f32_16x16x32_bf16 v[4:7], v[128:131], v[8:11], v[84:87]
	v_mfma_f32_16x16x32_bf16 v[36:39], v[222:225], v[12:15], v[4:7]
	v_mfma_f32_16x16x32_bf16 v[4:7], v[228:231], v[8:11], v[160:163]
	v_mfma_f32_16x16x32_bf16 v[4:7], v[232:235], v[12:15], v[4:7]
	v_mfma_f32_16x16x32_bf16 v[8:11], v[128:131], v[44:47], v[76:79]
	v_mfma_f32_16x16x32_bf16 v[12:15], v[128:131], v[202:205], v[68:71]
	v_mfma_f32_16x16x32_bf16 v[40:43], v[222:225], v[192:195], v[8:11]
	v_mfma_f32_16x16x32_bf16 v[8:11], v[228:231], v[44:47], v[164:167]
	v_mfma_f32_16x16x32_bf16 v[44:47], v[222:225], v[218:221], v[12:15]
	v_mfma_f32_16x16x32_bf16 v[12:15], v[228:231], v[202:205], v[64:67]
	v_mfma_f32_16x16x32_bf16 v[8:11], v[232:235], v[192:195], v[8:11]
	v_mfma_f32_16x16x32_bf16 v[12:15], v[232:235], v[218:221], v[12:15]
	s_setprio 0
	s_barrier
	ds_read_b128 v[64:67], v136 offset:49152
	ds_read_b128 v[136:139], v136 offset:50176
	ds_read_b128 v[156:159], v135 offset:49152
	ds_read_b128 v[160:163], v135 offset:50176
	ds_read_b128 v[164:167], v134 offset:49152
	ds_read_b128 v[192:195], v134 offset:50176
	ds_read_b128 v[202:205], v133 offset:49152
	ds_read_b128 v[218:221], v133 offset:50176
	s_barrier
	s_waitcnt lgkmcnt(0)
	s_setprio 1
	s_waitcnt lgkmcnt(0)
	v_mfma_f32_16x16x32_bf16 v[56:59], v[184:187], v[64:67], v[56:59]
	v_mfma_f32_16x16x32_bf16 v[48:51], v[184:187], v[156:159], v[48:51]
	v_mfma_f32_16x16x32_bf16 v[60:63], v[16:19], v[64:67], v[60:63]
	v_mfma_f32_16x16x32_bf16 v[92:95], v[188:191], v[136:139], v[56:59]
	v_mfma_f32_16x16x32_bf16 v[56:59], v[16:19], v[156:159], v[206:209]
	v_mfma_f32_16x16x32_bf16 v[84:87], v[188:191], v[160:163], v[48:51]
	v_mfma_f32_16x16x32_bf16 v[48:51], v[16:19], v[164:167], v[210:213]
	v_mfma_f32_16x16x32_bf16 v[16:19], v[16:19], v[202:205], v[140:143]
	v_mfma_f32_16x16x32_bf16 v[120:123], v[180:183], v[192:195], v[48:51]
	v_mfma_f32_16x16x32_bf16 v[48:51], v[184:187], v[164:167], v[214:217]
	v_mfma_f32_16x16x32_bf16 v[124:127], v[180:183], v[218:221], v[16:19]
	v_mfma_f32_16x16x32_bf16 v[16:19], v[184:187], v[202:205], v[32:35]
	v_mfma_f32_16x16x32_bf16 v[100:103], v[180:183], v[136:139], v[60:63]
	v_mfma_f32_16x16x32_bf16 v[112:115], v[180:183], v[160:163], v[56:59]
	v_mfma_f32_16x16x32_bf16 v[76:79], v[188:191], v[192:195], v[48:51]
	v_mfma_f32_16x16x32_bf16 v[68:71], v[188:191], v[218:221], v[16:19]
	s_setprio 0
	s_setprio 1
	v_mfma_f32_16x16x32_bf16 v[16:19], v[128:131], v[64:67], v[144:147]
	v_mfma_f32_16x16x32_bf16 v[48:51], v[222:225], v[136:139], v[16:19]
	v_mfma_f32_16x16x32_bf16 v[16:19], v[228:231], v[64:67], v[24:27]
	v_mfma_f32_16x16x32_bf16 v[20:23], v[128:131], v[156:159], v[20:23]
	v_mfma_f32_16x16x32_bf16 v[24:27], v[128:131], v[164:167], v[152:155]
	v_mfma_f32_16x16x32_bf16 v[32:35], v[128:131], v[202:205], v[172:175]
	v_mfma_f32_16x16x32_bf16 v[56:59], v[222:225], v[160:163], v[20:23]
	v_mfma_f32_16x16x32_bf16 v[20:23], v[228:231], v[156:159], v[148:151]
	v_mfma_f32_16x16x32_bf16 v[60:63], v[222:225], v[192:195], v[24:27]
	v_mfma_f32_16x16x32_bf16 v[24:27], v[228:231], v[164:167], v[168:171]
	v_mfma_f32_16x16x32_bf16 v[64:67], v[222:225], v[218:221], v[32:35]
	v_mfma_f32_16x16x32_bf16 v[32:35], v[228:231], v[202:205], v[176:179]
	v_mfma_f32_16x16x32_bf16 v[16:19], v[232:235], v[136:139], v[16:19]
	v_mfma_f32_16x16x32_bf16 v[20:23], v[232:235], v[160:163], v[20:23]
	v_mfma_f32_16x16x32_bf16 v[24:27], v[232:235], v[192:195], v[24:27]
	v_mfma_f32_16x16x32_bf16 v[32:35], v[232:235], v[218:221], v[32:35]
	s_setprio 0
	s_movk_i32 s9, 0x100
	v_cmp_gt_u32_e32 vcc, s9, v132
	s_barrier
	s_and_saveexec_b64 s[28:29], vcc
	s_cbranch_execz .LBB0_212
	s_barrier
	s_branch .LBB0_212

.LBB0_314:
	ds_read_b128 v[172:175], v170
	ds_read_b128 v[176:179], v170 offset:1024
	ds_read_b128 v[180:183], v170 offset:2048
	ds_read_b128 v[184:187], v170 offset:3072
	s_add_u32 s8, s37, vcc_lo
	s_addc_u32 s9, s38, vcc_hi
	ds_read_b128 v[188:191], v166
	ds_read_b128 v[192:195], v166 offset:1024
	ds_read_b128 v[202:205], v165
	ds_read_b128 v[206:209], v165 offset:1024
	ds_read_b128 v[210:213], v163
	ds_read_b128 v[214:217], v163 offset:1024
	ds_read_b128 v[218:221], v162
	ds_read_b128 v[236:239], v162 offset:1024
	s_add_i32 s40, s34, 0xc000
	s_mov_b32 m0, s40
	s_add_i32 s41, s34, 0xe000
	s_add_u32 s98, s8, s94
	s_addc_u32 s99, s9, s95
	global_load_lds_dwordx4 v160, s[98:99]
	s_mov_b32 m0, s41
	s_nop 0
	global_load_lds_dwordx4 v161, s[98:99]
	s_waitcnt lgkmcnt(8)
	s_barrier
	s_waitcnt lgkmcnt(0)
	s_setprio 1
	s_waitcnt lgkmcnt(0)
	v_mfma_f32_16x16x32_bf16 v[44:47], v[172:175], v[188:191], v[44:47]
	v_mfma_f32_16x16x32_bf16 v[40:43], v[180:183], v[188:191], v[40:43]
	v_mfma_f32_16x16x32_bf16 v[60:63], v[172:175], v[202:205], v[60:63]
	v_mfma_f32_16x16x32_bf16 v[56:59], v[180:183], v[202:205], v[56:59]
	v_mfma_f32_16x16x32_bf16 v[76:79], v[172:175], v[210:213], v[76:79]
	v_mfma_f32_16x16x32_bf16 v[72:75], v[180:183], v[210:213], v[72:75]
	v_mfma_f32_16x16x32_bf16 v[92:95], v[172:175], v[218:221], v[92:95]
	v_mfma_f32_16x16x32_bf16 v[88:91], v[180:183], v[218:221], v[88:91]
	v_mfma_f32_16x16x32_bf16 v[44:47], v[176:179], v[192:195], v[44:47]
	v_mfma_f32_16x16x32_bf16 v[40:43], v[184:187], v[192:195], v[40:43]
	v_mfma_f32_16x16x32_bf16 v[60:63], v[176:179], v[206:209], v[60:63]
	v_mfma_f32_16x16x32_bf16 v[56:59], v[184:187], v[206:209], v[56:59]
	v_mfma_f32_16x16x32_bf16 v[76:79], v[176:179], v[214:217], v[76:79]
	v_mfma_f32_16x16x32_bf16 v[72:75], v[184:187], v[214:217], v[72:75]
	v_mfma_f32_16x16x32_bf16 v[92:95], v[176:179], v[236:239], v[92:95]
	v_mfma_f32_16x16x32_bf16 v[88:91], v[184:187], v[236:239], v[88:91]
	s_setprio 0
	s_barrier
	s_add_i32 s39, s39, 2
	s_add_u32 s28, s6, vcc_lo
	s_addc_u32 s29, s7, vcc_hi
	ds_read_b128 v[240:243], v169
	ds_read_b128 v[244:247], v169 offset:1024
	ds_read_b128 v[248:251], v169 offset:2048
	ds_read_b128 v[228:231], v169 offset:3072
	s_mov_b32 m0, s59
	s_add_u32 s98, s28, s0
	s_addc_u32 s99, s29, s1
	global_load_lds_dwordx4 v160, s[98:99]
	s_mov_b32 m0, s61
	s_nop 0
	global_load_lds_dwordx4 v161, s[98:99]
	s_barrier
	s_waitcnt lgkmcnt(0)
	s_setprio 1
	s_waitcnt lgkmcnt(0)
	v_mfma_f32_16x16x32_bf16 v[32:35], v[240:243], v[188:191], v[32:35]
	v_mfma_f32_16x16x32_bf16 v[36:39], v[248:251], v[188:191], v[36:39]
	v_mfma_f32_16x16x32_bf16 v[48:51], v[240:243], v[202:205], v[48:51]
	v_mfma_f32_16x16x32_bf16 v[52:55], v[248:251], v[202:205], v[52:55]
	v_mfma_f32_16x16x32_bf16 v[64:67], v[240:243], v[210:213], v[64:67]
	v_mfma_f32_16x16x32_bf16 v[68:71], v[248:251], v[210:213], v[68:71]
	v_mfma_f32_16x16x32_bf16 v[80:83], v[240:243], v[218:221], v[80:83]
	v_mfma_f32_16x16x32_bf16 v[84:87], v[248:251], v[218:221], v[84:87]
	v_mfma_f32_16x16x32_bf16 v[32:35], v[244:247], v[192:195], v[32:35]
	v_mfma_f32_16x16x32_bf16 v[36:39], v[228:231], v[192:195], v[36:39]
	v_mfma_f32_16x16x32_bf16 v[48:51], v[244:247], v[206:209], v[48:51]
	v_mfma_f32_16x16x32_bf16 v[52:55], v[228:231], v[206:209], v[52:55]
	v_mfma_f32_16x16x32_bf16 v[64:67], v[244:247], v[214:217], v[64:67]
	v_mfma_f32_16x16x32_bf16 v[68:71], v[228:231], v[214:217], v[68:71]
	v_mfma_f32_16x16x32_bf16 v[80:83], v[244:247], v[236:239], v[80:83]
	v_mfma_f32_16x16x32_bf16 v[84:87], v[228:231], v[236:239], v[84:87]
	s_setprio 0
	s_add_u32 s92, s90, vcc_lo
	s_addc_u32 s93, s91, vcc_hi
	s_barrier
	ds_read_b128 v[188:191], v166 offset:16384
	ds_read_b128 v[192:195], v166 offset:17408
	ds_read_b128 v[202:205], v165 offset:16384
	ds_read_b128 v[206:209], v165 offset:17408
	ds_read_b128 v[210:213], v163 offset:16384
	ds_read_b128 v[214:217], v163 offset:17408
	ds_read_b128 v[218:221], v162 offset:16384
	ds_read_b128 v[236:239], v162 offset:17408
	s_mov_b32 m0, s34
	s_add_u32 s98, s92, s0
	s_addc_u32 s99, s93, s1
	global_load_lds_dwordx4 v160, s[98:99]
	s_mov_b32 m0, s79
	s_nop 0
	global_load_lds_dwordx4 v161, s[98:99]
	s_barrier
	s_waitcnt lgkmcnt(0)
	s_setprio 1
	s_waitcnt lgkmcnt(0)
	v_mfma_f32_16x16x32_bf16 v[108:111], v[172:175], v[188:191], v[108:111]
	v_mfma_f32_16x16x32_bf16 v[104:107], v[180:183], v[188:191], v[104:107]
	v_mfma_f32_16x16x32_bf16 v[124:127], v[172:175], v[202:205], v[124:127]
	v_mfma_f32_16x16x32_bf16 v[120:123], v[180:183], v[202:205], v[120:123]
	v_mfma_f32_16x16x32_bf16 v[140:143], v[172:175], v[210:213], v[140:143]
	v_mfma_f32_16x16x32_bf16 v[136:139], v[180:183], v[210:213], v[136:139]
	v_mfma_f32_16x16x32_bf16 v[156:159], v[172:175], v[218:221], v[156:159]
	v_mfma_f32_16x16x32_bf16 v[152:155], v[180:183], v[218:221], v[152:155]
	v_mfma_f32_16x16x32_bf16 v[108:111], v[176:179], v[192:195], v[108:111]
	v_mfma_f32_16x16x32_bf16 v[104:107], v[184:187], v[192:195], v[104:107]
	v_mfma_f32_16x16x32_bf16 v[124:127], v[176:179], v[206:209], v[124:127]
	v_mfma_f32_16x16x32_bf16 v[120:123], v[184:187], v[206:209], v[120:123]
	v_mfma_f32_16x16x32_bf16 v[140:143], v[176:179], v[214:217], v[140:143]
	v_mfma_f32_16x16x32_bf16 v[136:139], v[184:187], v[214:217], v[136:139]
	v_mfma_f32_16x16x32_bf16 v[156:159], v[176:179], v[236:239], v[156:159]
	v_mfma_f32_16x16x32_bf16 v[152:155], v[184:187], v[236:239], v[152:155]
	s_setprio 0
	s_barrier
	s_add_u32 s96, s82, vcc_lo
	s_addc_u32 s97, s36, vcc_hi
	s_mov_b32 m0, s52
	s_add_u32 s98, s96, s0
	s_addc_u32 s99, s97, s1
	global_load_lds_dwordx4 v160, s[98:99]
	s_mov_b32 m0, s53
	s_nop 0
	global_load_lds_dwordx4 v161, s[98:99]
	s_waitcnt vmcnt(6)
	s_barrier
	s_setprio 1
	v_mfma_f32_16x16x32_bf16 v[96:99], v[240:243], v[188:191], v[96:99]
	v_mfma_f32_16x16x32_bf16 v[100:103], v[248:251], v[188:191], v[100:103]
	v_mfma_f32_16x16x32_bf16 v[112:115], v[240:243], v[202:205], v[112:115]
	v_mfma_f32_16x16x32_bf16 v[116:119], v[248:251], v[202:205], v[116:119]
	v_mfma_f32_16x16x32_bf16 v[128:131], v[240:243], v[210:213], v[128:131]
	v_mfma_f32_16x16x32_bf16 v[132:135], v[248:251], v[210:213], v[132:135]
	v_mfma_f32_16x16x32_bf16 v[144:147], v[240:243], v[218:221], v[144:147]
	v_mfma_f32_16x16x32_bf16 v[148:151], v[248:251], v[218:221], v[148:151]
	v_mfma_f32_16x16x32_bf16 v[96:99], v[244:247], v[192:195], v[96:99]
	v_mfma_f32_16x16x32_bf16 v[100:103], v[228:231], v[192:195], v[100:103]
	v_mfma_f32_16x16x32_bf16 v[112:115], v[244:247], v[206:209], v[112:115]
	v_mfma_f32_16x16x32_bf16 v[116:119], v[228:231], v[206:209], v[116:119]
	v_mfma_f32_16x16x32_bf16 v[128:131], v[244:247], v[214:217], v[128:131]
	v_mfma_f32_16x16x32_bf16 v[132:135], v[228:231], v[214:217], v[132:135]
	v_mfma_f32_16x16x32_bf16 v[144:147], v[244:247], v[236:239], v[144:147]
	v_mfma_f32_16x16x32_bf16 v[148:151], v[228:231], v[236:239], v[148:151]
	s_setprio 0
	s_barrier
	ds_read_b128 v[172:175], v168
	ds_read_b128 v[176:179], v168 offset:1024
	ds_read_b128 v[180:183], v168 offset:2048
	ds_read_b128 v[184:187], v168 offset:3072
	ds_read_b128 v[188:191], v166 offset:32768
	ds_read_b128 v[192:195], v166 offset:33792
	ds_read_b128 v[202:205], v165 offset:32768
	ds_read_b128 v[206:209], v165 offset:33792
	ds_read_b128 v[210:213], v163 offset:32768
	ds_read_b128 v[214:217], v163 offset:33792
	ds_read_b128 v[218:221], v162 offset:32768
	ds_read_b128 v[228:231], v162 offset:33792
	s_mov_b32 m0, s68
	s_add_u32 s98, s8, s0
	s_addc_u32 s99, s9, s1
	global_load_lds_dwordx4 v160, s[98:99]
	s_mov_b32 m0, s69
	s_nop 0
	global_load_lds_dwordx4 v161, s[98:99]
	s_waitcnt lgkmcnt(8)
	s_barrier
	s_waitcnt lgkmcnt(0)
	s_setprio 1
	s_waitcnt lgkmcnt(0)
	v_mfma_f32_16x16x32_bf16 v[44:47], v[172:175], v[188:191], v[44:47]
	v_mfma_f32_16x16x32_bf16 v[40:43], v[180:183], v[188:191], v[40:43]
	v_mfma_f32_16x16x32_bf16 v[60:63], v[172:175], v[202:205], v[60:63]
	v_mfma_f32_16x16x32_bf16 v[56:59], v[180:183], v[202:205], v[56:59]
	v_mfma_f32_16x16x32_bf16 v[76:79], v[172:175], v[210:213], v[76:79]
	v_mfma_f32_16x16x32_bf16 v[72:75], v[180:183], v[210:213], v[72:75]
	v_mfma_f32_16x16x32_bf16 v[92:95], v[172:175], v[218:221], v[92:95]
	v_mfma_f32_16x16x32_bf16 v[88:91], v[180:183], v[218:221], v[88:91]
	v_mfma_f32_16x16x32_bf16 v[44:47], v[176:179], v[192:195], v[44:47]
	v_mfma_f32_16x16x32_bf16 v[40:43], v[184:187], v[192:195], v[40:43]
	v_mfma_f32_16x16x32_bf16 v[60:63], v[176:179], v[206:209], v[60:63]
	v_mfma_f32_16x16x32_bf16 v[56:59], v[184:187], v[206:209], v[56:59]
	v_mfma_f32_16x16x32_bf16 v[76:79], v[176:179], v[214:217], v[76:79]
	v_mfma_f32_16x16x32_bf16 v[72:75], v[184:187], v[214:217], v[72:75]
	v_mfma_f32_16x16x32_bf16 v[92:95], v[176:179], v[228:231], v[92:95]
	v_mfma_f32_16x16x32_bf16 v[88:91], v[184:187], v[228:231], v[88:91]
	s_setprio 0
	s_barrier
	ds_read_b128 v[236:239], v167
	ds_read_b128 v[240:243], v167 offset:1024
	ds_read_b128 v[244:247], v167 offset:2048
	ds_read_b128 v[248:251], v167 offset:3072
	s_mov_b32 m0, s70
	s_add_u32 s98, s28, s30
	s_addc_u32 s99, s29, s31
	global_load_lds_dwordx4 v160, s[98:99]
	s_mov_b32 m0, s71
	s_nop 0
	global_load_lds_dwordx4 v161, s[98:99]
	s_barrier
	s_waitcnt lgkmcnt(0)
	s_setprio 1
	s_waitcnt lgkmcnt(0)
	v_mfma_f32_16x16x32_bf16 v[32:35], v[236:239], v[188:191], v[32:35]
	v_mfma_f32_16x16x32_bf16 v[36:39], v[244:247], v[188:191], v[36:39]
	v_mfma_f32_16x16x32_bf16 v[48:51], v[236:239], v[202:205], v[48:51]
	v_mfma_f32_16x16x32_bf16 v[52:55], v[244:247], v[202:205], v[52:55]
	v_mfma_f32_16x16x32_bf16 v[64:67], v[236:239], v[210:213], v[64:67]
	v_mfma_f32_16x16x32_bf16 v[68:71], v[244:247], v[210:213], v[68:71]
	v_mfma_f32_16x16x32_bf16 v[80:83], v[236:239], v[218:221], v[80:83]
	v_mfma_f32_16x16x32_bf16 v[84:87], v[244:247], v[218:221], v[84:87]
	v_mfma_f32_16x16x32_bf16 v[32:35], v[240:243], v[192:195], v[32:35]
	v_mfma_f32_16x16x32_bf16 v[36:39], v[248:251], v[192:195], v[36:39]
	v_mfma_f32_16x16x32_bf16 v[48:51], v[240:243], v[206:209], v[48:51]
	v_mfma_f32_16x16x32_bf16 v[52:55], v[248:251], v[206:209], v[52:55]
	v_mfma_f32_16x16x32_bf16 v[64:67], v[240:243], v[214:217], v[64:67]
	v_mfma_f32_16x16x32_bf16 v[68:71], v[248:251], v[214:217], v[68:71]
	v_mfma_f32_16x16x32_bf16 v[80:83], v[240:243], v[228:231], v[80:83]
	v_mfma_f32_16x16x32_bf16 v[84:87], v[248:251], v[228:231], v[84:87]
	s_setprio 0
	v_mov_b32_e32 v222, v161
	s_barrier
	ds_read_b128 v[188:191], v166 offset:49152
	ds_read_b128 v[192:195], v166 offset:50176
	ds_read_b128 v[202:205], v165 offset:49152
	ds_read_b128 v[206:209], v165 offset:50176
	ds_read_b128 v[210:213], v163 offset:49152
	ds_read_b128 v[214:217], v163 offset:50176
	ds_read_b128 v[218:221], v162 offset:49152
	ds_read_b128 v[228:231], v162 offset:50176
	v_mov_b32_e32 v223, v197
	s_mov_b32 m0, s72
	s_add_u32 s98, s92, s30
	s_addc_u32 s99, s93, s31
	global_load_lds_dwordx4 v160, s[98:99]
	s_mov_b32 m0, s73
	s_nop 0
	global_load_lds_dwordx4 v161, s[98:99]
	s_barrier
	s_waitcnt lgkmcnt(0)
	s_setprio 1
	s_waitcnt lgkmcnt(0)
	v_mfma_f32_16x16x32_bf16 v[108:111], v[172:175], v[188:191], v[108:111]
	v_mfma_f32_16x16x32_bf16 v[104:107], v[180:183], v[188:191], v[104:107]
	v_mfma_f32_16x16x32_bf16 v[124:127], v[172:175], v[202:205], v[124:127]
	v_mfma_f32_16x16x32_bf16 v[120:123], v[180:183], v[202:205], v[120:123]
	v_mfma_f32_16x16x32_bf16 v[140:143], v[172:175], v[210:213], v[140:143]
	v_mfma_f32_16x16x32_bf16 v[136:139], v[180:183], v[210:213], v[136:139]
	v_mfma_f32_16x16x32_bf16 v[156:159], v[172:175], v[218:221], v[156:159]
	v_mfma_f32_16x16x32_bf16 v[152:155], v[180:183], v[218:221], v[152:155]
	v_mfma_f32_16x16x32_bf16 v[108:111], v[176:179], v[192:195], v[108:111]
	v_mfma_f32_16x16x32_bf16 v[104:107], v[184:187], v[192:195], v[104:107]
	v_mfma_f32_16x16x32_bf16 v[124:127], v[176:179], v[206:209], v[124:127]
	v_mfma_f32_16x16x32_bf16 v[120:123], v[184:187], v[206:209], v[120:123]
	v_mfma_f32_16x16x32_bf16 v[140:143], v[176:179], v[214:217], v[140:143]
	v_mfma_f32_16x16x32_bf16 v[136:139], v[184:187], v[214:217], v[136:139]
	v_mfma_f32_16x16x32_bf16 v[156:159], v[176:179], v[228:231], v[156:159]
	v_mfma_f32_16x16x32_bf16 v[152:155], v[184:187], v[228:231], v[152:155]
	s_setprio 0
	s_barrier
	v_mov_b32_e32 v196, v160
	s_mov_b32 m0, s75
	s_add_u32 s98, s96, s30
	s_addc_u32 s99, s97, s31
	global_load_lds_dwordx4 v160, s[98:99]
	s_mov_b32 m0, s89
	s_nop 0
	global_load_lds_dwordx4 v161, s[98:99]
	s_waitcnt vmcnt(6)
	s_barrier
	s_setprio 1
	v_mfma_f32_16x16x32_bf16 v[96:99], v[236:239], v[188:191], v[96:99]
	v_mfma_f32_16x16x32_bf16 v[100:103], v[244:247], v[188:191], v[100:103]
	v_mfma_f32_16x16x32_bf16 v[112:115], v[236:239], v[202:205], v[112:115]
	v_mfma_f32_16x16x32_bf16 v[116:119], v[244:247], v[202:205], v[116:119]
	v_mfma_f32_16x16x32_bf16 v[128:131], v[236:239], v[210:213], v[128:131]
	v_mfma_f32_16x16x32_bf16 v[132:135], v[244:247], v[210:213], v[132:135]
	v_mfma_f32_16x16x32_bf16 v[144:147], v[236:239], v[218:221], v[144:147]
	v_mfma_f32_16x16x32_bf16 v[148:151], v[244:247], v[218:221], v[148:151]
	v_mfma_f32_16x16x32_bf16 v[96:99], v[240:243], v[192:195], v[96:99]
	v_mfma_f32_16x16x32_bf16 v[100:103], v[248:251], v[192:195], v[100:103]
	v_mfma_f32_16x16x32_bf16 v[112:115], v[240:243], v[206:209], v[112:115]
	v_mfma_f32_16x16x32_bf16 v[116:119], v[248:251], v[206:209], v[116:119]
	v_mfma_f32_16x16x32_bf16 v[128:131], v[240:243], v[214:217], v[128:131]
	v_mfma_f32_16x16x32_bf16 v[132:135], v[248:251], v[214:217], v[132:135]
	v_mfma_f32_16x16x32_bf16 v[144:147], v[240:243], v[228:231], v[144:147]
	v_mfma_f32_16x16x32_bf16 v[148:151], v[248:251], v[228:231], v[148:151]
	s_setprio 0
	s_add_u32 vcc_lo, vcc_lo, 0x100
	s_addc_u32 vcc_hi, vcc_hi, 0
	s_cmp_lt_u32 s39, s74
	s_barrier
	s_cbranch_scc1 .LBB0_314
	s_add_i32 s34, s33, -1
	s_lshl_b64 s[6:7], s[34:35], 7
	s_add_u32 s6, s84, s6
	s_addc_u32 s7, s85, s7
	s_mov_b32 m0, s40
	ds_read_b128 v[172:175], v170
	ds_read_b128 v[176:179], v170 offset:1024
	ds_read_b128 v[180:183], v170 offset:2048
	ds_read_b128 v[184:187], v170 offset:3072
	ds_read_b128 v[188:191], v166
	ds_read_b128 v[192:195], v166 offset:1024
	ds_read_b128 v[202:205], v165
	ds_read_b128 v[206:209], v165 offset:1024
	ds_read_b128 v[210:213], v163
	ds_read_b128 v[214:217], v163 offset:1024
	ds_read_b128 v[218:221], v162
	ds_read_b128 v[228:231], v162 offset:1024
	s_nop 0
	global_load_lds_dwordx4 v160, s[6:7]
	s_mov_b32 m0, s41
	s_nop 0
	global_load_lds_dwordx4 v161, s[6:7]
	s_barrier
	s_waitcnt lgkmcnt(0)
	s_setprio 1
	s_waitcnt lgkmcnt(0)
	v_mfma_f32_16x16x32_bf16 v[40:43], v[180:183], v[188:191], v[40:43]
	v_mfma_f32_16x16x32_bf16 v[56:59], v[180:183], v[202:205], v[56:59]
	v_mfma_f32_16x16x32_bf16 v[72:75], v[180:183], v[210:213], v[72:75]
	v_mfma_f32_16x16x32_bf16 v[92:95], v[172:175], v[218:221], v[92:95]
	v_mfma_f32_16x16x32_bf16 v[88:91], v[180:183], v[218:221], v[88:91]
	v_mfma_f32_16x16x32_bf16 v[44:47], v[172:175], v[188:191], v[44:47]
	v_mfma_f32_16x16x32_bf16 v[40:43], v[184:187], v[192:195], v[40:43]
	v_mfma_f32_16x16x32_bf16 v[60:63], v[172:175], v[202:205], v[60:63]
	v_mfma_f32_16x16x32_bf16 v[56:59], v[184:187], v[206:209], v[56:59]
	v_mfma_f32_16x16x32_bf16 v[76:79], v[172:175], v[210:213], v[76:79]
	v_mfma_f32_16x16x32_bf16 v[72:75], v[184:187], v[214:217], v[72:75]
	v_mfma_f32_16x16x32_bf16 v[92:95], v[176:179], v[228:231], v[92:95]
	v_mfma_f32_16x16x32_bf16 v[88:91], v[184:187], v[228:231], v[88:91]
	v_mfma_f32_16x16x32_bf16 v[44:47], v[176:179], v[192:195], v[44:47]
	v_mfma_f32_16x16x32_bf16 v[60:63], v[176:179], v[206:209], v[60:63]
	v_mfma_f32_16x16x32_bf16 v[76:79], v[176:179], v[214:217], v[76:79]
	s_setprio 0
	s_barrier
	ds_read_b128 v[236:239], v169
	ds_read_b128 v[240:243], v169 offset:1024
	ds_read_b128 v[244:247], v169 offset:2048
	ds_read_b128 v[248:251], v169 offset:3072
	s_barrier
	s_waitcnt lgkmcnt(0)
	s_setprio 1
	s_waitcnt lgkmcnt(0)
	v_mfma_f32_16x16x32_bf16 v[36:39], v[244:247], v[188:191], v[36:39]
	v_mfma_f32_16x16x32_bf16 v[32:35], v[236:239], v[188:191], v[32:35]
	v_mfma_f32_16x16x32_bf16 v[188:191], v[248:251], v[192:195], v[36:39]
	v_mfma_f32_16x16x32_bf16 v[36:39], v[236:239], v[202:205], v[48:51]
	v_mfma_f32_16x16x32_bf16 v[48:51], v[240:243], v[206:209], v[36:39]
	v_mfma_f32_16x16x32_bf16 v[36:39], v[244:247], v[202:205], v[52:55]
	v_mfma_f32_16x16x32_bf16 v[32:35], v[240:243], v[192:195], v[32:35]
	v_mfma_f32_16x16x32_bf16 v[192:195], v[248:251], v[206:209], v[36:39]
	v_mfma_f32_16x16x32_bf16 v[36:39], v[236:239], v[210:213], v[64:67]
	v_mfma_f32_16x16x32_bf16 v[64:67], v[240:243], v[214:217], v[36:39]
	v_mfma_f32_16x16x32_bf16 v[36:39], v[244:247], v[210:213], v[68:71]
	v_mfma_f32_16x16x32_bf16 v[202:205], v[248:251], v[214:217], v[36:39]
	v_mfma_f32_16x16x32_bf16 v[36:39], v[236:239], v[218:221], v[80:83]
	v_mfma_f32_16x16x32_bf16 v[80:83], v[240:243], v[228:231], v[36:39]
	v_mfma_f32_16x16x32_bf16 v[36:39], v[244:247], v[218:221], v[84:87]
	v_mfma_f32_16x16x32_bf16 v[206:209], v[248:251], v[228:231], v[36:39]
	s_setprio 0
	s_barrier
	s_nop 4
	ds_read_b128 v[36:39], v166 offset:16384
	ds_read_b128 v[52:55], v166 offset:17408
	ds_read_b128 v[68:71], v165 offset:16384
	ds_read_b128 v[84:87], v165 offset:17408
	ds_read_b128 v[210:213], v163 offset:16384
	ds_read_b128 v[214:217], v163 offset:17408
	ds_read_b128 v[218:221], v162 offset:16384
	ds_read_b128 v[228:231], v162 offset:17408
	s_waitcnt vmcnt(4)
	s_barrier
	s_waitcnt lgkmcnt(0)
	s_setprio 1
	s_waitcnt lgkmcnt(0)
	v_mfma_f32_16x16x32_bf16 v[108:111], v[172:175], v[36:39], v[108:111]
	v_mfma_f32_16x16x32_bf16 v[222:225], v[176:179], v[52:55], v[108:111]
	v_mfma_f32_16x16x32_bf16 v[108:111], v[172:175], v[68:71], v[124:127]
	v_mfma_f32_16x16x32_bf16 v[124:127], v[176:179], v[84:87], v[108:111]
	v_mfma_f32_16x16x32_bf16 v[108:111], v[180:183], v[68:71], v[120:123]
	v_mfma_f32_16x16x32_bf16 v[120:123], v[184:187], v[84:87], v[108:111]
	v_mfma_f32_16x16x32_bf16 v[108:111], v[172:175], v[210:213], v[140:143]
	v_mfma_f32_16x16x32_bf16 v[140:143], v[176:179], v[214:217], v[108:111]
	v_mfma_f32_16x16x32_bf16 v[108:111], v[180:183], v[210:213], v[136:139]
	v_mfma_f32_16x16x32_bf16 v[136:139], v[184:187], v[214:217], v[108:111]
	v_mfma_f32_16x16x32_bf16 v[108:111], v[172:175], v[218:221], v[156:159]
	v_mfma_f32_16x16x32_bf16 v[104:107], v[180:183], v[36:39], v[104:107]
	v_mfma_f32_16x16x32_bf16 v[156:159], v[176:179], v[228:231], v[108:111]
	v_mfma_f32_16x16x32_bf16 v[108:111], v[180:183], v[218:221], v[152:155]
	v_mfma_f32_16x16x32_bf16 v[104:107], v[184:187], v[52:55], v[104:107]
	v_mfma_f32_16x16x32_bf16 v[152:155], v[184:187], v[228:231], v[108:111]
	s_setprio 0
	s_setprio 1
	v_mfma_f32_16x16x32_bf16 v[96:99], v[236:239], v[36:39], v[96:99]
	v_mfma_f32_16x16x32_bf16 v[36:39], v[244:247], v[36:39], v[100:103]
	v_mfma_f32_16x16x32_bf16 v[172:175], v[248:251], v[52:55], v[36:39]
	v_mfma_f32_16x16x32_bf16 v[36:39], v[236:239], v[68:71], v[112:115]
	v_mfma_f32_16x16x32_bf16 v[112:115], v[240:243], v[84:87], v[36:39]
	v_mfma_f32_16x16x32_bf16 v[36:39], v[244:247], v[68:71], v[116:119]
	v_mfma_f32_16x16x32_bf16 v[180:183], v[248:251], v[84:87], v[36:39]
	v_mfma_f32_16x16x32_bf16 v[36:39], v[236:239], v[210:213], v[128:131]
	v_mfma_f32_16x16x32_bf16 v[128:131], v[240:243], v[214:217], v[36:39]
	v_mfma_f32_16x16x32_bf16 v[36:39], v[244:247], v[210:213], v[132:135]
	v_mfma_f32_16x16x32_bf16 v[184:187], v[248:251], v[214:217], v[36:39]
	v_mfma_f32_16x16x32_bf16 v[36:39], v[236:239], v[218:221], v[144:147]
	v_mfma_f32_16x16x32_bf16 v[96:99], v[240:243], v[52:55], v[96:99]
	v_mfma_f32_16x16x32_bf16 v[144:147], v[240:243], v[228:231], v[36:39]
	v_mfma_f32_16x16x32_bf16 v[36:39], v[244:247], v[218:221], v[148:151]
	v_mfma_f32_16x16x32_bf16 v[210:213], v[248:251], v[228:231], v[36:39]
	s_setprio 0
	s_barrier
	ds_read_b128 v[148:151], v168
	ds_read_b128 v[214:217], v168 offset:1024
	ds_read_b128 v[218:221], v168 offset:2048
	ds_read_b128 v[228:231], v168 offset:3072
	ds_read_b128 v[100:103], v166 offset:32768
	ds_read_b128 v[108:111], v166 offset:33792
	ds_read_b128 v[116:119], v165 offset:32768
	ds_read_b128 v[132:135], v165 offset:33792
	ds_read_b128 v[236:239], v163 offset:32768
	ds_read_b128 v[240:243], v163 offset:33792
	ds_read_b128 v[244:247], v162 offset:32768
	ds_read_b128 v[248:251], v162 offset:33792
	s_waitcnt vmcnt(2)
	s_barrier
	s_waitcnt lgkmcnt(0)
	s_setprio 1
	s_waitcnt lgkmcnt(0)
	v_mfma_f32_16x16x32_bf16 v[36:39], v[148:151], v[100:103], v[44:47]
	v_mfma_f32_16x16x32_bf16 v[44:47], v[148:151], v[116:119], v[60:63]
	v_mfma_f32_16x16x32_bf16 v[52:55], v[214:217], v[132:135], v[44:47]
	v_mfma_f32_16x16x32_bf16 v[44:47], v[218:221], v[116:119], v[56:59]
	v_mfma_f32_16x16x32_bf16 v[56:59], v[228:231], v[132:135], v[44:47]
	v_mfma_f32_16x16x32_bf16 v[44:47], v[148:151], v[236:239], v[76:79]
	v_mfma_f32_16x16x32_bf16 v[68:71], v[214:217], v[240:243], v[44:47]
	v_mfma_f32_16x16x32_bf16 v[44:47], v[218:221], v[236:239], v[72:75]
	v_mfma_f32_16x16x32_bf16 v[72:75], v[228:231], v[240:243], v[44:47]
	v_mfma_f32_16x16x32_bf16 v[44:47], v[148:151], v[244:247], v[92:95]
	v_mfma_f32_16x16x32_bf16 v[40:43], v[218:221], v[100:103], v[40:43]
	v_mfma_f32_16x16x32_bf16 v[84:87], v[214:217], v[248:251], v[44:47]
	v_mfma_f32_16x16x32_bf16 v[44:47], v[218:221], v[244:247], v[88:91]
	v_mfma_f32_16x16x32_bf16 v[36:39], v[214:217], v[108:111], v[36:39]
	v_mfma_f32_16x16x32_bf16 v[40:43], v[228:231], v[108:111], v[40:43]
	v_mfma_f32_16x16x32_bf16 v[88:91], v[228:231], v[248:251], v[44:47]
	s_setprio 0
	s_barrier
	s_nop 2
	ds_read_b128 v[44:47], v167
	ds_read_b128 v[60:63], v167 offset:1024
	ds_read_b128 v[76:79], v167 offset:2048
	ds_read_b128 v[232:235], v167 offset:3072
	s_waitcnt vmcnt(0)
	s_barrier
	s_waitcnt lgkmcnt(0)
	s_setprio 1
	s_waitcnt lgkmcnt(0)
	v_mfma_f32_16x16x32_bf16 v[92:95], v[76:79], v[100:103], v[188:191]
	v_mfma_f32_16x16x32_bf16 v[176:179], v[232:235], v[108:111], v[92:95]
	v_mfma_f32_16x16x32_bf16 v[92:95], v[76:79], v[116:119], v[192:195]
	v_mfma_f32_16x16x32_bf16 v[32:35], v[44:47], v[100:103], v[32:35]
	v_mfma_f32_16x16x32_bf16 v[48:51], v[44:47], v[116:119], v[48:51]
	v_mfma_f32_16x16x32_bf16 v[168:171], v[232:235], v[132:135], v[92:95]
	v_mfma_f32_16x16x32_bf16 v[64:67], v[44:47], v[236:239], v[64:67]
	v_mfma_f32_16x16x32_bf16 v[92:95], v[76:79], v[236:239], v[202:205]
	v_mfma_f32_16x16x32_bf16 v[80:83], v[44:47], v[244:247], v[80:83]
	v_mfma_f32_16x16x32_bf16 v[100:103], v[76:79], v[244:247], v[206:209]
	v_mfma_f32_16x16x32_bf16 v[32:35], v[60:63], v[108:111], v[32:35]
	v_mfma_f32_16x16x32_bf16 v[48:51], v[60:63], v[132:135], v[48:51]
	v_mfma_f32_16x16x32_bf16 v[64:67], v[60:63], v[240:243], v[64:67]
	v_mfma_f32_16x16x32_bf16 v[92:95], v[232:235], v[240:243], v[92:95]
	v_mfma_f32_16x16x32_bf16 v[80:83], v[60:63], v[248:251], v[80:83]
	v_mfma_f32_16x16x32_bf16 v[108:111], v[232:235], v[248:251], v[100:103]
	s_setprio 0
	s_barrier
	ds_read_b128 v[188:191], v166 offset:49152
	ds_read_b128 v[192:195], v166 offset:50176
	ds_read_b128 v[202:205], v165 offset:49152
	ds_read_b128 v[206:209], v165 offset:50176
	ds_read_b128 v[236:239], v163 offset:49152
	ds_read_b128 v[240:243], v163 offset:50176
	ds_read_b128 v[244:247], v162 offset:49152
	ds_read_b128 v[160:163], v162 offset:50176
	s_barrier
	s_waitcnt lgkmcnt(0)
	s_setprio 1
	s_waitcnt lgkmcnt(0)
	v_mfma_f32_16x16x32_bf16 v[116:119], v[148:151], v[202:205], v[124:127]
	v_mfma_f32_16x16x32_bf16 v[124:127], v[148:151], v[236:239], v[140:143]
	v_mfma_f32_16x16x32_bf16 v[132:135], v[214:217], v[240:243], v[124:127]
	v_mfma_f32_16x16x32_bf16 v[124:127], v[218:221], v[236:239], v[136:139]
	v_mfma_f32_16x16x32_bf16 v[136:139], v[228:231], v[240:243], v[124:127]
	v_mfma_f32_16x16x32_bf16 v[124:127], v[148:151], v[244:247], v[156:159]
	v_mfma_f32_16x16x32_bf16 v[100:103], v[148:151], v[188:191], v[222:225]
	v_mfma_f32_16x16x32_bf16 v[104:107], v[218:221], v[188:191], v[104:107]
	v_mfma_f32_16x16x32_bf16 v[120:123], v[218:221], v[202:205], v[120:123]
	v_mfma_f32_16x16x32_bf16 v[148:151], v[214:217], v[160:163], v[124:127]
	v_mfma_f32_16x16x32_bf16 v[124:127], v[218:221], v[244:247], v[152:155]
	v_mfma_f32_16x16x32_bf16 v[100:103], v[214:217], v[192:195], v[100:103]
	v_mfma_f32_16x16x32_bf16 v[104:107], v[228:231], v[192:195], v[104:107]
	v_mfma_f32_16x16x32_bf16 v[116:119], v[214:217], v[206:209], v[116:119]
	v_mfma_f32_16x16x32_bf16 v[120:123], v[228:231], v[206:209], v[120:123]
	v_mfma_f32_16x16x32_bf16 v[152:155], v[228:231], v[160:163], v[124:127]
	s_setprio 0
	s_setprio 1
	v_mfma_f32_16x16x32_bf16 v[96:99], v[44:47], v[188:191], v[96:99]
	v_mfma_f32_16x16x32_bf16 v[112:115], v[44:47], v[202:205], v[112:115]
	v_mfma_f32_16x16x32_bf16 v[128:131], v[44:47], v[236:239], v[128:131]
	v_mfma_f32_16x16x32_bf16 v[44:47], v[44:47], v[244:247], v[144:147]
	v_mfma_f32_16x16x32_bf16 v[124:127], v[76:79], v[188:191], v[172:175]
	v_mfma_f32_16x16x32_bf16 v[140:143], v[76:79], v[202:205], v[180:183]
	v_mfma_f32_16x16x32_bf16 v[156:159], v[76:79], v[236:239], v[184:187]
	v_mfma_f32_16x16x32_bf16 v[144:147], v[60:63], v[160:163], v[44:47]
	v_mfma_f32_16x16x32_bf16 v[44:47], v[76:79], v[244:247], v[210:213]
	v_mfma_f32_16x16x32_bf16 v[96:99], v[60:63], v[192:195], v[96:99]
	v_mfma_f32_16x16x32_bf16 v[124:127], v[232:235], v[192:195], v[124:127]
	v_mfma_f32_16x16x32_bf16 v[112:115], v[60:63], v[206:209], v[112:115]
	v_mfma_f32_16x16x32_bf16 v[140:143], v[232:235], v[206:209], v[140:143]
	v_mfma_f32_16x16x32_bf16 v[128:131], v[60:63], v[240:243], v[128:131]
	v_mfma_f32_16x16x32_bf16 v[156:159], v[232:235], v[240:243], v[156:159]
	v_mfma_f32_16x16x32_bf16 v[160:163], v[232:235], v[160:163], v[44:47]
	s_setprio 0
	s_movk_i32 s6, 0x100
	v_cmp_gt_u32_e32 vcc, s6, v164
	s_barrier
	s_and_saveexec_b64 s[6:7], vcc
	s_cbranch_execz .LBB0_317
	s_barrier

.LBB0_568:
	ds_read_b128 v[140:143], v129
	ds_read_b128 v[144:147], v129 offset:1024
	ds_read_b128 v[148:151], v129 offset:2048
	ds_read_b128 v[152:155], v129 offset:3072
	s_add_u32 s28, s8, s10
	s_addc_u32 s29, s9, s11
	ds_read_b128 v[156:159], v136
	ds_read_b128 v[160:163], v136 offset:1024
	ds_read_b128 v[164:167], v135
	ds_read_b128 v[168:171], v135 offset:1024
	ds_read_b128 v[172:175], v134
	ds_read_b128 v[176:179], v134 offset:1024
	ds_read_b128 v[180:183], v133
	ds_read_b128 v[184:187], v133 offset:1024
	s_add_i32 s39, s68, 0xc000
	s_mov_b32 m0, s39
	s_add_i32 s38, s68, 0xe000
	s_add_u32 s98, s28, s44
	s_addc_u32 s99, s29, s45
	global_load_lds_dwordx4 v128, s[98:99]
	s_mov_b32 m0, s38
	s_nop 0
	global_load_lds_dwordx4 v130, s[98:99]
	s_waitcnt lgkmcnt(8)
	s_barrier
	s_waitcnt lgkmcnt(0)
	s_setprio 1
	s_waitcnt lgkmcnt(0)
	v_mfma_f32_16x16x32_bf16 v[124:127], v[140:143], v[156:159], v[124:127]
	v_mfma_f32_16x16x32_bf16 v[120:123], v[148:151], v[156:159], v[120:123]
	v_mfma_f32_16x16x32_bf16 v[116:119], v[140:143], v[164:167], v[116:119]
	v_mfma_f32_16x16x32_bf16 v[112:115], v[148:151], v[164:167], v[112:115]
	v_mfma_f32_16x16x32_bf16 v[108:111], v[140:143], v[172:175], v[108:111]
	v_mfma_f32_16x16x32_bf16 v[104:107], v[148:151], v[172:175], v[104:107]
	v_mfma_f32_16x16x32_bf16 v[100:103], v[140:143], v[180:183], v[100:103]
	v_mfma_f32_16x16x32_bf16 v[96:99], v[148:151], v[180:183], v[96:99]
	v_mfma_f32_16x16x32_bf16 v[124:127], v[144:147], v[160:163], v[124:127]
	v_mfma_f32_16x16x32_bf16 v[120:123], v[152:155], v[160:163], v[120:123]
	v_mfma_f32_16x16x32_bf16 v[116:119], v[144:147], v[168:171], v[116:119]
	v_mfma_f32_16x16x32_bf16 v[112:115], v[152:155], v[168:171], v[112:115]
	v_mfma_f32_16x16x32_bf16 v[108:111], v[144:147], v[176:179], v[108:111]
	v_mfma_f32_16x16x32_bf16 v[104:107], v[152:155], v[176:179], v[104:107]
	v_mfma_f32_16x16x32_bf16 v[100:103], v[144:147], v[184:187], v[100:103]
	v_mfma_f32_16x16x32_bf16 v[96:99], v[152:155], v[184:187], v[96:99]
	s_setprio 0
	s_barrier
	s_add_u32 s56, s6, s10
	s_addc_u32 s57, s7, s11
	ds_read_b128 v[188:191], v139
	ds_read_b128 v[192:195], v139 offset:1024
	ds_read_b128 v[202:205], v139 offset:2048
	ds_read_b128 v[206:209], v139 offset:3072
	s_add_i32 m0, s68, 0x10000
	s_add_u32 s98, s56, s0
	s_addc_u32 s99, s57, s1
	global_load_lds_dwordx4 v128, s[98:99]
	s_add_i32 m0, s68, 0x12000
	s_nop 0
	global_load_lds_dwordx4 v130, s[98:99]
	s_barrier
	s_waitcnt lgkmcnt(0)
	s_setprio 1
	s_waitcnt lgkmcnt(0)
	v_mfma_f32_16x16x32_bf16 v[92:95], v[188:191], v[156:159], v[92:95]
	v_mfma_f32_16x16x32_bf16 v[88:91], v[202:205], v[156:159], v[88:91]
	v_mfma_f32_16x16x32_bf16 v[84:87], v[188:191], v[164:167], v[84:87]
	v_mfma_f32_16x16x32_bf16 v[80:83], v[202:205], v[164:167], v[80:83]
	v_mfma_f32_16x16x32_bf16 v[76:79], v[188:191], v[172:175], v[76:79]
	v_mfma_f32_16x16x32_bf16 v[72:75], v[202:205], v[172:175], v[72:75]
	v_mfma_f32_16x16x32_bf16 v[68:71], v[188:191], v[180:183], v[68:71]
	v_mfma_f32_16x16x32_bf16 v[64:67], v[202:205], v[180:183], v[64:67]
	v_mfma_f32_16x16x32_bf16 v[92:95], v[192:195], v[160:163], v[92:95]
	v_mfma_f32_16x16x32_bf16 v[88:91], v[206:209], v[160:163], v[88:91]
	v_mfma_f32_16x16x32_bf16 v[84:87], v[192:195], v[168:171], v[84:87]
	v_mfma_f32_16x16x32_bf16 v[80:83], v[206:209], v[168:171], v[80:83]
	v_mfma_f32_16x16x32_bf16 v[76:79], v[192:195], v[176:179], v[76:79]
	v_mfma_f32_16x16x32_bf16 v[72:75], v[206:209], v[176:179], v[72:75]
	v_mfma_f32_16x16x32_bf16 v[68:71], v[192:195], v[184:187], v[68:71]
	v_mfma_f32_16x16x32_bf16 v[64:67], v[206:209], v[184:187], v[64:67]
	s_setprio 0
	s_barrier
	ds_read_b128 v[156:159], v136 offset:16384
	ds_read_b128 v[160:163], v136 offset:17408
	ds_read_b128 v[164:167], v135 offset:16384
	ds_read_b128 v[168:171], v135 offset:17408
	ds_read_b128 v[172:175], v134 offset:16384
	ds_read_b128 v[176:179], v134 offset:17408
	ds_read_b128 v[180:183], v133 offset:16384
	ds_read_b128 v[184:187], v133 offset:17408
	s_mov_b32 m0, s68
	s_add_u32 s98, s28, s0
	s_addc_u32 s99, s29, s1
	global_load_lds_dwordx4 v128, s[98:99]
	s_add_i32 m0, s68, 0x2000
	s_nop 0
	global_load_lds_dwordx4 v130, s[98:99]
	s_barrier
	s_waitcnt lgkmcnt(0)
	s_setprio 1
	s_waitcnt lgkmcnt(0)
	v_mfma_f32_16x16x32_bf16 v[60:63], v[140:143], v[156:159], v[60:63]
	v_mfma_f32_16x16x32_bf16 v[56:59], v[148:151], v[156:159], v[56:59]
	v_mfma_f32_16x16x32_bf16 v[52:55], v[140:143], v[164:167], v[52:55]
	v_mfma_f32_16x16x32_bf16 v[48:51], v[148:151], v[164:167], v[48:51]
	v_mfma_f32_16x16x32_bf16 v[44:47], v[140:143], v[172:175], v[44:47]
	v_mfma_f32_16x16x32_bf16 v[40:43], v[148:151], v[172:175], v[40:43]
	v_mfma_f32_16x16x32_bf16 v[36:39], v[140:143], v[180:183], v[36:39]
	v_mfma_f32_16x16x32_bf16 v[32:35], v[148:151], v[180:183], v[32:35]
	v_mfma_f32_16x16x32_bf16 v[60:63], v[144:147], v[160:163], v[60:63]
	v_mfma_f32_16x16x32_bf16 v[56:59], v[152:155], v[160:163], v[56:59]
	v_mfma_f32_16x16x32_bf16 v[52:55], v[144:147], v[168:171], v[52:55]
	v_mfma_f32_16x16x32_bf16 v[48:51], v[152:155], v[168:171], v[48:51]
	v_mfma_f32_16x16x32_bf16 v[44:47], v[144:147], v[176:179], v[44:47]
	v_mfma_f32_16x16x32_bf16 v[40:43], v[152:155], v[176:179], v[40:43]
	v_mfma_f32_16x16x32_bf16 v[36:39], v[144:147], v[184:187], v[36:39]
	v_mfma_f32_16x16x32_bf16 v[32:35], v[152:155], v[184:187], v[32:35]
	s_setprio 0
	s_barrier
	s_add_i32 m0, s68, 0x14000
	s_add_u32 s98, s56, s46
	s_addc_u32 s99, s57, s47
	global_load_lds_dwordx4 v128, s[98:99]
	s_add_i32 m0, s68, 0x16000
	s_nop 0
	global_load_lds_dwordx4 v130, s[98:99]
	s_waitcnt vmcnt(6)
	s_barrier
	s_setprio 1
	v_mfma_f32_16x16x32_bf16 v[28:31], v[188:191], v[156:159], v[28:31]
	v_mfma_f32_16x16x32_bf16 v[24:27], v[202:205], v[156:159], v[24:27]
	v_mfma_f32_16x16x32_bf16 v[20:23], v[188:191], v[164:167], v[20:23]
	v_mfma_f32_16x16x32_bf16 v[16:19], v[202:205], v[164:167], v[16:19]
	v_mfma_f32_16x16x32_bf16 v[12:15], v[188:191], v[172:175], v[12:15]
	v_mfma_f32_16x16x32_bf16 v[8:11], v[202:205], v[172:175], v[8:11]
	v_mfma_f32_16x16x32_bf16 v[4:7], v[188:191], v[180:183], v[4:7]
	v_mfma_f32_16x16x32_bf16 v[0:3], v[202:205], v[180:183], v[0:3]
	v_mfma_f32_16x16x32_bf16 v[28:31], v[192:195], v[160:163], v[28:31]
	v_mfma_f32_16x16x32_bf16 v[24:27], v[206:209], v[160:163], v[24:27]
	v_mfma_f32_16x16x32_bf16 v[20:23], v[192:195], v[168:171], v[20:23]
	v_mfma_f32_16x16x32_bf16 v[16:19], v[206:209], v[168:171], v[16:19]
	v_mfma_f32_16x16x32_bf16 v[12:15], v[192:195], v[176:179], v[12:15]
	v_mfma_f32_16x16x32_bf16 v[8:11], v[206:209], v[176:179], v[8:11]
	v_mfma_f32_16x16x32_bf16 v[4:7], v[192:195], v[184:187], v[4:7]
	v_mfma_f32_16x16x32_bf16 v[0:3], v[206:209], v[184:187], v[0:3]
	s_setprio 0
	s_barrier
	ds_read_b128 v[140:143], v138
	ds_read_b128 v[144:147], v138 offset:1024
	ds_read_b128 v[148:151], v138 offset:2048
	ds_read_b128 v[152:155], v138 offset:3072
	ds_read_b128 v[156:159], v136 offset:32768
	ds_read_b128 v[160:163], v136 offset:33792
	ds_read_b128 v[164:167], v135 offset:32768
	ds_read_b128 v[168:171], v135 offset:33792
	ds_read_b128 v[172:175], v134 offset:32768
	ds_read_b128 v[176:179], v134 offset:33792
	ds_read_b128 v[180:183], v133 offset:32768
	ds_read_b128 v[184:187], v133 offset:33792
	s_add_i32 m0, s68, 0x4000
	s_add_u32 s98, s28, s46
	s_addc_u32 s99, s29, s47
	global_load_lds_dwordx4 v128, s[98:99]
	s_add_i32 m0, s68, 0x6000
	s_nop 0
	global_load_lds_dwordx4 v130, s[98:99]
	s_waitcnt lgkmcnt(8)
	s_barrier
	s_waitcnt lgkmcnt(0)
	s_setprio 1
	s_waitcnt lgkmcnt(0)
	v_mfma_f32_16x16x32_bf16 v[124:127], v[140:143], v[156:159], v[124:127]
	v_mfma_f32_16x16x32_bf16 v[120:123], v[148:151], v[156:159], v[120:123]
	v_mfma_f32_16x16x32_bf16 v[116:119], v[140:143], v[164:167], v[116:119]
	v_mfma_f32_16x16x32_bf16 v[112:115], v[148:151], v[164:167], v[112:115]
	v_mfma_f32_16x16x32_bf16 v[108:111], v[140:143], v[172:175], v[108:111]
	v_mfma_f32_16x16x32_bf16 v[104:107], v[148:151], v[172:175], v[104:107]
	v_mfma_f32_16x16x32_bf16 v[100:103], v[140:143], v[180:183], v[100:103]
	v_mfma_f32_16x16x32_bf16 v[96:99], v[148:151], v[180:183], v[96:99]
	v_mfma_f32_16x16x32_bf16 v[124:127], v[144:147], v[160:163], v[124:127]
	v_mfma_f32_16x16x32_bf16 v[120:123], v[152:155], v[160:163], v[120:123]
	v_mfma_f32_16x16x32_bf16 v[116:119], v[144:147], v[168:171], v[116:119]
	v_mfma_f32_16x16x32_bf16 v[112:115], v[152:155], v[168:171], v[112:115]
	v_mfma_f32_16x16x32_bf16 v[108:111], v[144:147], v[176:179], v[108:111]
	v_mfma_f32_16x16x32_bf16 v[104:107], v[152:155], v[176:179], v[104:107]
	v_mfma_f32_16x16x32_bf16 v[100:103], v[144:147], v[184:187], v[100:103]
	v_mfma_f32_16x16x32_bf16 v[96:99], v[152:155], v[184:187], v[96:99]
	s_setprio 0
	s_barrier
	ds_read_b128 v[188:191], v137
	ds_read_b128 v[192:195], v137 offset:1024
	ds_read_b128 v[202:205], v137 offset:2048
	ds_read_b128 v[206:209], v137 offset:3072
	s_mov_b32 m0, s69
	s_add_u32 s98, s56, s30
	s_addc_u32 s99, s57, s31
	global_load_lds_dwordx4 v128, s[98:99]
	s_mov_b32 m0, s70
	s_nop 0
	global_load_lds_dwordx4 v130, s[98:99]
	s_barrier
	s_waitcnt lgkmcnt(0)
	s_setprio 1
	s_waitcnt lgkmcnt(0)
	v_mfma_f32_16x16x32_bf16 v[92:95], v[188:191], v[156:159], v[92:95]
	v_mfma_f32_16x16x32_bf16 v[88:91], v[202:205], v[156:159], v[88:91]
	v_mfma_f32_16x16x32_bf16 v[84:87], v[188:191], v[164:167], v[84:87]
	v_mfma_f32_16x16x32_bf16 v[80:83], v[202:205], v[164:167], v[80:83]
	v_mfma_f32_16x16x32_bf16 v[76:79], v[188:191], v[172:175], v[76:79]
	v_mfma_f32_16x16x32_bf16 v[72:75], v[202:205], v[172:175], v[72:75]
	v_mfma_f32_16x16x32_bf16 v[68:71], v[188:191], v[180:183], v[68:71]
	v_mfma_f32_16x16x32_bf16 v[64:67], v[202:205], v[180:183], v[64:67]
	v_mfma_f32_16x16x32_bf16 v[92:95], v[192:195], v[160:163], v[92:95]
	v_mfma_f32_16x16x32_bf16 v[88:91], v[206:209], v[160:163], v[88:91]
	v_mfma_f32_16x16x32_bf16 v[84:87], v[192:195], v[168:171], v[84:87]
	v_mfma_f32_16x16x32_bf16 v[80:83], v[206:209], v[168:171], v[80:83]
	v_mfma_f32_16x16x32_bf16 v[76:79], v[192:195], v[176:179], v[76:79]
	v_mfma_f32_16x16x32_bf16 v[72:75], v[206:209], v[176:179], v[72:75]
	v_mfma_f32_16x16x32_bf16 v[68:71], v[192:195], v[184:187], v[68:71]
	v_mfma_f32_16x16x32_bf16 v[64:67], v[206:209], v[184:187], v[64:67]
	s_setprio 0
	v_mov_b32_e32 v210, v130
	s_barrier
	ds_read_b128 v[156:159], v136 offset:49152
	ds_read_b128 v[160:163], v136 offset:50176
	ds_read_b128 v[164:167], v135 offset:49152
	ds_read_b128 v[168:171], v135 offset:50176
	ds_read_b128 v[172:175], v134 offset:49152
	ds_read_b128 v[176:179], v134 offset:50176
	ds_read_b128 v[180:183], v133 offset:49152
	ds_read_b128 v[184:187], v133 offset:50176
	v_mov_b32_e32 v211, v197
	s_mov_b32 m0, s71
	s_add_u32 s98, s28, s30
	s_addc_u32 s99, s29, s31
	global_load_lds_dwordx4 v128, s[98:99]
	s_mov_b32 m0, s33
	s_nop 0
	global_load_lds_dwordx4 v130, s[98:99]
	s_barrier
	s_waitcnt lgkmcnt(0)
	s_setprio 1
	s_waitcnt lgkmcnt(0)
	v_mfma_f32_16x16x32_bf16 v[60:63], v[140:143], v[156:159], v[60:63]
	v_mfma_f32_16x16x32_bf16 v[56:59], v[148:151], v[156:159], v[56:59]
	v_mfma_f32_16x16x32_bf16 v[52:55], v[140:143], v[164:167], v[52:55]
	v_mfma_f32_16x16x32_bf16 v[48:51], v[148:151], v[164:167], v[48:51]
	v_mfma_f32_16x16x32_bf16 v[44:47], v[140:143], v[172:175], v[44:47]
	v_mfma_f32_16x16x32_bf16 v[40:43], v[148:151], v[172:175], v[40:43]
	v_mfma_f32_16x16x32_bf16 v[36:39], v[140:143], v[180:183], v[36:39]
	v_mfma_f32_16x16x32_bf16 v[32:35], v[148:151], v[180:183], v[32:35]
	v_mfma_f32_16x16x32_bf16 v[60:63], v[144:147], v[160:163], v[60:63]
	v_mfma_f32_16x16x32_bf16 v[56:59], v[152:155], v[160:163], v[56:59]
	v_mfma_f32_16x16x32_bf16 v[52:55], v[144:147], v[168:171], v[52:55]
	v_mfma_f32_16x16x32_bf16 v[48:51], v[152:155], v[168:171], v[48:51]
	v_mfma_f32_16x16x32_bf16 v[44:47], v[144:147], v[176:179], v[44:47]
	v_mfma_f32_16x16x32_bf16 v[40:43], v[152:155], v[176:179], v[40:43]
	v_mfma_f32_16x16x32_bf16 v[36:39], v[144:147], v[184:187], v[36:39]
	v_mfma_f32_16x16x32_bf16 v[32:35], v[152:155], v[184:187], v[32:35]
	s_setprio 0
	s_barrier
	v_mov_b32_e32 v196, v128
	s_mov_b32 m0, s72
	s_add_u32 s98, s56, s48
	s_addc_u32 s99, s57, s49
	global_load_lds_dwordx4 v128, s[98:99]
	s_mov_b32 m0, s36
	s_nop 0
	global_load_lds_dwordx4 v130, s[98:99]
	s_waitcnt vmcnt(6)
	s_barrier
	s_setprio 1
	v_mfma_f32_16x16x32_bf16 v[28:31], v[188:191], v[156:159], v[28:31]
	v_mfma_f32_16x16x32_bf16 v[24:27], v[202:205], v[156:159], v[24:27]
	v_mfma_f32_16x16x32_bf16 v[20:23], v[188:191], v[164:167], v[20:23]
	v_mfma_f32_16x16x32_bf16 v[16:19], v[202:205], v[164:167], v[16:19]
	v_mfma_f32_16x16x32_bf16 v[12:15], v[188:191], v[172:175], v[12:15]
	v_mfma_f32_16x16x32_bf16 v[8:11], v[202:205], v[172:175], v[8:11]
	v_mfma_f32_16x16x32_bf16 v[4:7], v[188:191], v[180:183], v[4:7]
	v_mfma_f32_16x16x32_bf16 v[0:3], v[202:205], v[180:183], v[0:3]
	v_mfma_f32_16x16x32_bf16 v[28:31], v[192:195], v[160:163], v[28:31]
	v_mfma_f32_16x16x32_bf16 v[24:27], v[206:209], v[160:163], v[24:27]
	v_mfma_f32_16x16x32_bf16 v[20:23], v[192:195], v[168:171], v[20:23]
	v_mfma_f32_16x16x32_bf16 v[16:19], v[206:209], v[168:171], v[16:19]
	v_mfma_f32_16x16x32_bf16 v[12:15], v[192:195], v[176:179], v[12:15]
	v_mfma_f32_16x16x32_bf16 v[8:11], v[206:209], v[176:179], v[8:11]
	v_mfma_f32_16x16x32_bf16 v[4:7], v[192:195], v[184:187], v[4:7]
	v_mfma_f32_16x16x32_bf16 v[0:3], v[206:209], v[184:187], v[0:3]
	s_setprio 0
	s_add_i32 s37, s37, 2
	s_add_u32 s10, s10, 0x100
	s_addc_u32 s11, s11, 0
	s_cmp_lt_u32 s37, 28
	s_barrier
	s_cbranch_scc1 .LBB0_568
	s_lshl_b64 s[4:5], s[4:5], 12
	s_add_u32 s4, s67, s4
	s_addc_u32 s5, s53, s5
	ds_read_b128 v[140:143], v129
	ds_read_b128 v[144:147], v129 offset:1024
	ds_read_b128 v[148:151], v129 offset:2048
	ds_read_b128 v[152:155], v129 offset:3072
	ds_read_b128 v[156:159], v136
	ds_read_b128 v[160:163], v136 offset:1024
	ds_read_b128 v[164:167], v135
	ds_read_b128 v[168:171], v135 offset:1024
	ds_read_b128 v[172:175], v134
	ds_read_b128 v[176:179], v134 offset:1024
	ds_read_b128 v[180:183], v133
	ds_read_b128 v[184:187], v133 offset:1024
	v_mov_b32_e32 v129, v197
	v_lshl_add_u64 v[128:129], s[4:5], 0, v[128:129]
	s_mov_b64 s[6:7], 0xf80
	s_mov_b32 m0, s39
	v_lshl_add_u64 v[128:129], v[128:129], 0, s[6:7]
	v_mov_b32_e32 v131, v197
	global_load_lds_dwordx4 v[128:129], off
	v_lshl_add_u64 v[128:129], s[4:5], 0, v[130:131]
	v_lshl_add_u64 v[128:129], v[128:129], 0, s[6:7]
	s_mov_b32 m0, s38
	s_nop 0
	global_load_lds_dwordx4 v[128:129], off
	s_barrier
	s_waitcnt lgkmcnt(0)
	s_setprio 1
	s_waitcnt lgkmcnt(0)
	v_mfma_f32_16x16x32_bf16 v[124:127], v[140:143], v[156:159], v[124:127]
	v_mfma_f32_16x16x32_bf16 v[120:123], v[148:151], v[156:159], v[120:123]
	v_mfma_f32_16x16x32_bf16 v[116:119], v[140:143], v[164:167], v[116:119]
	v_mfma_f32_16x16x32_bf16 v[112:115], v[148:151], v[164:167], v[112:115]
	v_mfma_f32_16x16x32_bf16 v[100:103], v[140:143], v[180:183], v[100:103]
	v_mfma_f32_16x16x32_bf16 v[96:99], v[148:151], v[180:183], v[96:99]
	v_mfma_f32_16x16x32_bf16 v[124:127], v[144:147], v[160:163], v[124:127]
	v_mfma_f32_16x16x32_bf16 v[120:123], v[152:155], v[160:163], v[120:123]
	v_mfma_f32_16x16x32_bf16 v[116:119], v[144:147], v[168:171], v[116:119]
	v_mfma_f32_16x16x32_bf16 v[112:115], v[152:155], v[168:171], v[112:115]
	v_mfma_f32_16x16x32_bf16 v[108:111], v[140:143], v[172:175], v[108:111]
	v_mfma_f32_16x16x32_bf16 v[104:107], v[148:151], v[172:175], v[104:107]
	v_mfma_f32_16x16x32_bf16 v[100:103], v[144:147], v[184:187], v[100:103]
	v_mfma_f32_16x16x32_bf16 v[96:99], v[152:155], v[184:187], v[96:99]
	v_mfma_f32_16x16x32_bf16 v[128:131], v[144:147], v[176:179], v[108:111]
	v_mfma_f32_16x16x32_bf16 v[188:191], v[152:155], v[176:179], v[104:107]
	s_setprio 0
	s_barrier
	s_nop 1
	ds_read_b128 v[104:107], v139
	ds_read_b128 v[108:111], v139 offset:1024
	ds_read_b128 v[192:195], v139 offset:2048
	ds_read_b128 v[202:205], v139 offset:3072
	s_barrier
	s_waitcnt lgkmcnt(0)
	s_setprio 1
	s_waitcnt lgkmcnt(0)
	v_mfma_f32_16x16x32_bf16 v[84:87], v[104:107], v[164:167], v[84:87]
	v_mfma_f32_16x16x32_bf16 v[80:83], v[192:195], v[164:167], v[80:83]
	v_mfma_f32_16x16x32_bf16 v[68:71], v[104:107], v[180:183], v[68:71]
	v_mfma_f32_16x16x32_bf16 v[64:67], v[192:195], v[180:183], v[64:67]
	v_mfma_f32_16x16x32_bf16 v[92:95], v[104:107], v[156:159], v[92:95]
	v_mfma_f32_16x16x32_bf16 v[88:91], v[192:195], v[156:159], v[88:91]
	v_mfma_f32_16x16x32_bf16 v[84:87], v[108:111], v[168:171], v[84:87]
	v_mfma_f32_16x16x32_bf16 v[80:83], v[202:205], v[168:171], v[80:83]
	v_mfma_f32_16x16x32_bf16 v[76:79], v[104:107], v[172:175], v[76:79]
	v_mfma_f32_16x16x32_bf16 v[72:75], v[192:195], v[172:175], v[72:75]
	v_mfma_f32_16x16x32_bf16 v[68:71], v[108:111], v[184:187], v[68:71]
	v_mfma_f32_16x16x32_bf16 v[64:67], v[202:205], v[184:187], v[64:67]
	v_mfma_f32_16x16x32_bf16 v[206:209], v[108:111], v[160:163], v[92:95]
	v_mfma_f32_16x16x32_bf16 v[156:159], v[202:205], v[160:163], v[88:91]
	v_mfma_f32_16x16x32_bf16 v[160:163], v[108:111], v[176:179], v[76:79]
	v_mfma_f32_16x16x32_bf16 v[164:167], v[202:205], v[176:179], v[72:75]
	s_setprio 0
	s_barrier
	s_nop 0
	ds_read_b128 v[72:75], v136 offset:16384
	ds_read_b128 v[76:79], v136 offset:17408
	ds_read_b128 v[88:91], v135 offset:16384
	ds_read_b128 v[92:95], v135 offset:17408
	ds_read_b128 v[168:171], v134 offset:16384
	ds_read_b128 v[172:175], v134 offset:17408
	ds_read_b128 v[176:179], v133 offset:16384
	ds_read_b128 v[180:183], v133 offset:17408
	s_waitcnt vmcnt(4)
	s_barrier
	s_waitcnt lgkmcnt(0)
	s_setprio 1
	s_waitcnt lgkmcnt(0)
	v_mfma_f32_16x16x32_bf16 v[60:63], v[140:143], v[72:75], v[60:63]
	v_mfma_f32_16x16x32_bf16 v[56:59], v[148:151], v[72:75], v[56:59]
	v_mfma_f32_16x16x32_bf16 v[52:55], v[140:143], v[88:91], v[52:55]
	v_mfma_f32_16x16x32_bf16 v[48:51], v[148:151], v[88:91], v[48:51]
	v_mfma_f32_16x16x32_bf16 v[36:39], v[140:143], v[176:179], v[36:39]
	v_mfma_f32_16x16x32_bf16 v[32:35], v[148:151], v[176:179], v[32:35]
	v_mfma_f32_16x16x32_bf16 v[60:63], v[144:147], v[76:79], v[60:63]
	v_mfma_f32_16x16x32_bf16 v[56:59], v[152:155], v[76:79], v[56:59]
	v_mfma_f32_16x16x32_bf16 v[52:55], v[144:147], v[92:95], v[52:55]
	v_mfma_f32_16x16x32_bf16 v[48:51], v[152:155], v[92:95], v[48:51]
	v_mfma_f32_16x16x32_bf16 v[44:47], v[140:143], v[168:171], v[44:47]
	v_mfma_f32_16x16x32_bf16 v[40:43], v[148:151], v[168:171], v[40:43]
	v_mfma_f32_16x16x32_bf16 v[36:39], v[144:147], v[180:183], v[36:39]
	v_mfma_f32_16x16x32_bf16 v[32:35], v[152:155], v[180:183], v[32:35]
	v_mfma_f32_16x16x32_bf16 v[184:187], v[144:147], v[172:175], v[44:47]
	v_mfma_f32_16x16x32_bf16 v[210:213], v[152:155], v[172:175], v[40:43]
	s_setprio 0
	s_setprio 1
	v_mfma_f32_16x16x32_bf16 v[20:23], v[104:107], v[88:91], v[20:23]
	v_mfma_f32_16x16x32_bf16 v[16:19], v[192:195], v[88:91], v[16:19]
	v_mfma_f32_16x16x32_bf16 v[4:7], v[104:107], v[176:179], v[4:7]
	v_mfma_f32_16x16x32_bf16 v[0:3], v[192:195], v[176:179], v[0:3]
	v_mfma_f32_16x16x32_bf16 v[28:31], v[104:107], v[72:75], v[28:31]
	v_mfma_f32_16x16x32_bf16 v[24:27], v[192:195], v[72:75], v[24:27]
	v_mfma_f32_16x16x32_bf16 v[20:23], v[108:111], v[92:95], v[20:23]
	v_mfma_f32_16x16x32_bf16 v[16:19], v[202:205], v[92:95], v[16:19]
	v_mfma_f32_16x16x32_bf16 v[12:15], v[104:107], v[168:171], v[12:15]
	v_mfma_f32_16x16x32_bf16 v[8:11], v[192:195], v[168:171], v[8:11]
	v_mfma_f32_16x16x32_bf16 v[4:7], v[108:111], v[180:183], v[4:7]
	v_mfma_f32_16x16x32_bf16 v[0:3], v[202:205], v[180:183], v[0:3]
	v_mfma_f32_16x16x32_bf16 v[140:143], v[108:111], v[76:79], v[28:31]
	v_mfma_f32_16x16x32_bf16 v[144:147], v[202:205], v[76:79], v[24:27]
	v_mfma_f32_16x16x32_bf16 v[148:151], v[108:111], v[172:175], v[12:15]
	v_mfma_f32_16x16x32_bf16 v[152:155], v[202:205], v[172:175], v[8:11]
	s_setprio 0
	s_barrier
	s_nop 0
	ds_read_b128 v[8:11], v138
	ds_read_b128 v[12:15], v138 offset:1024
	ds_read_b128 v[168:171], v138 offset:2048
	ds_read_b128 v[172:175], v138 offset:3072
	ds_read_b128 v[24:27], v136 offset:32768
	ds_read_b128 v[28:31], v136 offset:33792
	ds_read_b128 v[40:43], v135 offset:32768
	ds_read_b128 v[44:47], v135 offset:33792
	ds_read_b128 v[176:179], v134 offset:32768
	ds_read_b128 v[180:183], v134 offset:33792
	ds_read_b128 v[192:195], v133 offset:32768
	ds_read_b128 v[202:205], v133 offset:33792
	s_waitcnt vmcnt(2)
	s_barrier
	s_waitcnt lgkmcnt(0)
	s_setprio 1
	s_waitcnt lgkmcnt(0)
	v_mfma_f32_16x16x32_bf16 v[72:75], v[8:11], v[24:27], v[124:127]
	v_mfma_f32_16x16x32_bf16 v[124:127], v[12:15], v[28:31], v[72:75]
	v_mfma_f32_16x16x32_bf16 v[72:75], v[168:171], v[24:27], v[120:123]
	v_mfma_f32_16x16x32_bf16 v[120:123], v[172:175], v[28:31], v[72:75]
	v_mfma_f32_16x16x32_bf16 v[72:75], v[8:11], v[40:43], v[116:119]
	v_mfma_f32_16x16x32_bf16 v[108:111], v[12:15], v[44:47], v[72:75]
	v_mfma_f32_16x16x32_bf16 v[72:75], v[168:171], v[40:43], v[112:115]
	v_mfma_f32_16x16x32_bf16 v[104:107], v[172:175], v[44:47], v[72:75]
	v_mfma_f32_16x16x32_bf16 v[72:75], v[8:11], v[176:179], v[128:131]
	v_mfma_f32_16x16x32_bf16 v[92:95], v[12:15], v[180:183], v[72:75]
	v_mfma_f32_16x16x32_bf16 v[72:75], v[168:171], v[176:179], v[188:191]
	v_mfma_f32_16x16x32_bf16 v[88:91], v[172:175], v[180:183], v[72:75]
	v_mfma_f32_16x16x32_bf16 v[72:75], v[8:11], v[192:195], v[100:103]
	v_mfma_f32_16x16x32_bf16 v[76:79], v[12:15], v[202:205], v[72:75]
	v_mfma_f32_16x16x32_bf16 v[72:75], v[168:171], v[192:195], v[96:99]
	v_mfma_f32_16x16x32_bf16 v[72:75], v[172:175], v[202:205], v[72:75]
	s_setprio 0
	s_barrier
	ds_read_b128 v[128:131], v137
	ds_read_b128 v[188:191], v137 offset:1024
	ds_read_b128 v[214:217], v137 offset:2048
	ds_read_b128 v[218:221], v137 offset:3072
	s_waitcnt vmcnt(0)
	s_barrier
	s_waitcnt lgkmcnt(0)
	s_setprio 1
	s_waitcnt lgkmcnt(0)
	v_mfma_f32_16x16x32_bf16 v[96:99], v[128:131], v[24:27], v[206:209]
	v_mfma_f32_16x16x32_bf16 v[24:27], v[214:217], v[24:27], v[156:159]
	v_mfma_f32_16x16x32_bf16 v[112:115], v[218:221], v[28:31], v[24:27]
	v_mfma_f32_16x16x32_bf16 v[24:27], v[128:131], v[40:43], v[84:87]
	v_mfma_f32_16x16x32_bf16 v[100:103], v[188:191], v[44:47], v[24:27]
	v_mfma_f32_16x16x32_bf16 v[24:27], v[214:217], v[40:43], v[80:83]
	v_mfma_f32_16x16x32_bf16 v[116:119], v[188:191], v[28:31], v[96:99]
	v_mfma_f32_16x16x32_bf16 v[96:99], v[218:221], v[44:47], v[24:27]
	v_mfma_f32_16x16x32_bf16 v[24:27], v[128:131], v[176:179], v[160:163]
	v_mfma_f32_16x16x32_bf16 v[84:87], v[188:191], v[180:183], v[24:27]
	v_mfma_f32_16x16x32_bf16 v[24:27], v[214:217], v[176:179], v[164:167]
	v_mfma_f32_16x16x32_bf16 v[80:83], v[218:221], v[180:183], v[24:27]
	v_mfma_f32_16x16x32_bf16 v[24:27], v[128:131], v[192:195], v[68:71]
	v_mfma_f32_16x16x32_bf16 v[68:71], v[188:191], v[202:205], v[24:27]
	v_mfma_f32_16x16x32_bf16 v[24:27], v[214:217], v[192:195], v[64:67]
	v_mfma_f32_16x16x32_bf16 v[64:67], v[218:221], v[202:205], v[24:27]
	s_setprio 0
	s_barrier
	ds_read_b128 v[156:159], v136 offset:49152
	ds_read_b128 v[136:139], v136 offset:50176
	ds_read_b128 v[160:163], v135 offset:49152
	ds_read_b128 v[164:167], v135 offset:50176
	ds_read_b128 v[176:179], v134 offset:49152
	ds_read_b128 v[180:183], v134 offset:50176
	ds_read_b128 v[192:195], v133 offset:49152
	ds_read_b128 v[202:205], v133 offset:50176
	s_barrier
	s_waitcnt lgkmcnt(0)
	s_setprio 1
	s_waitcnt lgkmcnt(0)
	v_mfma_f32_16x16x32_bf16 v[24:27], v[8:11], v[156:159], v[60:63]
	v_mfma_f32_16x16x32_bf16 v[60:63], v[12:15], v[136:139], v[24:27]
	v_mfma_f32_16x16x32_bf16 v[24:27], v[168:171], v[156:159], v[56:59]
	v_mfma_f32_16x16x32_bf16 v[56:59], v[172:175], v[136:139], v[24:27]
	v_mfma_f32_16x16x32_bf16 v[24:27], v[8:11], v[160:163], v[52:55]
	v_mfma_f32_16x16x32_bf16 v[44:47], v[12:15], v[164:167], v[24:27]
	v_mfma_f32_16x16x32_bf16 v[24:27], v[168:171], v[160:163], v[48:51]
	v_mfma_f32_16x16x32_bf16 v[40:43], v[172:175], v[164:167], v[24:27]
	v_mfma_f32_16x16x32_bf16 v[24:27], v[8:11], v[176:179], v[184:187]
	v_mfma_f32_16x16x32_bf16 v[8:11], v[8:11], v[192:195], v[36:39]
	v_mfma_f32_16x16x32_bf16 v[28:31], v[12:15], v[180:183], v[24:27]
	v_mfma_f32_16x16x32_bf16 v[24:27], v[168:171], v[176:179], v[210:213]
	v_mfma_f32_16x16x32_bf16 v[12:15], v[12:15], v[202:205], v[8:11]
	v_mfma_f32_16x16x32_bf16 v[8:11], v[168:171], v[192:195], v[32:35]
	v_mfma_f32_16x16x32_bf16 v[24:27], v[172:175], v[180:183], v[24:27]
	v_mfma_f32_16x16x32_bf16 v[8:11], v[172:175], v[202:205], v[8:11]
	s_setprio 0
	s_setprio 1
	v_mfma_f32_16x16x32_bf16 v[32:35], v[128:131], v[156:159], v[140:143]
	v_mfma_f32_16x16x32_bf16 v[52:55], v[188:191], v[136:139], v[32:35]
	v_mfma_f32_16x16x32_bf16 v[32:35], v[214:217], v[156:159], v[144:147]
	v_mfma_f32_16x16x32_bf16 v[16:19], v[214:217], v[160:163], v[16:19]
	v_mfma_f32_16x16x32_bf16 v[48:51], v[218:221], v[136:139], v[32:35]
	v_mfma_f32_16x16x32_bf16 v[20:23], v[128:131], v[160:163], v[20:23]
	v_mfma_f32_16x16x32_bf16 v[32:35], v[218:221], v[164:167], v[16:19]
	v_mfma_f32_16x16x32_bf16 v[16:19], v[128:131], v[176:179], v[148:151]
	v_mfma_f32_16x16x32_bf16 v[36:39], v[188:191], v[164:167], v[20:23]
	v_mfma_f32_16x16x32_bf16 v[20:23], v[188:191], v[180:183], v[16:19]
	v_mfma_f32_16x16x32_bf16 v[16:19], v[214:217], v[176:179], v[152:155]
	v_mfma_f32_16x16x32_bf16 v[4:7], v[128:131], v[192:195], v[4:7]
	v_mfma_f32_16x16x32_bf16 v[0:3], v[214:217], v[192:195], v[0:3]
	v_mfma_f32_16x16x32_bf16 v[16:19], v[218:221], v[180:183], v[16:19]
	v_mfma_f32_16x16x32_bf16 v[4:7], v[188:191], v[202:205], v[4:7]
	v_mfma_f32_16x16x32_bf16 v[0:3], v[218:221], v[202:205], v[0:3]
	s_setprio 0
	s_movk_i32 s4, 0x100
	v_cmp_gt_u32_e32 vcc, s4, v132
	s_barrier
	s_and_saveexec_b64 s[4:5], vcc
	s_cbranch_execz .LBB0_571
	s_barrier
